# attention tile loops rescheduled: p0-chain then p1-chain QK, exp/cvt/rowsum hidden in MFMA gaps, LDS reads 3 MFMAs ahead with counted lgkmcnt; bit-identical output
# speedup vs baseline: 1.0275x; 1.0275x over previous
; #define LAS __attribute__((address_space(3)))
; __device__ __forceinline__ int v_rd_base(int lane) { return ((lane & 3) << 3) | (((lane >> 2) & 3) << 6) | (((lane >> 4) & 1) << 5) | (((lane >> 5) & 1) << 8); }
; #define VMW0() asm volatile("s_waitcnt vmcnt(0)" ::: "memory")
; template <int DQK, bool DOUBLE> ...
;     constexpr int RB = DQK * 2, NCH = DQK / 8, NLD = NCH / 8;
;     const int wid = __builtin_amdgcn_readfirstlane(tid >> 6), lane = tid & 63, r32 = lane & 31, hi = lane >> 5;
;     LAS char* V_lds = lds; LAS char* K_lds = lds + K_OFF;
;     bf16x8 qr[DQK / 16];
;     { const bf16_t* Qw = Q + (size_t)(wid * 32 + r32) * ldq + hi * 8;
; #pragma unroll
;       for (int d0 = 0; d0 < DQK / 16; ++d0) qr[d0] = *(const bf16x8*)(Qw + d0 * 16); }
; #pragma unroll
;     for (int d = 0; d < 4; ++d) o[d] = f32x16{};
;     l_reg = 0.f;
;     int vrow[2], vcol[2], krow[NLD], kcol[NLD];
; #pragma unroll
;     for (int i = 0; i < 2; ++i) { const int q = tid + 512 * i, sub = q >> 5, within = q & 31, kk = (sub >> 2) * 8 + (within >> 2);
;         vrow[i] = kk; vcol[i] = (sub & 3) * 32 + (within & 3) * 8; }
; #pragma unroll
;     for (int i = 0; i < NLD; ++i) { const int q = tid + 512 * i, row = q / NCH, chp = q % NCH; const int x = (RB == 256) ? (row & 15) : ((row >> 1) & 7);
;         krow[i] = row; kcol[i] = (chp ^ x) * 8; }
;     const unsigned vb0 = (unsigned)(uintptr_t)V_lds + v_rd_base(lane);
;     int ka[8];
; #pragma unroll
;     for (int q = 0; q < 8; ++q) ka[q] = kswz<RB>(r32, q * 32 + hi * 16);
;     ...
;     bf16x8 pa0, pa1, pa2, pa3;
;     __syncthreads();
;     DMA(0, 0); DMA(1, 1); VMW0(); __syncthreads();
; __device__ __forceinline__ void attn_item(const AttnBufs& T, int type, int b, int h, int qrow0, int NT, LAS char* lds, int tid_) {
;     ...
;         att::attn_pass<192, false>(T.QB + (size_t)qrow0 * 1536 + h * 192, 1536, T.KB + h * 192, 1536, T.VB + h * 128, 1024, rowc, rowl, NT,
;                             T.lamv[2], o, l_reg, lds, tid);
.LBB0_139:
	v_mov_b32_e32 v164, v186
	s_lshl_b32 s45, s70, 8
	v_readfirstlane_b32 s2, v164
	s_ashr_i32 s73, s2, 6
	s_and_b32 s2, s2, 0x3fffffc0
	s_lshl_b32 s2, s2, 2
	s_add_i32 s90, s2, 0
	s_lshl_b32 s2, s73, 5
	s_add_i32 s46, s45, 0x4000
	s_lshl_b32 s44, s70, 12
	s_add_i32 s90, s90, 0x1e000
	s_ashr_i32 s31, s30, 31
	s_ashr_i32 s3, s2, 31
	s_add_u32 s36, s2, s30
	s_addc_u32 s37, s3, s31
	v_and_b32_e32 v182, 63, v164
	v_and_b32_e32 v181, 31, v164
	v_bfe_u32 v176, v164, 5, 1
	s_mov_b64 s[56:57], -1
	s_mov_b64 s[48:49], 0
	s_cmp_lt_i32 s69, 1
	s_mulk_i32 s73, 0x4200
	s_mov_b64 s[50:51], 0
	s_cbranch_scc1 .LBB0_151
	s_cmp_eq_u32 s69, 1
	s_mov_b64 s[50:51], -1
	s_cbranch_scc0 .LBB0_150
	s_mul_i32 s3, s30, 0xc00
	v_readlane_b32 s4, v251, 32
	s_mul_hi_i32 s2, s30, 0xc00
	v_readlane_b32 s5, v251, 33
	s_add_u32 s4, s4, s3
	s_addc_u32 s5, s5, s2
	s_mul_i32 s2, s72, 0xc0
	s_ashr_i32 s3, s2, 31
	s_lshl_b64 s[2:3], s[2:3], 1
	s_add_u32 s4, s4, s2
	s_addc_u32 s5, s5, s3
	v_readlane_b32 s20, v251, 34
	v_readlane_b32 s21, v251, 35
	s_add_u32 s56, s20, s2
	s_addc_u32 s57, s21, s3
	s_lshl_b32 s50, s72, 7
	s_ashr_i32 s51, s50, 31
	s_lshl_b64 s[2:3], s[50:51], 1
	v_readlane_b32 s20, v251, 38
	v_readlane_b32 s21, v251, 39
	s_add_u32 s58, s20, s2
	v_readfirstlane_b32 s2, v164
	s_addc_u32 s59, s21, s3
	s_ashr_i32 s20, s2, 6
	v_lshl_or_b32 v1, s20, 5, v181
	v_mov_b64_e32 v[2:3], s[4:5]
	s_movk_i32 s41, 0xc00
	v_mad_i64_i32 v[2:3], s[2:3], v1, s41, v[2:3]
	v_lshlrev_b32_e32 v166, 4, v176
	v_mov_b32_e32 v167, v177
	v_lshl_add_u64 v[2:3], v[2:3], 0, v[166:167]
	global_load_dword v0, v177, s[14:15] offset:8
	global_load_dwordx4 v[112:115], v[2:3], off
	global_load_dwordx4 v[116:119], v[2:3], off offset:32
	global_load_dwordx4 v[120:123], v[2:3], off offset:64
	global_load_dwordx4 v[124:127], v[2:3], off offset:96
	s_waitcnt lgkmcnt(0)
	global_load_dwordx4 v[128:131], v[2:3], off offset:128
	global_load_dwordx4 v[132:135], v[2:3], off offset:160
	global_load_dwordx4 v[136:139], v[2:3], off offset:192
	global_load_dwordx4 v[140:143], v[2:3], off offset:224
	global_load_dwordx4 v[144:147], v[2:3], off offset:256
	global_load_dwordx4 v[148:151], v[2:3], off offset:288
	global_load_dwordx4 v[152:155], v[2:3], off offset:320
	global_load_dwordx4 v[156:159], v[2:3], off offset:352
	v_and_b32_e32 v2, 0x60, v164
	v_lshlrev_b32_e32 v3, 3, v164
	v_lshrrev_b32_e32 v1, 2, v164
	v_and_or_b32 v3, v3, 24, v2
	v_ashrrev_i32_e32 v2, 4, v164
	v_add_u32_e32 v4, 0x200, v164
	v_bfi_b32 v168, -8, v2, v1
	v_ashrrev_i32_e32 v2, 4, v4
	s_mov_b32 s2, 0x2aaaaaab
	v_bfi_b32 v170, -8, v2, v1
	v_mul_hi_i32 v1, v164, s2
	v_lshrrev_b32_e32 v2, 31, v1
	v_ashrrev_i32_e32 v1, 2, v1
	v_add_u32_e32 v172, v1, v2
	v_mul_lo_u32 v1, v172, 24
	v_sub_u32_e32 v1, v164, v1
	v_lshrrev_b32_e32 v2, 1, v172
	v_bitop3_b32 v1, v2, v1, 7 bitop3:0x6c
	v_lshlrev_b32_e32 v2, 3, v1
	v_mul_hi_i32 v1, v4, s2
	v_lshrrev_b32_e32 v5, 31, v1
	v_ashrrev_i32_e32 v1, 2, v1
	v_add_u32_e32 v174, v1, v5
	v_mul_lo_u32 v1, v174, 24
	v_sub_u32_e32 v1, v4, v1
	v_lshrrev_b32_e32 v4, 1, v174
	v_bitop3_b32 v1, v4, v1, 7 bitop3:0x6c
	s_ashr_i32 s47, s46, 31
	v_ashrrev_i32_e32 v169, 31, v168
	v_lshlrev_b32_e32 v4, 3, v1
	v_add_u32_e32 v1, 0x400, v164
	v_lshl_add_u64 v[8:9], v[168:169], 0, s[46:47]
	v_mul_hi_i32 v5, v1, s2
	s_lshl_b32 s2, s20, 10
	v_lshlrev_b64 v[8:9], 11, v[8:9]
	s_add_i32 s3, s2, 0
	v_lshl_add_u64 v[8:9], s[58:59], 0, v[8:9]
	v_lshlrev_b32_e32 v80, 1, v3
	v_mov_b32_e32 v81, v177
	v_lshl_add_u64 v[8:9], v[8:9], 0, v[80:81]
	s_mov_b32 m0, s3
	v_ashrrev_i32_e32 v171, 31, v170
	s_barrier
	global_load_lds_dwordx4 v[8:9], off
	v_lshl_add_u64 v[8:9], v[170:171], 0, s[46:47]
	v_lshlrev_b64 v[8:9], 11, v[8:9]
	v_lshl_add_u64 v[8:9], s[58:59], 0, v[8:9]
	s_add_i32 s21, s3, 0x2000
	v_lshl_add_u64 v[8:9], v[8:9], 0, v[80:81]
	s_mov_b32 m0, s21
	v_ashrrev_i32_e32 v173, 31, v172
	global_load_lds_dwordx4 v[8:9], off
	v_lshl_add_u64 v[8:9], v[172:173], 0, s[46:47]
	v_mov_b64_e32 v[84:85], s[56:57]
	v_lshrrev_b32_e32 v6, 31, v5
	v_ashrrev_i32_e32 v5, 2, v5
	v_mad_u64_u32 v[10:11], s[4:5], v8, s41, v[84:85]
	v_ashrrev_i32_e32 v3, 31, v2
	v_add_u32_e32 v192, v5, v6
	s_add_i32 s20, s3, 0xc000
	v_mad_i32_i24 v11, v9, s41, v11
	v_lshlrev_b64 v[82:83], 1, v[2:3]
	v_mul_lo_u32 v5, v192, 24
	v_lshl_add_u64 v[2:3], v[10:11], 0, v[82:83]
	s_mov_b32 m0, s20
	v_ashrrev_i32_e32 v175, 31, v174
	v_sub_u32_e32 v1, v1, v5
	v_lshrrev_b32_e32 v5, 1, v192
	global_load_lds_dwordx4 v[2:3], off
	v_lshl_add_u64 v[2:3], v[174:175], 0, s[46:47]
	v_bitop3_b32 v1, v5, v1, 7 bitop3:0x6c
	v_mad_u64_u32 v[8:9], s[4:5], v2, s41, v[84:85]
	v_ashrrev_i32_e32 v5, 31, v4
	v_mad_i32_i24 v9, v3, s41, v9
	v_lshlrev_b64 v[86:87], 1, v[4:5]
	s_add_i32 s33, s3, 0xe000
	v_lshl_add_u64 v[2:3], v[8:9], 0, v[86:87]
	s_mov_b32 m0, s33
	v_ashrrev_i32_e32 v193, 31, v192
	v_lshlrev_b32_e32 v6, 3, v1
	global_load_lds_dwordx4 v[2:3], off
	v_lshl_add_u64 v[2:3], v[192:193], 0, s[46:47]
	v_mad_u64_u32 v[4:5], s[4:5], v2, s41, v[84:85]
	v_ashrrev_i32_e32 v7, 31, v6
	v_mad_i32_i24 v5, v3, s41, v5
	v_lshlrev_b64 v[88:89], 1, v[6:7]
	s_add_i32 s35, s3, 0x10000
	s_add_i32 s4, s45, 0x4040
	v_lshl_add_u64 v[2:3], v[4:5], 0, v[88:89]
	s_mov_b32 m0, s35
	s_ashr_i32 s5, s4, 31
	global_load_lds_dwordx4 v[2:3], off
	v_lshl_add_u64 v[2:3], v[168:169], 0, s[4:5]
	v_lshlrev_b64 v[2:3], 11, v[2:3]
	v_lshl_add_u64 v[2:3], s[58:59], 0, v[2:3]
	s_add_i32 m0, s3, 0x4000
	v_lshl_add_u64 v[2:3], v[2:3], 0, v[80:81]
	global_load_lds_dwordx4 v[2:3], off
	v_lshl_add_u64 v[2:3], v[170:171], 0, s[4:5]
	v_lshlrev_b64 v[2:3], 11, v[2:3]
	v_lshl_add_u64 v[2:3], s[58:59], 0, v[2:3]
	v_lshl_add_u64 v[2:3], v[2:3], 0, v[80:81]
	s_add_i32 m0, s3, 0x6000
	v_mul_u32_u24_e32 v1, 0x180, v181
	global_load_lds_dwordx4 v[2:3], off
	v_lshl_add_u64 v[2:3], v[172:173], 0, s[4:5]
	v_mad_u64_u32 v[4:5], s[42:43], v2, s41, v[84:85]
	v_mad_i32_i24 v5, v3, s41, v5
	s_add_i32 m0, s3, 0x12000
	v_lshl_add_u64 v[2:3], v[4:5], 0, v[82:83]
	global_load_lds_dwordx4 v[2:3], off
	v_lshl_add_u64 v[2:3], v[174:175], 0, s[4:5]
	v_mad_u64_u32 v[4:5], s[42:43], v2, s41, v[84:85]
	v_mad_i32_i24 v5, v3, s41, v5
	v_lshl_add_u64 v[2:3], v[4:5], 0, v[86:87]
	s_add_i32 m0, s3, 0x14000
	s_waitcnt vmcnt(0)
	v_mov_b32_e32 v6, v0
	global_load_lds_dwordx4 v[2:3], off
	v_lshl_add_u64 v[2:3], v[192:193], 0, s[4:5]
	v_mad_u64_u32 v[4:5], s[4:5], v2, s41, v[84:85]
	v_mad_i32_i24 v5, v3, s41, v5
	s_add_i32 s4, s45, 0x4080
	v_lshl_add_u64 v[2:3], v[4:5], 0, v[88:89]
	s_add_i32 m0, s3, 0x16000
	s_ashr_i32 s5, s4, 31
	global_load_lds_dwordx4 v[2:3], off
	v_lshl_add_u64 v[2:3], v[168:169], 0, s[4:5]
	v_lshlrev_b64 v[2:3], 11, v[2:3]
	v_lshl_add_u64 v[2:3], s[58:59], 0, v[2:3]
	s_add_i32 m0, s3, 0x8000
	v_lshl_add_u64 v[2:3], v[2:3], 0, v[80:81]
	s_waitcnt vmcnt(0)
	s_waitcnt vmcnt(0) lgkmcnt(0)
	s_barrier
; #define LAS __attribute__((address_space(3)))
; __device__ __forceinline__ int v_rd_base(int lane) { return ((lane & 3) << 3) | (((lane >> 2) & 3) << 6) | (((lane >> 4) & 1) << 5) | (((lane >> 5) & 1) << 8); }
; template <int DQK>
; __device__ __forceinline__ void qkt(f32x16& p0, f32x16& p1, const LAS char* Ks, const bf16x8 (&qr)[DQK / 16], const int (&ka)[8], float nMB) {
;     constexpr int RB = DQK * 2, NA = (RB == 256) ? 8 : 4;
; #pragma unroll
;     for (int r = 0; r < 16; ++r) { p0[r] = nMB; p1[r] = nMB; }
; #pragma unroll
;     for (int d0 = 0; d0 < DQK / 16; ++d0) {
;         const LAS char* a = Ks + ka[d0 % NA] + (d0 / NA) * (NA * 32);
;         const bf16x8 b0 = *(const LAS bf16x8*)(a);
;         const bf16x8 b1 = *(const LAS bf16x8*)(a + 32 * RB);
;         p0 = __builtin_amdgcn_mfma_f32_32x32x16_bf16(b0, qr[d0], p0, 0, 0, 0);
;         p1 = __builtin_amdgcn_mfma_f32_32x32x16_bf16(b1, qr[d0], p1, 0, 0, 0); }
; }
; template <int DQK, bool DOUBLE> ...
;     ...
;     for (int i = 0; i < 2; ++i) { const int q = tid + 512 * i, sub = q >> 5, within = q & 31, kk = (sub >> 2) * 8 + (within >> 2);
;         vrow[i] = kk; vcol[i] = (sub & 3) * 32 + (within & 3) * 8; }
; #pragma unroll
;     for (int i = 0; i < NLD; ++i) { const int q = tid + 512 * i, row = q / NCH, chp = q % NCH; const int x = (RB == 256) ? (row & 15) : ((row >> 1) & 7);
;         krow[i] = row; kcol[i] = (chp ^ x) * 8; }
;     const unsigned vb0 = (unsigned)(uintptr_t)V_lds + v_rd_base(lane);
;     int ka[8];
; #pragma unroll
;     for (int q = 0; q < 8; ++q) ka[q] = kswz<RB>(r32, q * 32 + hi * 16);
	global_load_lds_dwordx4 v[2:3], off
	v_lshl_add_u64 v[2:3], v[170:171], 0, s[4:5]
	v_lshlrev_b64 v[2:3], 11, v[2:3]
	v_lshl_add_u64 v[2:3], s[58:59], 0, v[2:3]
	v_lshl_add_u64 v[2:3], v[2:3], 0, v[80:81]
	s_add_i32 m0, s3, 0xa000
	v_mov_b32_e32 v7, v0
	global_load_lds_dwordx4 v[2:3], off
	v_lshl_add_u64 v[2:3], v[172:173], 0, s[4:5]
	v_mad_u64_u32 v[4:5], s[42:43], v2, s41, v[84:85]
	v_mad_i32_i24 v5, v3, s41, v5
	s_add_i32 m0, s3, 0x18000
	v_lshl_add_u64 v[2:3], v[4:5], 0, v[82:83]
	global_load_lds_dwordx4 v[2:3], off
	v_lshl_add_u64 v[2:3], v[174:175], 0, s[4:5]
	v_mad_u64_u32 v[4:5], s[42:43], v2, s41, v[84:85]
	v_mad_i32_i24 v5, v3, s41, v5
	v_lshl_add_u64 v[2:3], v[4:5], 0, v[86:87]
	s_add_i32 m0, s3, 0x1a000
	s_movk_i32 s42, 0x118
	global_load_lds_dwordx4 v[2:3], off
	v_lshl_add_u64 v[2:3], v[192:193], 0, s[4:5]
	v_mad_u64_u32 v[4:5], s[4:5], v2, s41, v[84:85]
	v_mad_i32_i24 v5, v3, s41, v5
	v_lshl_add_u64 v[2:3], v[4:5], 0, v[88:89]
	s_add_i32 m0, s3, 0x1c000
	s_mov_b32 s5, 1
	global_load_lds_dwordx4 v[2:3], off
	v_lshlrev_b32_e32 v2, 3, v181
	v_and_b32_e32 v2, 0x70, v2
	v_or_b32_e32 v3, 32, v166
	v_bitop3_b32 v165, v3, v1, v2 bitop3:0xde
	v_or_b32_e32 v3, 64, v166
	v_bitop3_b32 v167, v3, v1, v2 bitop3:0xde
	v_or_b32_e32 v3, 0x60, v166
	v_bitop3_b32 v161, v166, v1, v2 bitop3:0xde
	v_bitop3_b32 v187, v3, v1, v2 bitop3:0xde
	v_lshlrev_b32_e32 v1, 1, v182
	v_and_b32_e32 v1, 32, v1
	v_lshlrev_b32_e32 v2, 3, v182
	v_lshlrev_b32_e32 v3, 4, v182
	v_and_b32_e32 v16, 0xc0, v3
	v_and_or_b32 v17, v2, s42, v1
	s_mov_b32 s4, 2
	v_mov_b32_e32 v1, v0
	v_mov_b32_e32 v2, v0
	v_mov_b32_e32 v3, v0
	v_mov_b32_e32 v4, v0
	v_mov_b32_e32 v5, v0
	v_mov_b32_e32 v8, v0
	v_mov_b32_e32 v9, v0
	v_mov_b32_e32 v10, v0
	v_mov_b32_e32 v11, v0
	v_mov_b32_e32 v12, v0
	v_mov_b32_e32 v13, v0
	v_mov_b32_e32 v14, v0
	v_mov_b32_e32 v15, v0
	v_add3_u32 v191, v16, 0, v17
	s_add_i32 s60, s45, 0x40c0
	v_add_u32_e32 v56, 0, v161
	ds_read_b128 v[16:19], v56 offset:49152
	ds_read_b128 v[48:51], v56 offset:61440
	v_add_u32_e32 v57, 0, v165
	v_add_u32_e32 v58, 0, v167
	v_add_u32_e32 v59, 0, v187
	s_waitcnt lgkmcnt(0)
	v_mfma_f32_32x32x16_bf16 v[32:47], v[16:19], v[112:115], v[0:15]
	v_mfma_f32_32x32x16_bf16 v[16:31], v[48:51], v[112:115], v[0:15]
	ds_read_b128 v[48:51], v57 offset:49152
	ds_read_b128 v[52:55], v57 offset:61440
	s_waitcnt lgkmcnt(0)
	v_mfma_f32_32x32x16_bf16 v[32:47], v[48:51], v[116:119], v[32:47]
	v_mfma_f32_32x32x16_bf16 v[16:31], v[52:55], v[116:119], v[16:31]
	ds_read_b128 v[48:51], v58 offset:49152
	ds_read_b128 v[52:55], v58 offset:61440
	s_waitcnt lgkmcnt(0)
	v_mfma_f32_32x32x16_bf16 v[32:47], v[48:51], v[120:123], v[32:47]
	v_mfma_f32_32x32x16_bf16 v[16:31], v[52:55], v[120:123], v[16:31]
	ds_read_b128 v[48:51], v59 offset:49152
	ds_read_b128 v[52:55], v59 offset:61440
	s_waitcnt lgkmcnt(0)
	v_mfma_f32_32x32x16_bf16 v[32:47], v[48:51], v[124:127], v[32:47]
	v_mfma_f32_32x32x16_bf16 v[16:31], v[52:55], v[124:127], v[16:31]
	ds_read_b128 v[48:51], v56 offset:49280
	ds_read_b128 v[52:55], v56 offset:61568
	s_waitcnt lgkmcnt(0)
	v_mfma_f32_32x32x16_bf16 v[32:47], v[48:51], v[128:131], v[32:47]
	v_mfma_f32_32x32x16_bf16 v[16:31], v[52:55], v[128:131], v[16:31]
	ds_read_b128 v[48:51], v57 offset:49280
	ds_read_b128 v[52:55], v57 offset:61568
	s_waitcnt lgkmcnt(0)
	v_mfma_f32_32x32x16_bf16 v[32:47], v[48:51], v[132:135], v[32:47]
	v_mfma_f32_32x32x16_bf16 v[16:31], v[52:55], v[132:135], v[16:31]
	ds_read_b128 v[48:51], v58 offset:49280
	ds_read_b128 v[52:55], v58 offset:61568
	s_waitcnt lgkmcnt(0)
	v_mfma_f32_32x32x16_bf16 v[32:47], v[48:51], v[136:139], v[32:47]
	v_mfma_f32_32x32x16_bf16 v[16:31], v[52:55], v[136:139], v[16:31]
	ds_read_b128 v[48:51], v59 offset:49280
	ds_read_b128 v[52:55], v59 offset:61568
	s_waitcnt lgkmcnt(0)
	v_mfma_f32_32x32x16_bf16 v[32:47], v[48:51], v[140:143], v[32:47]
	v_mfma_f32_32x32x16_bf16 v[16:31], v[52:55], v[140:143], v[16:31]
	ds_read_b128 v[48:51], v56 offset:49408
	ds_read_b128 v[52:55], v56 offset:61696
	s_waitcnt lgkmcnt(0)
	v_mfma_f32_32x32x16_bf16 v[32:47], v[48:51], v[144:147], v[32:47]
	v_mfma_f32_32x32x16_bf16 v[16:31], v[52:55], v[144:147], v[16:31]
	ds_read_b128 v[48:51], v57 offset:49408
	ds_read_b128 v[52:55], v57 offset:61696
	s_waitcnt lgkmcnt(0)
	v_mfma_f32_32x32x16_bf16 v[32:47], v[48:51], v[148:151], v[32:47]
	v_mfma_f32_32x32x16_bf16 v[16:31], v[52:55], v[148:151], v[16:31]
	ds_read_b128 v[48:51], v58 offset:49408
	ds_read_b128 v[52:55], v58 offset:61696
	s_waitcnt lgkmcnt(0)
	v_mfma_f32_32x32x16_bf16 v[32:47], v[48:51], v[152:155], v[32:47]
	v_mfma_f32_32x32x16_bf16 v[16:31], v[52:55], v[152:155], v[16:31]
	ds_read_b128 v[48:51], v59 offset:49408
	ds_read_b128 v[52:55], v59 offset:61696
	s_waitcnt lgkmcnt(0)
; #define SBAR() __builtin_amdgcn_sched_barrier(0)
; #define PK8(P, BASE, OUT) do { u32x4 w = {cvt_pk_bf16(P[BASE + 0], P[BASE + 1]), cvt_pk_bf16(P[BASE + 2], P[BASE + 3]), cvt_pk_bf16(P[BASE + 4], P[BASE + 5]), cvt_pk_bf16(P[BASE + 6], P[BASE + 7])}; \
;     OUT = *reinterpret_cast<bf16x8*>(&w); } while (0)
; #define VMW0() asm volatile("s_waitcnt vmcnt(0)" ::: "memory")
; template <int D0> __device__ __forceinline__ void pv_one(f32x16& od, unsigned vb, bf16x8 pa0, bf16x8 pa1, bf16x8 pa2, bf16x8 pa3) {
;     const s16x4 l0 = tr_read<v_rd_off(D0, 0, 0)>(vb), h0 = tr_read<v_rd_off(D0, 0, 1)>(vb), l1 = tr_read<v_rd_off(D0, 1, 0)>(vb), h1 = tr_read<v_rd_off(D0, 1, 1)>(vb);
;     const s16x4 l2 = tr_read<v_rd_off(D0, 2, 0)>(vb), h2 = tr_read<v_rd_off(D0, 2, 1)>(vb), l3 = tr_read<v_rd_off(D0, 3, 0)>(vb), h3 = tr_read<v_rd_off(D0, 3, 1)>(vb);
;     asm volatile("s_waitcnt lgkmcnt(0)" ::: "memory"); SBAR();
;     ...
;     od = __builtin_amdgcn_mfma_f32_32x32x16_bf16(pa0, PK(l0, h0), od, 0, 0, 0);
;     od = __builtin_amdgcn_mfma_f32_32x32x16_bf16(pa1, PK(l1, h1), od, 0, 0, 0);
;     od = __builtin_amdgcn_mfma_f32_32x32x16_bf16(pa2, PK(l2, h2), od, 0, 0, 0);
;     od = __builtin_amdgcn_mfma_f32_32x32x16_bf16(pa3, PK(l3, h3), od, 0, 0, 0);
;     ...
; }
; __device__ __forceinline__ void pv_d0(f32x16 (&o)[4], unsigned vb, bf16x8 pa0, bf16x8 pa1, bf16x8 pa2, bf16x8 pa3) {
;     pv_one<0>(o[0], vb, pa0, pa1, pa2, pa3); pv_one<1>(o[1], vb, pa0, pa1, pa2, pa3); pv_one<2>(o[2], vb, pa0, pa1, pa2, pa3); pv_one<3>(o[3], vb, pa0, pa1, pa2, pa3);
; }
; __device__ __forceinline__ void partialSM(f32x16& p0, f32x16& p1) {
; #pragma unroll
;     for (int r = 0; r < 16; ++r) p0[r] = __builtin_amdgcn_exp2f(p0[r]);
; }
; __device__ __forceinline__ void finishSM(f32x16& p0, f32x16& p1, float& l_reg, bf16x8& pa0, bf16x8& pa1, bf16x8& pa2, bf16x8& pa3) {
; #pragma unroll
;     for (int r = 0; r < 16; ++r) p1[r] = __builtin_amdgcn_exp2f(p1[r]);
;     float ps = 0;
; #pragma unroll
;     for (int r = 0; r < 16; ++r) ps += p0[r];
; #pragma unroll
;     for (int r = 0; r < 16; ++r) ps += p1[r];
;     l_reg += ps;
;     ...
;     PK8(p0, 0, pa0); PK8(p0, 8, pa1); PK8(p1, 0, pa2); PK8(p1, 8, pa3);
;     ...
; }
; template <int DQK, bool DOUBLE> ...
;     ...
;             if (j + 1 < NT) { VMW0(); __syncthreads(); if (j + 3 < NT) DMA(j + 3, bc); }
	v_mfma_f32_32x32x16_bf16 v[32:47], v[48:51], v[156:159], v[32:47]
	v_mfma_f32_32x32x16_bf16 v[16:31], v[52:55], v[156:159], v[16:31]
	s_nop 10
	v_exp_f32_e32 v32, v32
	v_exp_f32_e32 v33, v33
	v_exp_f32_e32 v34, v34
	v_exp_f32_e32 v35, v35
	v_exp_f32_e32 v36, v36
	v_add_f32_e32 v48, 0, v32
	v_exp_f32_e32 v37, v37
	v_add_f32_e32 v48, v33, v48
	v_exp_f32_e32 v38, v38
	v_add_f32_e32 v48, v34, v48
	v_exp_f32_e32 v39, v39
	v_add_f32_e32 v48, v35, v48
	v_exp_f32_e32 v40, v40
	v_add_f32_e32 v48, v36, v48
	v_exp_f32_e32 v41, v41
	v_add_f32_e32 v48, v37, v48
	v_exp_f32_e32 v42, v42
	v_add_f32_e32 v48, v38, v48
	v_exp_f32_e32 v43, v43
	v_add_f32_e32 v48, v39, v48
	v_exp_f32_e32 v44, v44
	v_add_f32_e32 v48, v40, v48
	v_exp_f32_e32 v45, v45
	v_add_f32_e32 v48, v41, v48
	v_exp_f32_e32 v46, v46
	v_add_f32_e32 v48, v42, v48
	v_exp_f32_e32 v47, v47
	v_add_f32_e32 v48, v43, v48
	v_exp_f32_e32 v16, v16
	v_add_f32_e32 v48, v44, v48
	v_exp_f32_e32 v17, v17
	v_add_f32_e32 v48, v45, v48
	v_exp_f32_e32 v18, v18
	v_add_f32_e32 v48, v46, v48
	v_exp_f32_e32 v19, v19
	v_add_f32_e32 v48, v47, v48
	v_exp_f32_e32 v20, v20
	v_add_f32_e32 v48, v16, v48
	v_exp_f32_e32 v21, v21
	v_add_f32_e32 v48, v17, v48
	v_exp_f32_e32 v22, v22
	v_add_f32_e32 v48, v18, v48
	v_exp_f32_e32 v23, v23
	v_add_f32_e32 v48, v19, v48
	v_exp_f32_e32 v24, v24
	v_add_f32_e32 v48, v20, v48
	v_exp_f32_e32 v25, v25
	v_add_f32_e32 v48, v21, v48
	v_exp_f32_e32 v26, v26
	v_add_f32_e32 v48, v22, v48
	v_exp_f32_e32 v27, v27
	v_add_f32_e32 v48, v23, v48
	v_exp_f32_e32 v28, v28
	v_add_f32_e32 v48, v24, v48
	v_exp_f32_e32 v29, v29
	v_add_f32_e32 v48, v25, v48
	v_exp_f32_e32 v30, v30
	v_add_f32_e32 v48, v26, v48
	v_exp_f32_e32 v31, v31
	v_add_f32_e32 v48, v27, v48
	v_add_f32_e32 v48, v28, v48
	v_add_f32_e32 v48, v29, v48
	v_add_f32_e32 v48, v30, v48
	v_add_f32_e32 v48, v31, v48
	v_add_f32_e32 v202, 0, v48
	v_cvt_pk_bf16_f32 v64, v32, v33
	v_cvt_pk_bf16_f32 v65, v34, v35
	v_cvt_pk_bf16_f32 v66, v36, v37
	v_cvt_pk_bf16_f32 v67, v38, v39
	v_cvt_pk_bf16_f32 v90, v40, v41
	v_cvt_pk_bf16_f32 v91, v42, v43
	v_cvt_pk_bf16_f32 v92, v44, v45
	v_cvt_pk_bf16_f32 v93, v46, v47
	v_cvt_pk_bf16_f32 v94, v16, v17
	v_cvt_pk_bf16_f32 v95, v18, v19
	v_cvt_pk_bf16_f32 v96, v20, v21
	v_cvt_pk_bf16_f32 v97, v22, v23
	v_cvt_pk_bf16_f32 v98, v24, v25
	v_cvt_pk_bf16_f32 v99, v26, v27
	v_cvt_pk_bf16_f32 v100, v28, v29
	v_cvt_pk_bf16_f32 v101, v30, v31
	ds_read_b64_tr_b16 v[16:17], v191 offset:0
	ds_read_b64_tr_b16 v[18:19], v191 offset:0x800
	ds_read_b64_tr_b16 v[32:33], v191 offset:0x1000
	ds_read_b64_tr_b16 v[34:35], v191 offset:0x1800
	ds_read_b64_tr_b16 v[36:37], v191 offset:0x2000
	ds_read_b64_tr_b16 v[38:39], v191 offset:0x2800
	ds_read_b64_tr_b16 v[40:41], v191 offset:0x3000
	ds_read_b64_tr_b16 v[42:43], v191 offset:0x3800
	s_waitcnt lgkmcnt(0)
	s_nop 0
	v_mfma_f32_32x32x16_bf16 v[16:31], v[64:67], v[16:19], 0
	v_mfma_f32_32x32x16_bf16 v[16:31], v[90:93], v[32:35], v[16:31]
	ds_read_b64_tr_b16 v[32:33], v191 offset:0x200
	ds_read_b64_tr_b16 v[34:35], v191 offset:0xa00
	ds_read_b64_tr_b16 v[48:49], v191 offset:0x1200
	ds_read_b64_tr_b16 v[50:51], v191 offset:0x1a00
	ds_read_b64_tr_b16 v[52:53], v191 offset:0x2200
	ds_read_b64_tr_b16 v[54:55], v191 offset:0x2a00
	ds_read_b64_tr_b16 v[56:57], v191 offset:0x3200
	v_mfma_f32_32x32x16_bf16 v[16:31], v[94:97], v[36:39], v[16:31]
	ds_read_b64_tr_b16 v[58:59], v191 offset:0x3a00
	s_waitcnt lgkmcnt(0)
	v_mfma_f32_32x32x16_bf16 v[16:31], v[98:101], v[40:43], v[16:31]
	v_mfma_f32_32x32x16_bf16 v[32:47], v[64:67], v[32:35], 0
	v_mfma_f32_32x32x16_bf16 v[32:47], v[90:93], v[48:51], v[32:47]
	ds_read_b64_tr_b16 v[48:49], v191 offset:0x400
	ds_read_b64_tr_b16 v[50:51], v191 offset:0xc00
	ds_read_b64_tr_b16 v[68:69], v191 offset:0x1400
	ds_read_b64_tr_b16 v[70:71], v191 offset:0x1c00
	ds_read_b64_tr_b16 v[72:73], v191 offset:0x2400
	ds_read_b64_tr_b16 v[74:75], v191 offset:0x2c00
	ds_read_b64_tr_b16 v[76:77], v191 offset:0x3400
	v_mfma_f32_32x32x16_bf16 v[32:47], v[94:97], v[52:55], v[32:47]
	ds_read_b64_tr_b16 v[78:79], v191 offset:0x3c00
	s_waitcnt lgkmcnt(0)
	v_mfma_f32_32x32x16_bf16 v[32:47], v[98:101], v[56:59], v[32:47]
	v_mfma_f32_32x32x16_bf16 v[48:63], v[64:67], v[48:51], 0
	v_mfma_f32_32x32x16_bf16 v[48:63], v[90:93], v[68:71], v[48:63]
	ds_read_b64_tr_b16 v[68:69], v191 offset:0x600
	ds_read_b64_tr_b16 v[70:71], v191 offset:0xe00
	ds_read_b64_tr_b16 v[102:103], v191 offset:0x1600
	ds_read_b64_tr_b16 v[104:105], v191 offset:0x1e00
	ds_read_b64_tr_b16 v[106:107], v191 offset:0x2600
	ds_read_b64_tr_b16 v[108:109], v191 offset:0x2e00
	ds_read_b64_tr_b16 v[194:195], v191 offset:0x3600
	v_mfma_f32_32x32x16_bf16 v[48:63], v[94:97], v[72:75], v[48:63]
	ds_read_b64_tr_b16 v[196:197], v191 offset:0x3e00
	s_waitcnt lgkmcnt(0)
	v_mfma_f32_32x32x16_bf16 v[48:63], v[98:101], v[76:79], v[48:63]
	v_mfma_f32_32x32x16_bf16 v[64:79], v[64:67], v[68:71], 0
	s_ashr_i32 s61, s60, 31
	v_lshl_add_u64 v[110:111], v[168:169], 0, s[60:61]
	v_lshlrev_b64 v[110:111], 11, v[110:111]
	v_lshl_add_u64 v[110:111], s[58:59], 0, v[110:111]
	s_mov_b32 m0, s3
	v_lshl_add_u64 v[110:111], v[110:111], 0, v[80:81]
	s_waitcnt vmcnt(0)
	s_waitcnt vmcnt(0)
	s_barrier
	global_load_lds_dwordx4 v[110:111], off
	v_lshl_add_u64 v[110:111], v[170:171], 0, s[60:61]
	v_mfma_f32_32x32x16_bf16 v[64:79], v[90:93], v[102:105], v[64:79]
	v_lshlrev_b64 v[90:91], 11, v[110:111]
	v_lshl_add_u64 v[90:91], s[58:59], 0, v[90:91]
	v_lshl_add_u64 v[90:91], v[90:91], 0, v[80:81]
	s_mov_b32 m0, s21
	v_lshl_add_u64 v[198:199], s[56:57], 0, v[86:87]
	global_load_lds_dwordx4 v[90:91], off
	v_lshl_add_u64 v[90:91], v[172:173], 0, s[60:61]
	v_mad_u64_u32 v[92:93], s[42:43], v90, s41, v[84:85]
	v_mad_i32_i24 v93, v91, s41, v93
	v_lshl_add_u64 v[90:91], v[92:93], 0, v[82:83]
	s_mov_b32 m0, s20
	v_mfma_f32_32x32x16_bf16 v[64:79], v[94:97], v[106:109], v[64:79]
	global_load_lds_dwordx4 v[90:91], off
	v_lshl_add_u64 v[90:91], v[174:175], 0, s[60:61]
	v_mad_u64_u32 v[92:93], s[20:21], v90, s41, v[84:85]
	v_mad_i32_i24 v93, v91, s41, v93
	v_lshl_add_u64 v[90:91], v[92:93], 0, v[86:87]
	s_mov_b32 m0, s33
	v_mfma_f32_32x32x16_bf16 v[64:79], v[98:101], v[194:197], v[64:79]
	global_load_lds_dwordx4 v[90:91], off
	v_lshl_add_u64 v[90:91], v[192:193], 0, s[60:61]
	v_mad_u64_u32 v[84:85], s[20:21], v90, s41, v[84:85]
	v_mad_i32_i24 v85, v91, s41, v85
	v_lshl_add_u64 v[84:85], v[84:85], 0, v[88:89]
	s_mov_b32 m0, s35
	v_lshl_add_u64 v[194:195], s[58:59], 0, v[80:81]
	global_load_lds_dwordx4 v[84:85], off
	v_lshl_add_u64 v[196:197], s[56:57], 0, v[82:83]
	v_lshl_add_u64 v[200:201], s[56:57], 0, v[88:89]
	s_add_i32 s20, s71, -1
	s_mov_b32 s21, 0
	s_mov_b32 s56, s44
	s_mov_b32 s35, 0
	s_waitcnt lgkmcnt(0)
; #define LAS __attribute__((address_space(3)))
; #define SBAR() __builtin_amdgcn_sched_barrier(0)
; template <int D0> __device__ __forceinline__ void pv_one(f32x16& od, unsigned vb, bf16x8 pa0, bf16x8 pa1, bf16x8 pa2, bf16x8 pa3) {
;     const s16x4 l0 = tr_read<v_rd_off(D0, 0, 0)>(vb), h0 = tr_read<v_rd_off(D0, 0, 1)>(vb), l1 = tr_read<v_rd_off(D0, 1, 0)>(vb), h1 = tr_read<v_rd_off(D0, 1, 1)>(vb);
;     const s16x4 l2 = tr_read<v_rd_off(D0, 2, 0)>(vb), h2 = tr_read<v_rd_off(D0, 2, 1)>(vb), l3 = tr_read<v_rd_off(D0, 3, 0)>(vb), h3 = tr_read<v_rd_off(D0, 3, 1)>(vb);
;     asm volatile("s_waitcnt lgkmcnt(0)" ::: "memory"); SBAR();
;     ...
;     od = __builtin_amdgcn_mfma_f32_32x32x16_bf16(pa0, PK(l0, h0), od, 0, 0, 0);
;     od = __builtin_amdgcn_mfma_f32_32x32x16_bf16(pa1, PK(l1, h1), od, 0, 0, 0);
;     od = __builtin_amdgcn_mfma_f32_32x32x16_bf16(pa2, PK(l2, h2), od, 0, 0, 0);
;     od = __builtin_amdgcn_mfma_f32_32x32x16_bf16(pa3, PK(l3, h3), od, 0, 0, 0);
; __device__ __forceinline__ void partialSM(f32x16& p0, f32x16& p1) {
; #pragma unroll
;     for (int r = 0; r < 16; ++r) p0[r] = __builtin_amdgcn_exp2f(p0[r]);
; }
; __device__ __forceinline__ void finishSM(f32x16& p0, f32x16& p1, float& l_reg, bf16x8& pa0, bf16x8& pa1, bf16x8& pa2, bf16x8& pa3) {
; #pragma unroll
;     for (int r = 0; r < 16; ++r) p1[r] = __builtin_amdgcn_exp2f(p1[r]);
;     float ps = 0;
; #pragma unroll
;     for (int r = 0; r < 16; ++r) ps += p0[r];
; #pragma unroll
;     for (int r = 0; r < 16; ++r) ps += p1[r];
;     l_reg += ps;
;     ...
;     PK8(p0, 0, pa0); PK8(p0, 8, pa1); PK8(p1, 0, pa2); PK8(p1, 8, pa3);
; template <int DQK>
; __device__ __forceinline__ void qkt(f32x16& p0, f32x16& p1, const LAS char* Ks, const bf16x8 (&qr)[DQK / 16], const int (&ka)[8], float nMB) {
;     constexpr int RB = DQK * 2, NA = (RB == 256) ? 8 : 4;
; #pragma unroll
;     for (int r = 0; r < 16; ++r) { p0[r] = nMB; p1[r] = nMB; }
; #pragma unroll
;     for (int d0 = 0; d0 < DQK / 16; ++d0) {
;         const LAS char* a = Ks + ka[d0 % NA] + (d0 / NA) * (NA * 32);
;         const bf16x8 b0 = *(const LAS bf16x8*)(a);
;         const bf16x8 b1 = *(const LAS bf16x8*)(a + 32 * RB);
;         p0 = __builtin_amdgcn_mfma_f32_32x32x16_bf16(b0, qr[d0], p0, 0, 0, 0);
;         p1 = __builtin_amdgcn_mfma_f32_32x32x16_bf16(b1, qr[d0], p1, 0, 0, 0); }
; }
.LBB0_142:
	s_mov_b32 s33, s4
	s_mov_b32 s4, s35
	s_mul_i32 s35, s5, 0x6000
	s_add_i32 s35, s35, 0
	s_lshl_b32 s41, s5, 14
	v_add_u32_e32 v204, s35, v161
	v_add_u32_e32 v205, s35, v165
	v_add_u32_e32 v206, s35, v167
	v_add_u32_e32 v207, s35, v187
	v_add_u32_e32 v184, s41, v191
	ds_read_b128 v[220:223], v204 offset:49152
	ds_read_b128 v[238:241], v205 offset:49152
	ds_read_b128 v[242:245], v206 offset:49152
	s_waitcnt lgkmcnt(2)
	v_mfma_f32_32x32x16_bf16 v[96:111], v[220:223], v[112:115], v[0:15]
	ds_read_b128 v[246:249], v207 offset:49152
	s_waitcnt lgkmcnt(2)
	v_mfma_f32_32x32x16_bf16 v[96:111], v[238:241], v[116:119], v[96:111]
	ds_read_b128 v[220:223], v204 offset:49280
	s_waitcnt lgkmcnt(2)
	v_mfma_f32_32x32x16_bf16 v[96:111], v[242:245], v[120:123], v[96:111]
	ds_read_b128 v[238:241], v205 offset:49280
	s_waitcnt lgkmcnt(2)
	v_mfma_f32_32x32x16_bf16 v[96:111], v[246:249], v[124:127], v[96:111]
	ds_read_b128 v[242:245], v206 offset:49280
	s_waitcnt lgkmcnt(2)
	v_mfma_f32_32x32x16_bf16 v[96:111], v[220:223], v[128:131], v[96:111]
	ds_read_b128 v[246:249], v207 offset:49280
	s_waitcnt lgkmcnt(2)
	v_mfma_f32_32x32x16_bf16 v[96:111], v[238:241], v[132:135], v[96:111]
	ds_read_b128 v[220:223], v204 offset:49408
	s_waitcnt lgkmcnt(2)
	v_mfma_f32_32x32x16_bf16 v[96:111], v[242:245], v[136:139], v[96:111]
	ds_read_b128 v[238:241], v205 offset:49408
	s_waitcnt lgkmcnt(2)
	v_mfma_f32_32x32x16_bf16 v[96:111], v[246:249], v[140:143], v[96:111]
	ds_read_b128 v[242:245], v206 offset:49408
	s_waitcnt lgkmcnt(2)
	v_mfma_f32_32x32x16_bf16 v[96:111], v[220:223], v[144:147], v[96:111]
	ds_read_b128 v[246:249], v207 offset:49408
	s_waitcnt lgkmcnt(2)
	v_mfma_f32_32x32x16_bf16 v[96:111], v[238:241], v[148:151], v[96:111]
	ds_read_b128 v[220:223], v204 offset:61440
	s_waitcnt lgkmcnt(2)
	v_mfma_f32_32x32x16_bf16 v[96:111], v[242:245], v[152:155], v[96:111]
	ds_read_b128 v[238:241], v205 offset:61440
	s_waitcnt lgkmcnt(2)
	v_mfma_f32_32x32x16_bf16 v[96:111], v[246:249], v[156:159], v[96:111]
	ds_read_b128 v[242:245], v206 offset:61440
	s_waitcnt lgkmcnt(2)
	v_mfma_f32_32x32x16_bf16 v[80:95], v[220:223], v[112:115], v[0:15]
	ds_read_b128 v[246:249], v207 offset:61440
	s_waitcnt lgkmcnt(2)
	v_mfma_f32_32x32x16_bf16 v[80:95], v[238:241], v[116:119], v[80:95]
	ds_read_b128 v[220:223], v204 offset:61568
	s_nop 4
	v_exp_f32_e32 v96, v96
	v_exp_f32_e32 v97, v97
	v_exp_f32_e32 v104, v104
	s_waitcnt lgkmcnt(2)
	v_mfma_f32_32x32x16_bf16 v[80:95], v[242:245], v[120:123], v[80:95]
	ds_read_b128 v[238:241], v205 offset:61568
	v_exp_f32_e32 v98, v98
	v_exp_f32_e32 v105, v105
	s_waitcnt lgkmcnt(2)
	v_mfma_f32_32x32x16_bf16 v[80:95], v[246:249], v[124:127], v[80:95]
	ds_read_b128 v[242:245], v206 offset:61568
	v_exp_f32_e32 v99, v99
	v_exp_f32_e32 v106, v106
	s_waitcnt lgkmcnt(2)
	v_mfma_f32_32x32x16_bf16 v[80:95], v[220:223], v[128:131], v[80:95]
	ds_read_b128 v[246:249], v207 offset:61568
	v_exp_f32_e32 v100, v100
	v_exp_f32_e32 v107, v107
	s_waitcnt lgkmcnt(2)
	v_mfma_f32_32x32x16_bf16 v[80:95], v[238:241], v[132:135], v[80:95]
	ds_read_b128 v[220:223], v204 offset:61696
	v_exp_f32_e32 v101, v101
	v_exp_f32_e32 v108, v108
	s_waitcnt lgkmcnt(2)
	v_mfma_f32_32x32x16_bf16 v[80:95], v[242:245], v[136:139], v[80:95]
	ds_read_b128 v[238:241], v205 offset:61696
	v_exp_f32_e32 v102, v102
	v_exp_f32_e32 v109, v109
	s_waitcnt lgkmcnt(2)
	v_mfma_f32_32x32x16_bf16 v[80:95], v[246:249], v[140:143], v[80:95]
	ds_read_b128 v[242:245], v206 offset:61696
	v_exp_f32_e32 v103, v103
	v_exp_f32_e32 v110, v110
	s_waitcnt lgkmcnt(2)
	v_mfma_f32_32x32x16_bf16 v[80:95], v[220:223], v[144:147], v[80:95]
	ds_read_b128 v[246:249], v207 offset:61696
	v_exp_f32_e32 v111, v111
	s_waitcnt lgkmcnt(2)
	v_mfma_f32_32x32x16_bf16 v[80:95], v[238:241], v[148:151], v[80:95]
	ds_read_b64_tr_b16 v[220:221], v184 offset:0
	ds_read_b64_tr_b16 v[222:223], v184 offset:2048
	v_cvt_pk_bf16_f32 v204, v96, v97
	v_cvt_pk_bf16_f32 v205, v98, v99
	v_cvt_pk_bf16_f32 v208, v104, v105
	s_waitcnt lgkmcnt(3)
	v_mfma_f32_32x32x16_bf16 v[80:95], v[242:245], v[152:155], v[80:95]
	ds_read_b64_tr_b16 v[238:239], v184 offset:512
	ds_read_b64_tr_b16 v[240:241], v184 offset:2560
	v_cvt_pk_bf16_f32 v206, v100, v101
	v_cvt_pk_bf16_f32 v209, v106, v107
	s_waitcnt lgkmcnt(4)
	v_mfma_f32_32x32x16_bf16 v[80:95], v[246:249], v[156:159], v[80:95]
	ds_read_b64_tr_b16 v[242:243], v184 offset:1024
	ds_read_b64_tr_b16 v[244:245], v184 offset:3072
	v_cvt_pk_bf16_f32 v207, v102, v103
	v_cvt_pk_bf16_f32 v210, v108, v109
	v_add_f32_e32 v96, 0, v96
	v_add_f32_e32 v96, v97, v96
	s_waitcnt lgkmcnt(4)
	v_mfma_f32_32x32x16_bf16 v[16:31], v[204:207], v[220:223], v[16:31]
	ds_read_b64_tr_b16 v[246:247], v184 offset:1536
	ds_read_b64_tr_b16 v[248:249], v184 offset:3584
	v_cvt_pk_bf16_f32 v211, v110, v111
	v_add_f32_e32 v96, v98, v96
	v_add_f32_e32 v96, v99, v96
	v_add_f32_e32 v96, v100, v96
	s_waitcnt lgkmcnt(4)
	v_mfma_f32_32x32x16_bf16 v[32:47], v[204:207], v[238:241], v[32:47]
	ds_read_b64_tr_b16 v[220:221], v184 offset:4096
	ds_read_b64_tr_b16 v[222:223], v184 offset:6144
	v_exp_f32_e32 v80, v80
	v_exp_f32_e32 v81, v81
	v_exp_f32_e32 v88, v88
	v_exp_f32_e32 v89, v89
	v_add_f32_e32 v96, v101, v96
	v_add_f32_e32 v96, v102, v96
	s_waitcnt lgkmcnt(4)
	v_mfma_f32_32x32x16_bf16 v[48:63], v[204:207], v[242:245], v[48:63]
	ds_read_b64_tr_b16 v[238:239], v184 offset:4608
	ds_read_b64_tr_b16 v[240:241], v184 offset:6656
	v_exp_f32_e32 v82, v82
	v_exp_f32_e32 v83, v83
	v_exp_f32_e32 v90, v90
	v_add_f32_e32 v96, v103, v96
	v_add_f32_e32 v96, v104, v96
	s_waitcnt lgkmcnt(4)
; #define SBAR() __builtin_amdgcn_sched_barrier(0)
; #define PK8(P, BASE, OUT) do { u32x4 w = {cvt_pk_bf16(P[BASE + 0], P[BASE + 1]), cvt_pk_bf16(P[BASE + 2], P[BASE + 3]), cvt_pk_bf16(P[BASE + 4], P[BASE + 5]), cvt_pk_bf16(P[BASE + 6], P[BASE + 7])}; \
;     OUT = *reinterpret_cast<bf16x8*>(&w); } while (0)
; #define VMW0() asm volatile("s_waitcnt vmcnt(0)" ::: "memory")
; template <int D0> __device__ __forceinline__ void pv_one(f32x16& od, unsigned vb, bf16x8 pa0, bf16x8 pa1, bf16x8 pa2, bf16x8 pa3) {
;     const s16x4 l0 = tr_read<v_rd_off(D0, 0, 0)>(vb), h0 = tr_read<v_rd_off(D0, 0, 1)>(vb), l1 = tr_read<v_rd_off(D0, 1, 0)>(vb), h1 = tr_read<v_rd_off(D0, 1, 1)>(vb);
;     const s16x4 l2 = tr_read<v_rd_off(D0, 2, 0)>(vb), h2 = tr_read<v_rd_off(D0, 2, 1)>(vb), l3 = tr_read<v_rd_off(D0, 3, 0)>(vb), h3 = tr_read<v_rd_off(D0, 3, 1)>(vb);
;     asm volatile("s_waitcnt lgkmcnt(0)" ::: "memory"); SBAR();
;     ...
;     od = __builtin_amdgcn_mfma_f32_32x32x16_bf16(pa0, PK(l0, h0), od, 0, 0, 0);
;     od = __builtin_amdgcn_mfma_f32_32x32x16_bf16(pa1, PK(l1, h1), od, 0, 0, 0);
;     od = __builtin_amdgcn_mfma_f32_32x32x16_bf16(pa2, PK(l2, h2), od, 0, 0, 0);
;     od = __builtin_amdgcn_mfma_f32_32x32x16_bf16(pa3, PK(l3, h3), od, 0, 0, 0);
;     ...
; }
; __device__ __forceinline__ void pv_d0(f32x16 (&o)[4], unsigned vb, bf16x8 pa0, bf16x8 pa1, bf16x8 pa2, bf16x8 pa3) {
;     pv_one<0>(o[0], vb, pa0, pa1, pa2, pa3); pv_one<1>(o[1], vb, pa0, pa1, pa2, pa3); pv_one<2>(o[2], vb, pa0, pa1, pa2, pa3); pv_one<3>(o[3], vb, pa0, pa1, pa2, pa3);
; }
; __device__ __forceinline__ void finishSM(f32x16& p0, f32x16& p1, float& l_reg, bf16x8& pa0, bf16x8& pa1, bf16x8& pa2, bf16x8& pa3) {
;     ...
; #pragma unroll
;     for (int r = 0; r < 16; ++r) ps += p1[r];
;     l_reg += ps;
;     ...
;     PK8(p0, 0, pa0); PK8(p0, 8, pa1); PK8(p1, 0, pa2); PK8(p1, 8, pa3);
; template <int DQK, bool DOUBLE> ...
;     ...
;             if (j + 1 < NT) { VMW0(); __syncthreads(); if (j + 3 < NT) DMA(j + 3, bc); }
	v_mfma_f32_32x32x16_bf16 v[64:79], v[204:207], v[246:249], v[64:79]
	ds_read_b64_tr_b16 v[242:243], v184 offset:5120
	ds_read_b64_tr_b16 v[244:245], v184 offset:7168
	v_exp_f32_e32 v84, v84
	v_exp_f32_e32 v85, v85
	v_exp_f32_e32 v91, v91
	v_add_f32_e32 v96, v105, v96
	v_add_f32_e32 v96, v106, v96
	s_waitcnt lgkmcnt(4)
	v_mfma_f32_32x32x16_bf16 v[16:31], v[208:211], v[220:223], v[16:31]
	ds_read_b64_tr_b16 v[246:247], v184 offset:5632
	ds_read_b64_tr_b16 v[248:249], v184 offset:7680
	v_exp_f32_e32 v86, v86
	v_exp_f32_e32 v87, v87
	v_exp_f32_e32 v92, v92
	v_add_f32_e32 v96, v107, v96
	v_add_f32_e32 v96, v108, v96
	s_waitcnt lgkmcnt(4)
	v_mfma_f32_32x32x16_bf16 v[32:47], v[208:211], v[238:241], v[32:47]
	ds_read_b64_tr_b16 v[220:221], v184 offset:8192
	ds_read_b64_tr_b16 v[222:223], v184 offset:10240
	v_cvt_pk_bf16_f32 v212, v80, v81
	v_cvt_pk_bf16_f32 v213, v82, v83
	v_exp_f32_e32 v93, v93
	v_add_f32_e32 v96, v109, v96
	v_add_f32_e32 v96, v110, v96
	s_waitcnt lgkmcnt(4)
	v_mfma_f32_32x32x16_bf16 v[48:63], v[208:211], v[242:245], v[48:63]
	ds_read_b64_tr_b16 v[238:239], v184 offset:8704
	ds_read_b64_tr_b16 v[240:241], v184 offset:10752
	v_cvt_pk_bf16_f32 v214, v84, v85
	v_exp_f32_e32 v94, v94
	v_add_f32_e32 v96, v111, v96
	s_waitcnt lgkmcnt(4)
	v_mfma_f32_32x32x16_bf16 v[64:79], v[208:211], v[246:249], v[64:79]
	ds_read_b64_tr_b16 v[242:243], v184 offset:9216
	ds_read_b64_tr_b16 v[244:245], v184 offset:11264
	v_cvt_pk_bf16_f32 v215, v86, v87
	v_exp_f32_e32 v95, v95
	v_add_f32_e32 v80, v80, v96
	v_add_f32_e32 v80, v81, v80
	s_waitcnt lgkmcnt(4)
	v_mfma_f32_32x32x16_bf16 v[16:31], v[212:215], v[220:223], v[16:31]
	ds_read_b64_tr_b16 v[246:247], v184 offset:9728
	ds_read_b64_tr_b16 v[248:249], v184 offset:11776
	v_cvt_pk_bf16_f32 v216, v88, v89
	v_add_f32_e32 v80, v82, v80
	v_add_f32_e32 v80, v83, v80
	v_add_f32_e32 v80, v84, v80
	s_waitcnt lgkmcnt(4)
	v_mfma_f32_32x32x16_bf16 v[32:47], v[212:215], v[238:241], v[32:47]
	ds_read_b64_tr_b16 v[220:221], v184 offset:12288
	ds_read_b64_tr_b16 v[222:223], v184 offset:14336
	v_cvt_pk_bf16_f32 v217, v90, v91
	v_add_f32_e32 v80, v85, v80
	v_add_f32_e32 v80, v86, v80
	v_add_f32_e32 v80, v87, v80
	s_waitcnt lgkmcnt(4)
	v_mfma_f32_32x32x16_bf16 v[48:63], v[212:215], v[242:245], v[48:63]
	ds_read_b64_tr_b16 v[238:239], v184 offset:12800
	ds_read_b64_tr_b16 v[240:241], v184 offset:14848
	v_cvt_pk_bf16_f32 v218, v92, v93
	s_waitcnt lgkmcnt(4)
	v_mfma_f32_32x32x16_bf16 v[64:79], v[212:215], v[246:249], v[64:79]
	ds_read_b64_tr_b16 v[242:243], v184 offset:13312
	ds_read_b64_tr_b16 v[244:245], v184 offset:15360
	v_cvt_pk_bf16_f32 v219, v94, v95
	v_add_f32_e32 v80, v88, v80
	v_add_f32_e32 v80, v89, v80
	v_add_f32_e32 v80, v90, v80
	s_waitcnt lgkmcnt(4)
	v_mfma_f32_32x32x16_bf16 v[16:31], v[216:219], v[220:223], v[16:31]
	ds_read_b64_tr_b16 v[246:247], v184 offset:13824
	ds_read_b64_tr_b16 v[248:249], v184 offset:15872
	v_add_f32_e32 v80, v91, v80
	v_add_f32_e32 v80, v92, v80
	v_add_f32_e32 v80, v93, v80
	v_add_f32_e32 v80, v94, v80
	s_waitcnt lgkmcnt(4)
	v_mfma_f32_32x32x16_bf16 v[32:47], v[216:219], v[238:241], v[32:47]
	v_add_f32_e32 v80, v95, v80
	s_waitcnt lgkmcnt(2)
	v_mfma_f32_32x32x16_bf16 v[48:63], v[216:219], v[242:245], v[48:63]
	s_waitcnt lgkmcnt(0)
	v_mfma_f32_32x32x16_bf16 v[64:79], v[216:219], v[246:249], v[64:79]
	s_add_i32 s42, s21, 2
	s_cmp_ge_i32 s42, s71
	s_cbranch_scc1 .LBB0_145
	s_waitcnt vmcnt(0)
	s_add_i32 s42, s21, 4
	s_cmp_ge_i32 s42, s71
	s_waitcnt vmcnt(0)
	s_barrier
	s_cbranch_scc1 .LBB0_145
	s_ashr_i32 s57, s56, 31
	v_lshl_add_u64 v[184:185], s[56:57], 0, v[168:169]
	s_add_i32 s41, s3, s41
	v_lshlrev_b64 v[184:185], 11, v[184:185]
	v_lshl_add_u64 v[184:185], v[194:195], 0, v[184:185]
	s_mov_b32 m0, s41
	s_add_i32 s35, s35, s2
	global_load_lds_dwordx4 v[184:185], off
	v_lshl_add_u64 v[184:185], s[56:57], 0, v[170:171]
	v_lshlrev_b64 v[184:185], 11, v[184:185]
	v_lshl_add_u64 v[184:185], v[194:195], 0, v[184:185]
	s_add_i32 m0, s41, 0x2000
	s_movk_i32 s41, 0xc00
	global_load_lds_dwordx4 v[184:185], off
	v_lshl_add_u64 v[184:185], s[56:57], 0, v[172:173]
	v_mad_u64_u32 v[204:205], s[42:43], v184, s41, v[196:197]
	s_add_i32 m0, s35, 0xc000
	v_mad_i32_i24 v205, v185, s41, v205
	v_lshl_add_u64 v[184:185], s[56:57], 0, v[174:175]
	global_load_lds_dwordx4 v[204:205], off
	v_mad_u64_u32 v[204:205], s[42:43], v184, s41, v[198:199]
	v_mad_i32_i24 v205, v185, s41, v205
	s_add_i32 m0, s35, 0xe000
	v_lshl_add_u64 v[184:185], s[56:57], 0, v[192:193]
	global_load_lds_dwordx4 v[204:205], off
	v_mad_u64_u32 v[204:205], s[42:43], v184, s41, v[200:201]
	v_mad_i32_i24 v205, v185, s41, v205
	s_add_i32 m0, s35, 0x10000
	s_nop 0
	global_load_lds_dwordx4 v[204:205], off
.LBB0_145:
	s_add_i32 s56, s56, 64
	s_add_i32 s21, s21, 1
	s_cmp_lg_u32 s20, s21
	v_add_f32_e32 v202, v202, v80
	s_cbranch_scc0 .LBB0_147
	s_mov_b32 s35, s5
	s_mov_b32 s5, s33
	s_branch .LBB0_142
; #define LAS __attribute__((address_space(3)))
; __device__ __forceinline__ int crow(int r, int hi) { return (r & 3) + 8 * (r >> 2) + 4 * hi; }
; __device__ __forceinline__ void row_recip(float l_reg, float (&rli)[16], LAS float* li, int r32, int hi) {
;     { auto rr = __builtin_amdgcn_permlane32_swap(__float_as_uint(l_reg), __float_as_uint(l_reg), false, false);
;       l_reg = __uint_as_float(rr[0]) + __uint_as_float(rr[1]); }
;     if (hi == 0) li[r32] = l_reg;
;     asm volatile("s_waitcnt lgkmcnt(0)" ::: "memory");
; #pragma unroll
;     for (int r = 0; r < 16; ++r) rli[r] = __builtin_amdgcn_rcpf(li[crow(r, hi)]);
;     asm volatile("s_waitcnt lgkmcnt(0)" ::: "memory");
; }
; template <bool SUBLN>
; __device__ __forceinline__ void attn_out(const AttnBufs& T, f32x16 (&o)[4], int type, int h, size_t orow0, LAS char* lds, int wid, int lane, int r32, int hi) {
;     const int rr = lane >> 5, c4 = (lane & 31) * 4;
;     const int col = type * 1024 + h * 128 + c4;
;     const bf16_t* gp = T.GATE + (orow0 + rr) * 3072 + col; bf16_t* op = T.BR + (orow0 + rr) * 3072 + col;
;     u32x2 gg[16];
; #pragma unroll
;     for (int i = 0; i < 16; ++i) gg[i] = *(const u32x2*)(gp + (size_t)i * 2 * 3072);
;     __syncthreads();
; __device__ __forceinline__ void attn_item(const AttnBufs& T, int type, int b, int h, int qrow0, int NT, LAS char* lds, int tid_) {
;     ...
;         att::row_recip(l_reg, rli, li, r32, hi);
; #pragma unroll
;         for (int d0 = 0; d0 < 4; ++d0)
; #pragma unroll
;             for (int r = 0; r < 16; ++r) o[d0][r] *= rli[r];
;         attn_out<false>(T, o, 1, h, orow0, lds, wid, lane, r32, hi);
.LBB0_147:
	s_nop 11
	v_mov_b32_e32 v0, v202
	s_nop 1
	v_permlane32_swap_b32_e32 v202, v0
	v_cmp_gt_u32_e32 vcc, 32, v182
	s_and_saveexec_b64 s[56:57], vcc
	v_lshl_add_u32 v1, v181, 2, s90
	v_add_f32_e32 v0, v202, v0
	ds_write_b32 v1, v0
	s_or_b64 exec, exec, s[56:57]
	s_waitcnt lgkmcnt(0)
	v_add_u32_e32 v8, s90, v166
	ds_read_b128 v[0:3], v8
	ds_read_b128 v[4:7], v8 offset:32
	v_readlane_b32 s2, v251, 46
	v_readlane_b32 s3, v251, 47
	s_movk_i32 s4, 0x1800
	s_waitcnt lgkmcnt(0)
	v_rcp_f32_e32 v9, v0
	v_rcp_f32_e32 v10, v1
	v_rcp_f32_e32 v11, v2
	v_rcp_f32_e32 v12, v3
	ds_read_b128 v[0:3], v8 offset:64
	v_rcp_f32_e32 v4, v4
	v_rcp_f32_e32 v5, v5
	v_mul_f32_e32 v99, v34, v11
	v_mul_f32_e32 v100, v35, v12
	s_waitcnt lgkmcnt(0)
	v_rcp_f32_e32 v13, v0
	v_rcp_f32_e32 v14, v1
	v_rcp_f32_e32 v15, v2
	v_rcp_f32_e32 v80, v3
	ds_read_b128 v[0:3], v8 offset:96
	v_mov_b32_e32 v35, v177
	v_mul_f32_e32 v85, v20, v4
	v_mul_f32_e32 v86, v21, v5
	v_mul_f32_e32 v101, v36, v4
	s_waitcnt lgkmcnt(0)
	v_rcp_f32_e32 v0, v0
	v_rcp_f32_e32 v1, v1
	v_rcp_f32_e32 v2, v2
	v_rcp_f32_e32 v3, v3
	v_mul_f32_e32 v93, v28, v0
	v_mul_f32_e32 v44, v44, v0
	v_mul_f32_e32 v60, v60, v0
	v_mul_f32_e32 v76, v76, v0
	v_lshlrev_b32_e32 v0, 2, v182
	v_mul_f32_e32 v94, v29, v1
	v_mul_f32_e32 v95, v30, v2
	v_mul_f32_e32 v96, v31, v3
	v_mul_f32_e32 v45, v45, v1
	v_mul_f32_e32 v46, v46, v2
	v_mul_f32_e32 v47, v47, v3
	v_mul_f32_e32 v61, v61, v1
	v_mul_f32_e32 v62, v62, v2
	v_mul_f32_e32 v63, v63, v3
	v_mul_f32_e32 v77, v77, v1
	v_mul_f32_e32 v78, v78, v2
	v_mul_f32_e32 v79, v79, v3
	v_and_b32_e32 v34, 0x7c, v0
	v_lshl_add_u64 v[0:1], s[36:37], 0, v[176:177]
	v_mov_b64_e32 v[2:3], s[2:3]
	v_mul_f32_e32 v102, v37, v5
	v_mul_f32_e32 v52, v52, v4
	v_mul_f32_e32 v53, v53, v5
	v_mul_f32_e32 v68, v68, v4
	v_mul_f32_e32 v69, v69, v5
	v_mad_u64_u32 v[2:3], s[2:3], v0, s4, v[2:3]
	v_lshl_add_u64 v[4:5], v[34:35], 0, s[50:51]
	v_mul_f32_e32 v82, v17, v10
	v_mul_f32_e32 v83, v18, v11
	v_mul_f32_e32 v98, v33, v10
	v_mul_f32_e32 v49, v49, v10
	v_mul_f32_e32 v50, v50, v11
	v_mul_f32_e32 v65, v65, v10
	v_mul_f32_e32 v66, v66, v11
	v_mad_i32_i24 v3, v1, s4, v3
	v_lshlrev_b64 v[10:11], 1, v[4:5]
	s_waitcnt lgkmcnt(0)
	v_lshl_add_u64 v[2:3], v[2:3], 0, v[10:11]
	v_mul_f32_e32 v103, v40, v13
	v_mul_f32_e32 v104, v41, v14
	global_load_dwordx2 v[40:41], v[2:3], off offset:2048
	v_readlane_b32 s2, v251, 48
	v_readlane_b32 s3, v251, 49
	v_mul_f32_e32 v97, v32, v9
	v_mul_f32_e32 v91, v26, v15
	v_mov_b64_e32 v[4:5], s[2:3]
	v_mad_u64_u32 v[36:37], s[2:3], v0, s4, v[4:5]
	v_add_co_u32_e32 v0, vcc, s40, v2
	v_mad_i32_i24 v37, v1, s4, v37
	s_nop 0
	v_addc_co_u32_e32 v1, vcc, 0, v3, vcc
	global_load_dwordx2 v[32:33], v[0:1], off offset:2048
	v_add_co_u32_e32 v0, vcc, s82, v2
	s_mov_b32 s4, 0x9000
	s_nop 0
	v_addc_co_u32_e32 v1, vcc, 0, v3, vcc
	global_load_dwordx2 v[30:31], v[0:1], off offset:2048
	v_add_co_u32_e32 v0, vcc, s4, v2
	v_mul_f32_e32 v92, v27, v80
	s_nop 0
	v_addc_co_u32_e32 v1, vcc, 0, v3, vcc
	global_load_dwordx2 v[28:29], v[0:1], off offset:2048
	v_add_co_u32_e32 v0, vcc, s77, v2
	s_mov_b32 s5, 0xf000
	s_nop 0
	v_addc_co_u32_e32 v1, vcc, 0, v3, vcc
	global_load_dwordx2 v[26:27], v[0:1], off offset:2048
	v_rcp_f32_e32 v6, v6
	v_rcp_f32_e32 v7, v7
	v_add_co_u32_e32 v0, vcc, s5, v2
	v_mul_f32_e32 v89, v24, v13
	s_nop 0
	v_addc_co_u32_e32 v1, vcc, 0, v3, vcc
	v_mul_f32_e32 v90, v25, v14
	global_load_dwordx2 v[24:25], v[0:1], off offset:2048
	v_add_co_u32_e32 v0, vcc, s85, v2
	s_mov_b32 s20, 0x15000
	s_nop 0
	v_addc_co_u32_e32 v1, vcc, 0, v3, vcc
	v_mul_f32_e32 v87, v22, v6
	v_mul_f32_e32 v88, v23, v7
	global_load_dwordx2 v[22:23], v[0:1], off offset:2048
	v_add_co_u32_e32 v0, vcc, s20, v2
	s_mov_b32 s21, 0x1b000
	s_nop 0
	v_addc_co_u32_e32 v1, vcc, 0, v3, vcc
	global_load_dwordx2 v[20:21], v[0:1], off offset:2048
	v_add_co_u32_e32 v0, vcc, s76, v2
	v_mul_f32_e32 v84, v19, v12
	s_nop 0
	v_addc_co_u32_e32 v1, vcc, 0, v3, vcc
	global_load_dwordx2 v[18:19], v[0:1], off offset:2048
	v_add_co_u32_e32 v0, vcc, s21, v2
	v_mul_f32_e32 v81, v16, v9
	s_nop 0
	v_addc_co_u32_e32 v1, vcc, 0, v3, vcc
	global_load_dwordx2 v[16:17], v[0:1], off offset:2048
	v_add_co_u32_e32 v0, vcc, s92, v2
	s_mov_b32 s3, 0x21000
	s_nop 0
	v_addc_co_u32_e32 v1, vcc, 0, v3, vcc
	v_mul_f32_e32 v42, v42, v15
	v_mul_f32_e32 v57, v57, v14
	v_mul_f32_e32 v58, v58, v15
	v_mul_f32_e32 v73, v73, v14
	v_mul_f32_e32 v74, v74, v15
	global_load_dwordx2 v[14:15], v[0:1], off offset:2048
	v_add_co_u32_e32 v0, vcc, s3, v2
	v_mul_f32_e32 v51, v51, v12
	s_nop 0
	v_addc_co_u32_e32 v1, vcc, 0, v3, vcc
	v_mul_f32_e32 v56, v56, v13
	v_mul_f32_e32 v67, v67, v12
	v_mul_f32_e32 v72, v72, v13
	global_load_dwordx2 v[12:13], v[0:1], off offset:2048
	v_add_co_u32_e32 v0, vcc, s91, v2
	s_mov_b32 s33, 0x27000
	s_nop 0
	v_addc_co_u32_e32 v1, vcc, 0, v3, vcc
	v_mul_f32_e32 v48, v48, v9
	v_mul_f32_e32 v64, v64, v9
	global_load_dwordx2 v[8:9], v[0:1], off offset:2048
	v_add_co_u32_e32 v0, vcc, s33, v2
	v_mul_f32_e32 v38, v38, v6
	s_nop 0
	v_addc_co_u32_e32 v1, vcc, 0, v3, vcc
	v_mul_f32_e32 v39, v39, v7
	v_mul_f32_e32 v54, v54, v6
	v_mul_f32_e32 v55, v55, v7
	v_mul_f32_e32 v70, v70, v6
	v_mul_f32_e32 v71, v71, v7
	global_load_dwordx2 v[6:7], v[0:1], off offset:2048
	v_add_co_u32_e32 v0, vcc, s94, v2
	s_mov_b32 s2, 0x2d000
	s_nop 0
	v_addc_co_u32_e32 v1, vcc, 0, v3, vcc
	global_load_dwordx2 v[4:5], v[0:1], off offset:2048
	v_add_co_u32_e32 v0, vcc, s2, v2
	s_add_i32 s2, s73, 0
	s_nop 0
	v_addc_co_u32_e32 v1, vcc, 0, v3, vcc
	global_load_dwordx2 v[2:3], v[0:1], off offset:2048
	v_lshlrev_b32_e32 v0, 2, v181
	v_mul_u32_u24_e32 v1, 0x840, v176
	v_add3_u32 v0, s2, v0, v1
	v_mul_f32_e32 v43, v43, v80
	v_mul_f32_e32 v59, v59, v80
	v_mul_f32_e32 v75, v75, v80
	v_add_u32_e32 v1, 0x400, v0
	v_add_u32_e32 v35, 0x1000, v0
	v_add_u32_e32 v80, 0x1400, v0
	s_waitcnt vmcnt(0)
	s_barrier
; #define LAS __attribute__((address_space(3)))
; __device__ __forceinline__ float bf2f(unsigned h) { return __uint_as_float(h << 16); }
; __device__ __forceinline__ unsigned cvt_pk_bf16(float lo, float hi) { unsigned r; asm volatile("v_cvt_pk_bf16_f32 %0, %1, %2" : "=v"(r) : "v"(lo), "v"(hi)); return r; }
; __device__ __forceinline__ int crow(int r, int hi) { return (r & 3) + 8 * (r >> 2) + 4 * hi; }
; template <bool SUBLN>
; __device__ __forceinline__ void attn_out(const AttnBufs& T, f32x16 (&o)[4], int type, int h, size_t orow0, LAS char* lds, int wid, int lane, int r32, int hi) {
;     ...
;     LAS float* stg = (LAS float*)(lds + wid * 16896);
; #pragma unroll
;     for (int d0 = 0; d0 < 4; ++d0)
; #pragma unroll
;         for (int r = 0; r < 16; ++r) stg[att::crow(r, hi) * 132 + d0 * 32 + r32] = o[d0][r];
;     asm volatile("s_waitcnt lgkmcnt(0)" ::: "memory");
;     f32x4 wsub = {1.f, 1.f, 1.f, 1.f};
;     if (SUBLN) { wsub = *(const f32x4*)(T.subln + c4) * (1.f - T.lam_init); }
; #pragma unroll
;     for (int i = 0; i < 16; ++i) {
;         f32x4 v = *(const LAS f32x4*)(stg + (2 * i + rr) * 132 + c4);
;         if (SUBLN) {
;             float s = (v[0] * v[0] + v[1] * v[1]) + (v[2] * v[2] + v[3] * v[3]);
;             s += __shfl_xor(s, 1); s += __shfl_xor(s, 2); s += __shfl_xor(s, 4); s += __shfl_xor(s, 8); s += __shfl_xor(s, 16);
;             v = v * (rsqrtf(s * (1.f / 128.f) + EPS)) * wsub;
;         }
;         u32x2 w; w.x = cvt_pk_bf16(v[0] * bf2f(gg[i].x & 0xffffu), v[1] * bf2f(gg[i].x >> 16)); w.y = cvt_pk_bf16(v[2] * bf2f(gg[i].y & 0xffffu), v[3] * bf2f(gg[i].y >> 16));
;         *(u32x2*)(op + (size_t)i * 2 * 3072) = w;
;     }
	ds_write2_b32 v0, v81, v97 offset1:32
	ds_write2_b32 v0, v82, v98 offset0:132 offset1:164
	ds_write2_b32 v1, v83, v99 offset0:8 offset1:40
	ds_write2_b32 v1, v84, v100 offset0:140 offset1:172
	ds_write2_b32 v35, v85, v101 offset0:32 offset1:64
	ds_write2_b32 v35, v86, v102 offset0:164 offset1:196
	ds_write2_b32 v80, v87, v38 offset0:40 offset1:72
	ds_write2_b32 v80, v88, v39 offset0:172 offset1:204
	v_add_u32_e32 v38, 0x2000, v0
	v_add_u32_e32 v39, 0x2400, v0
	ds_write2_b32 v38, v89, v103 offset0:64 offset1:96
	ds_write2_b32 v38, v90, v104 offset0:196 offset1:228
	ds_write2_b32 v39, v91, v42 offset0:72 offset1:104
	ds_write2_b32 v39, v92, v43 offset0:204 offset1:236
	v_add_u32_e32 v42, 0x3000, v0
	v_add_u32_e32 v43, 0x3200, v0
	ds_write2_b32 v42, v93, v44 offset0:96 offset1:128
	ds_write2_b32 v43, v94, v45 offset0:100 offset1:132
	v_add_u32_e32 v43, 0x3400, v0
	v_add_u32_e32 v44, 0x3600, v0
	ds_write2_b32 v43, v95, v46 offset0:104 offset1:136
	ds_write2_b32 v44, v96, v47 offset0:108 offset1:140
	ds_write2_b32 v0, v48, v64 offset0:64 offset1:96
	ds_write2_b32 v0, v49, v65 offset0:196 offset1:228
	ds_write2_b32 v1, v50, v66 offset0:72 offset1:104
	ds_write2_b32 v1, v51, v67 offset0:204 offset1:236
	ds_write2_b32 v35, v52, v68 offset0:96 offset1:128
	v_add_u32_e32 v1, 0x1200, v0
	ds_write2_b32 v1, v53, v69 offset0:100 offset1:132
	ds_write2_b32 v80, v54, v70 offset0:104 offset1:136
	v_add_u32_e32 v1, 0x1600, v0
	ds_write2_b32 v1, v55, v71 offset0:108 offset1:140
	ds_write2_b32 v38, v56, v72 offset0:128 offset1:160
	ds_write2_b32 v39, v57, v73 offset0:4 offset1:36
	ds_write2_b32 v39, v58, v74 offset0:136 offset1:168
	v_add_u32_e32 v1, 0x2800, v0
	v_add_u32_e32 v0, 0x3800, v0
	ds_write2_b32 v1, v59, v75 offset0:12 offset1:44
	ds_write2_b32 v42, v60, v76 offset0:160 offset1:192
	ds_write2_b32 v43, v61, v77 offset0:36 offset1:68
	ds_write2_b32 v43, v62, v78 offset0:168 offset1:200
	ds_write2_b32 v0, v63, v79 offset0:44 offset1:76
	v_lshlrev_b32_e32 v34, 2, v34
	v_mul_u32_u24_e32 v35, 0x210, v176
	s_waitcnt lgkmcnt(0)
	v_add3_u32 v34, s2, v34, v35
	v_lshl_add_u64 v[10:11], v[36:37], 0, v[10:11]
	ds_read_b128 v[36:39], v34
	v_lshlrev_b32_e32 v35, 16, v40
	v_lshl_add_u64 v[0:1], v[10:11], 0, s[28:29]
	s_mov_b64 s[50:51], 0
	s_waitcnt lgkmcnt(0)
	v_mul_f32_e32 v35, v36, v35
	v_and_b32_e32 v36, 0xffff0000, v40
	v_mul_f32_e32 v36, v37, v36
	v_and_b32_e32 v37, 0xffff0000, v41
	v_cvt_pk_bf16_f32 v36, v35, v36
	v_lshlrev_b32_e32 v35, 16, v41
	v_mul_f32_e32 v37, v39, v37
	v_mul_f32_e32 v35, v38, v35
	v_cvt_pk_bf16_f32 v37, v35, v37
	global_store_dwordx2 v[10:11], v[36:37], off offset:2048
	ds_read_b128 v[36:39], v34 offset:1056
	v_lshlrev_b32_e32 v35, 16, v32
	v_and_b32_e32 v32, 0xffff0000, v32
	s_waitcnt lgkmcnt(0)
	v_mul_f32_e32 v35, v36, v35
	v_mul_f32_e32 v32, v37, v32
	v_cvt_pk_bf16_f32 v32, v35, v32
	v_lshlrev_b32_e32 v35, 16, v33
	v_and_b32_e32 v33, 0xffff0000, v33
	v_add_co_u32_e32 v36, vcc, s40, v10
	v_mul_f32_e32 v33, v39, v33
	s_nop 0
	v_addc_co_u32_e32 v37, vcc, 0, v11, vcc
	v_mul_f32_e32 v35, v38, v35
	v_cvt_pk_bf16_f32 v33, v35, v33
	global_store_dwordx2 v[36:37], v[32:33], off offset:2048
	ds_read_b128 v[36:39], v34 offset:2112
	v_lshlrev_b32_e32 v32, 16, v30
	v_and_b32_e32 v30, 0xffff0000, v30
	v_lshlrev_b32_e32 v35, 16, v28
	v_and_b32_e32 v28, 0xffff0000, v28
	s_waitcnt lgkmcnt(0)
	v_mul_f32_e32 v32, v36, v32
	v_mul_f32_e32 v30, v37, v30
	v_cvt_pk_bf16_f32 v30, v32, v30
	v_lshlrev_b32_e32 v32, 16, v31
	v_and_b32_e32 v31, 0xffff0000, v31
	v_mul_f32_e32 v32, v38, v32
	v_mul_f32_e32 v31, v39, v31
	v_cvt_pk_bf16_f32 v31, v32, v31
	v_add_co_u32_e32 v32, vcc, s82, v10
	s_nop 1
	v_addc_co_u32_e32 v33, vcc, 0, v11, vcc
	global_store_dwordx2 v[32:33], v[30:31], off offset:2048
	ds_read_b128 v[30:33], v34 offset:3168
	s_waitcnt lgkmcnt(0)
	v_mul_f32_e32 v30, v30, v35
	v_mul_f32_e32 v28, v31, v28
	v_cvt_pk_bf16_f32 v28, v30, v28
	v_lshlrev_b32_e32 v30, 16, v29
	v_and_b32_e32 v29, 0xffff0000, v29
	v_mul_f32_e32 v30, v32, v30
	v_mul_f32_e32 v29, v33, v29
	v_cvt_pk_bf16_f32 v29, v30, v29
	v_add_co_u32_e32 v30, vcc, s4, v10
	v_lshlrev_b32_e32 v32, 16, v26
	s_nop 0
	v_addc_co_u32_e32 v31, vcc, 0, v11, vcc
	global_store_dwordx2 v[30:31], v[28:29], off offset:2048
	ds_read_b128 v[28:31], v34 offset:4224
	v_and_b32_e32 v26, 0xffff0000, v26
	s_waitcnt lgkmcnt(0)
	v_mul_f32_e32 v28, v28, v32
	v_mul_f32_e32 v26, v29, v26
	v_cvt_pk_bf16_f32 v26, v28, v26
	v_lshlrev_b32_e32 v28, 16, v27
	v_and_b32_e32 v27, 0xffff0000, v27
	v_mul_f32_e32 v28, v30, v28
	v_mul_f32_e32 v27, v31, v27
	v_cvt_pk_bf16_f32 v27, v28, v27
	v_add_co_u32_e32 v28, vcc, s77, v10
	v_lshlrev_b32_e32 v30, 16, v24
	s_nop 0
	v_addc_co_u32_e32 v29, vcc, 0, v11, vcc
	global_store_dwordx2 v[28:29], v[26:27], off offset:2048
	ds_read_b128 v[26:29], v34 offset:5280
	v_and_b32_e32 v24, 0xffff0000, v24
	s_waitcnt lgkmcnt(0)
	v_mul_f32_e32 v26, v26, v30
	v_mul_f32_e32 v24, v27, v24
	v_cvt_pk_bf16_f32 v24, v26, v24
	v_lshlrev_b32_e32 v26, 16, v25
	v_and_b32_e32 v25, 0xffff0000, v25
	v_mul_f32_e32 v26, v28, v26
	v_mul_f32_e32 v25, v29, v25
	v_cvt_pk_bf16_f32 v25, v26, v25
	v_add_co_u32_e32 v26, vcc, s5, v10
	v_lshlrev_b32_e32 v28, 16, v22
	s_nop 0
	v_addc_co_u32_e32 v27, vcc, 0, v11, vcc
	global_store_dwordx2 v[26:27], v[24:25], off offset:2048
	ds_read_b128 v[24:27], v34 offset:6336
	v_and_b32_e32 v22, 0xffff0000, v22
	s_waitcnt lgkmcnt(0)
; #define LAS __attribute__((address_space(3)))
; __device__ __forceinline__ float bf2f(unsigned h) { return __uint_as_float(h << 16); }
; __device__ __forceinline__ unsigned cvt_pk_bf16(float lo, float hi) { unsigned r; asm volatile("v_cvt_pk_bf16_f32 %0, %1, %2" : "=v"(r) : "v"(lo), "v"(hi)); return r; }
; template <bool SUBLN>
; __device__ __forceinline__ void attn_out(const AttnBufs& T, f32x16 (&o)[4], int type, int h, size_t orow0, LAS char* lds, int wid, int lane, int r32, int hi) {
;     ...
;     for (int i = 0; i < 16; ++i) {
;         f32x4 v = *(const LAS f32x4*)(stg + (2 * i + rr) * 132 + c4);
;         if (SUBLN) {
;             float s = (v[0] * v[0] + v[1] * v[1]) + (v[2] * v[2] + v[3] * v[3]);
;             s += __shfl_xor(s, 1); s += __shfl_xor(s, 2); s += __shfl_xor(s, 4); s += __shfl_xor(s, 8); s += __shfl_xor(s, 16);
;             v = v * (rsqrtf(s * (1.f / 128.f) + EPS)) * wsub;
;         }
;         u32x2 w; w.x = cvt_pk_bf16(v[0] * bf2f(gg[i].x & 0xffffu), v[1] * bf2f(gg[i].x >> 16)); w.y = cvt_pk_bf16(v[2] * bf2f(gg[i].y & 0xffffu), v[3] * bf2f(gg[i].y >> 16));
;         *(u32x2*)(op + (size_t)i * 2 * 3072) = w;
;     }
	v_mul_f32_e32 v24, v24, v28
	v_mul_f32_e32 v22, v25, v22
	v_cvt_pk_bf16_f32 v22, v24, v22
	v_lshlrev_b32_e32 v24, 16, v23
	v_and_b32_e32 v23, 0xffff0000, v23
	v_mul_f32_e32 v24, v26, v24
	v_mul_f32_e32 v23, v27, v23
	v_cvt_pk_bf16_f32 v23, v24, v23
	v_add_co_u32_e32 v24, vcc, s85, v10
	v_lshlrev_b32_e32 v26, 16, v20
	s_nop 0
	v_addc_co_u32_e32 v25, vcc, 0, v11, vcc
	global_store_dwordx2 v[24:25], v[22:23], off offset:2048
	ds_read_b128 v[22:25], v34 offset:7392
	v_and_b32_e32 v20, 0xffff0000, v20
	s_waitcnt lgkmcnt(0)
	v_mul_f32_e32 v22, v22, v26
	v_mul_f32_e32 v20, v23, v20
	v_cvt_pk_bf16_f32 v20, v22, v20
	v_lshlrev_b32_e32 v22, 16, v21
	v_and_b32_e32 v21, 0xffff0000, v21
	v_mul_f32_e32 v22, v24, v22
	v_mul_f32_e32 v21, v25, v21
	v_cvt_pk_bf16_f32 v21, v22, v21
	v_add_co_u32_e32 v22, vcc, s20, v10
	v_lshlrev_b32_e32 v24, 16, v18
	s_nop 0
	v_addc_co_u32_e32 v23, vcc, 0, v11, vcc
	global_store_dwordx2 v[22:23], v[20:21], off offset:2048
	ds_read_b128 v[20:23], v34 offset:8448
	v_and_b32_e32 v18, 0xffff0000, v18
	s_waitcnt lgkmcnt(0)
	v_mul_f32_e32 v20, v20, v24
	v_mul_f32_e32 v18, v21, v18
	v_cvt_pk_bf16_f32 v18, v20, v18
	v_lshlrev_b32_e32 v20, 16, v19
	v_and_b32_e32 v19, 0xffff0000, v19
	v_mul_f32_e32 v20, v22, v20
	v_mul_f32_e32 v19, v23, v19
	v_cvt_pk_bf16_f32 v19, v20, v19
	v_add_co_u32_e32 v20, vcc, s76, v10
	v_lshlrev_b32_e32 v22, 16, v16
	s_nop 0
	v_addc_co_u32_e32 v21, vcc, 0, v11, vcc
	global_store_dwordx2 v[20:21], v[18:19], off offset:2048
	ds_read_b128 v[18:21], v34 offset:9504
	v_and_b32_e32 v16, 0xffff0000, v16
	s_waitcnt lgkmcnt(0)
	v_mul_f32_e32 v18, v18, v22
	v_mul_f32_e32 v16, v19, v16
	v_cvt_pk_bf16_f32 v16, v18, v16
	v_lshlrev_b32_e32 v18, 16, v17
	v_and_b32_e32 v17, 0xffff0000, v17
	v_mul_f32_e32 v18, v20, v18
	v_mul_f32_e32 v17, v21, v17
	v_cvt_pk_bf16_f32 v17, v18, v17
	v_add_co_u32_e32 v18, vcc, s21, v10
	v_lshlrev_b32_e32 v20, 16, v14
	s_nop 0
	v_addc_co_u32_e32 v19, vcc, 0, v11, vcc
	global_store_dwordx2 v[18:19], v[16:17], off offset:2048
	ds_read_b128 v[16:19], v34 offset:10560
	v_and_b32_e32 v14, 0xffff0000, v14
	s_waitcnt lgkmcnt(0)
	v_mul_f32_e32 v16, v16, v20
	v_mul_f32_e32 v14, v17, v14
	v_cvt_pk_bf16_f32 v14, v16, v14
	v_lshlrev_b32_e32 v16, 16, v15
	v_and_b32_e32 v15, 0xffff0000, v15
	v_mul_f32_e32 v16, v18, v16
	v_mul_f32_e32 v15, v19, v15
	v_cvt_pk_bf16_f32 v15, v16, v15
	v_add_co_u32_e32 v16, vcc, s92, v10
	v_lshlrev_b32_e32 v18, 16, v12
	s_nop 0
	v_addc_co_u32_e32 v17, vcc, 0, v11, vcc
	global_store_dwordx2 v[16:17], v[14:15], off offset:2048
	ds_read_b128 v[14:17], v34 offset:11616
	v_and_b32_e32 v12, 0xffff0000, v12
	s_waitcnt lgkmcnt(0)
	v_mul_f32_e32 v14, v14, v18
	v_mul_f32_e32 v12, v15, v12
	v_cvt_pk_bf16_f32 v12, v14, v12
	v_lshlrev_b32_e32 v14, 16, v13
	v_and_b32_e32 v13, 0xffff0000, v13
	v_mul_f32_e32 v14, v16, v14
	v_mul_f32_e32 v13, v17, v13
	v_cvt_pk_bf16_f32 v13, v14, v13
	v_add_co_u32_e32 v14, vcc, s3, v10
	v_lshlrev_b32_e32 v16, 16, v8
	s_nop 0
	v_addc_co_u32_e32 v15, vcc, 0, v11, vcc
	global_store_dwordx2 v[14:15], v[12:13], off offset:2048
	ds_read_b128 v[12:15], v34 offset:12672
	v_and_b32_e32 v8, 0xffff0000, v8
	s_waitcnt lgkmcnt(0)
	v_mul_f32_e32 v12, v12, v16
	v_mul_f32_e32 v8, v13, v8
	v_cvt_pk_bf16_f32 v8, v12, v8
	v_lshlrev_b32_e32 v12, 16, v9
	v_and_b32_e32 v9, 0xffff0000, v9
	v_mul_f32_e32 v12, v14, v12
	v_mul_f32_e32 v9, v15, v9
	v_cvt_pk_bf16_f32 v9, v12, v9
	v_add_co_u32_e32 v12, vcc, s91, v10
	s_nop 1
	v_addc_co_u32_e32 v13, vcc, 0, v11, vcc
	global_store_dwordx2 v[12:13], v[8:9], off offset:2048
	ds_read_b128 v[12:15], v34 offset:13728
	v_lshlrev_b32_e32 v8, 16, v6
	v_and_b32_e32 v6, 0xffff0000, v6
	s_waitcnt lgkmcnt(0)
	v_mul_f32_e32 v8, v12, v8
	v_mul_f32_e32 v6, v13, v6
	v_cvt_pk_bf16_f32 v6, v8, v6
	v_lshlrev_b32_e32 v8, 16, v7
	v_and_b32_e32 v7, 0xffff0000, v7
	v_mul_f32_e32 v8, v14, v8
	v_mul_f32_e32 v7, v15, v7
	v_cvt_pk_bf16_f32 v7, v8, v7
	v_add_co_u32_e32 v8, vcc, s33, v10
	v_lshlrev_b32_e32 v12, 16, v4
	s_nop 0
	v_addc_co_u32_e32 v9, vcc, 0, v11, vcc
	global_store_dwordx2 v[8:9], v[6:7], off offset:2048
	ds_read_b128 v[6:9], v34 offset:14784
	v_and_b32_e32 v4, 0xffff0000, v4
	s_waitcnt lgkmcnt(0)
	v_mul_f32_e32 v6, v6, v12
	v_mul_f32_e32 v4, v7, v4
	v_cvt_pk_bf16_f32 v4, v6, v4
	v_lshlrev_b32_e32 v6, 16, v5
	v_and_b32_e32 v5, 0xffff0000, v5
	v_mul_f32_e32 v6, v8, v6
	v_mul_f32_e32 v5, v9, v5
	v_cvt_pk_bf16_f32 v5, v6, v5
	v_add_co_u32_e32 v6, vcc, s94, v10
	v_lshlrev_b32_e32 v8, 16, v2
	s_nop 0
	v_addc_co_u32_e32 v7, vcc, 0, v11, vcc
	global_store_dwordx2 v[6:7], v[4:5], off offset:2048
	ds_read_b128 v[4:7], v34 offset:15840
	v_and_b32_e32 v2, 0xffff0000, v2
	s_waitcnt lgkmcnt(0)
	v_mul_f32_e32 v4, v4, v8
	v_mul_f32_e32 v2, v5, v2
	v_cvt_pk_bf16_f32 v2, v4, v2
	v_lshlrev_b32_e32 v4, 16, v3
	v_and_b32_e32 v3, 0xffff0000, v3
	v_mul_f32_e32 v3, v7, v3
	v_mul_f32_e32 v4, v6, v4
	v_cvt_pk_bf16_f32 v3, v4, v3

; __device__ __forceinline__ int v_rd_base(int lane) { return ((lane & 3) << 3) | (((lane >> 2) & 3) << 6) | (((lane >> 4) & 1) << 5) | (((lane >> 5) & 1) << 8); }
; #define VMW0() asm volatile("s_waitcnt vmcnt(0)" ::: "memory")
; template <int DQK, bool DOUBLE> ...
;     ...
;     { const bf16_t* Qw = Q + (size_t)(wid * 32 + r32) * ldq + hi * 8;
; #pragma unroll
;       for (int d0 = 0; d0 < DQK / 16; ++d0) qr[d0] = *(const bf16x8*)(Qw + d0 * 16); }
; #pragma unroll
;     for (int d = 0; d < 4; ++d) o[d] = f32x16{};
;     l_reg = 0.f;
;     int vrow[2], vcol[2], krow[NLD], kcol[NLD];
; #pragma unroll
;     for (int i = 0; i < 2; ++i) { const int q = tid + 512 * i, sub = q >> 5, within = q & 31, kk = (sub >> 2) * 8 + (within >> 2);
;         vrow[i] = kk; vcol[i] = (sub & 3) * 32 + (within & 3) * 8; }
; #pragma unroll
;     for (int i = 0; i < NLD; ++i) { const int q = tid + 512 * i, row = q / NCH, chp = q % NCH; const int x = (RB == 256) ? (row & 15) : ((row >> 1) & 7);
;         krow[i] = row; kcol[i] = (chp ^ x) * 8; }
;     const unsigned vb0 = (unsigned)(uintptr_t)V_lds + v_rd_base(lane);
;     int ka[8];
; #pragma unroll
;     for (int q = 0; q < 8; ++q) ka[q] = kswz<RB>(r32, q * 32 + hi * 16);
;     ...
;     bf16x8 pa0, pa1, pa2, pa3;
;     __syncthreads();
;     DMA(0, 0); DMA(1, 1); VMW0(); __syncthreads();
; __device__ __forceinline__ void attn_item(const AttnBufs& T, int type, int b, int h, int qrow0, int NT, LAS char* lds, int tid_) {
;     ...
;     } else if (MK_ATYPE & 4) {
;         f32x16 o[4]; float l_reg; float rli[16];
;         att::attn_pass<64, ATT_DBL>(T.QC + (size_t)qrow0 * 1024 + h * 128, 1024, T.KC + h * 128, 1024, T.VC + h * 128, 1024, rowc, rowl, NT,
;                            T.lamv[3], o, l_reg, lds, tid);
.LBB0_153:
	v_lshlrev_b32_e32 v144, 4, v176
	v_and_b32_e32 v4, 0x60, v164
	v_lshlrev_b32_e32 v5, 3, v164
	v_add_u32_e32 v194, 0x200, v164
	v_lshlrev_b32_e32 v6, 4, v182
	s_andn2_b64 vcc, exec, s[50:51]
	v_ashrrev_i32_e32 v195, 4, v164
	v_ashrrev_i32_e32 v165, 31, v164
	v_lshlrev_b32_e32 v174, 3, v182
	v_lshrrev_b32_e32 v196, 2, v164
	v_and_or_b32 v193, v5, 24, v4
	v_ashrrev_i32_e32 v197, 4, v194
	v_or_b32_e32 v187, 32, v144
	v_or_b32_e32 v191, 64, v144
	v_or_b32_e32 v192, 0x60, v144
	v_lshlrev_b32_e32 v175, 1, v182
	v_and_b32_e32 v173, 0xc0, v6
	s_cbranch_vccnz .LBB0_171
	s_lshl_b64 s[2:3], s[30:31], 11
	v_readlane_b32 s4, v251, 40
	v_readlane_b32 s5, v251, 41
	s_add_u32 s4, s4, s2
	s_addc_u32 s5, s5, s3
	s_lshl_b32 s48, s72, 7
	s_ashr_i32 s49, s48, 31
	s_lshl_b64 s[2:3], s[48:49], 1
	s_add_u32 s50, s4, s2
	s_addc_u32 s51, s5, s3
	v_readlane_b32 s4, v251, 42
	v_readlane_b32 s5, v251, 43
	s_add_u32 s60, s4, s2
	s_addc_u32 s61, s5, s3
	v_readlane_b32 s4, v251, 44
	v_readlane_b32 s5, v251, 45
	s_add_u32 s56, s4, s2
	v_readfirstlane_b32 s2, v164
	s_addc_u32 s57, s5, s3
	s_ashr_i32 s2, s2, 6
	v_lshl_or_b32 v2, s2, 5, v181
	v_ashrrev_i32_e32 v3, 31, v2
	v_lshlrev_b64 v[2:3], 11, v[2:3]
	v_lshrrev_b32_e32 v1, 29, v165
	v_lshl_add_u64 v[2:3], s[50:51], 0, v[2:3]
	v_mov_b32_e32 v145, v177
	v_add_u32_e32 v1, v164, v1
	v_lshl_add_u64 v[2:3], v[2:3], 0, v[144:145]
	v_ashrrev_i32_e32 v132, 3, v1
	v_and_b32_e32 v1, 0x1ffffff8, v1
	global_load_dword v0, v177, s[14:15] offset:12
	global_load_dwordx4 v[112:115], v[2:3], off
	global_load_dwordx4 v[116:119], v[2:3], off offset:32
	global_load_dwordx4 v[120:123], v[2:3], off offset:64
	global_load_dwordx4 v[124:127], v[2:3], off offset:96
	v_sub_u32_e32 v1, v164, v1
	v_lshrrev_b32_e32 v2, 1, v132
	v_bitop3_b32 v1, v2, v1, 7 bitop3:0x6c
	v_bfi_b32 v128, -8, v195, v196
	v_lshlrev_b32_e32 v2, 3, v1
	s_add_i32 s42, s45, 0x4040
	v_ashrrev_i32_e32 v129, 31, v128
	v_ashrrev_i32_e32 v3, 31, v2
	s_ashr_i32 s43, s42, 31
	v_lshlrev_b64 v[16:17], 1, v[2:3]
	v_lshl_add_u64 v[2:3], v[128:129], 0, s[42:43]
	v_bfi_b32 v130, -8, v197, v196
	v_lshlrev_b64 v[2:3], 11, v[2:3]
	s_ashr_i32 s47, s46, 31
	v_lshlrev_b32_e32 v80, 1, v193
	v_mov_b32_e32 v81, v177
	s_waitcnt lgkmcnt(0)
	v_ashrrev_i32_e32 v131, 31, v130
	v_lshl_add_u64 v[2:3], s[56:57], 0, v[2:3]
	v_lshl_add_u64 v[4:5], v[128:129], 0, s[46:47]
	v_lshl_add_u64 v[148:149], v[2:3], 0, v[80:81]
	v_lshl_add_u64 v[2:3], v[130:131], 0, s[42:43]
	v_lshlrev_b64 v[4:5], 11, v[4:5]
	v_lshlrev_b64 v[2:3], 11, v[2:3]
	v_lshl_add_u64 v[4:5], s[56:57], 0, v[4:5]
	v_ashrrev_i32_e32 v133, 31, v132
	v_lshl_add_u64 v[2:3], s[56:57], 0, v[2:3]
	v_lshl_add_u64 v[140:141], v[4:5], 0, v[80:81]
	v_lshl_add_u64 v[4:5], v[130:131], 0, s[46:47]
	v_lshl_add_u64 v[150:151], v[2:3], 0, v[80:81]
	v_lshl_add_u64 v[2:3], v[132:133], 0, s[42:43]
	v_lshlrev_b64 v[4:5], 11, v[4:5]
	v_lshlrev_b64 v[2:3], 11, v[2:3]
	s_add_i32 s42, s45, 0x4080
	s_lshl_b32 s3, s2, 10
	v_lshl_add_u64 v[4:5], s[56:57], 0, v[4:5]
	v_lshl_add_u64 v[2:3], s[60:61], 0, v[2:3]
	s_ashr_i32 s43, s42, 31
	s_add_i32 s4, s3, 0
	v_lshl_add_u64 v[142:143], v[4:5], 0, v[80:81]
	v_lshl_add_u64 v[4:5], v[132:133], 0, s[46:47]
	v_lshl_add_u64 v[152:153], v[2:3], 0, v[16:17]
	v_lshl_add_u64 v[2:3], v[128:129], 0, s[42:43]
	s_mov_b32 m0, s4
	s_add_i32 s2, s4, 0x2000
	v_lshlrev_b64 v[4:5], 11, v[4:5]
	v_lshlrev_b64 v[2:3], 11, v[2:3]
	s_barrier
	global_load_lds_dwordx4 v[140:141], off
	s_mov_b32 m0, s2
	v_lshl_add_u64 v[4:5], s[60:61], 0, v[4:5]
	s_add_i32 s21, s4, 0xc000
	v_lshl_add_u64 v[2:3], s[56:57], 0, v[2:3]
	global_load_lds_dwordx4 v[142:143], off
	v_lshl_add_u64 v[146:147], v[4:5], 0, v[16:17]
	s_mov_b32 m0, s21
	v_lshl_add_u64 v[154:155], v[2:3], 0, v[80:81]
	v_lshl_add_u64 v[2:3], v[130:131], 0, s[42:43]
	global_load_lds_dwordx4 v[146:147], off
	s_add_i32 m0, s4, 0x4000
	v_lshlrev_b64 v[2:3], 11, v[2:3]
	global_load_lds_dwordx4 v[148:149], off
	s_add_i32 m0, s4, 0x6000
	v_lshl_add_u64 v[2:3], s[56:57], 0, v[2:3]
	global_load_lds_dwordx4 v[150:151], off
	s_add_i32 m0, s4, 0x12000
	v_lshl_add_u64 v[156:157], v[2:3], 0, v[80:81]
	v_lshl_add_u64 v[2:3], v[132:133], 0, s[42:43]
	global_load_lds_dwordx4 v[152:153], off
	s_add_i32 m0, s4, 0x8000
	v_lshlrev_b64 v[2:3], 11, v[2:3]
	s_waitcnt vmcnt(0)
	s_waitcnt vmcnt(0) lgkmcnt(0)
	s_barrier
; #define LAS __attribute__((address_space(3)))
; #define SBAR() __builtin_amdgcn_sched_barrier(0)
; template <int D0> __device__ __forceinline__ void pv_one(f32x16& od, unsigned vb, bf16x8 pa0, bf16x8 pa1, bf16x8 pa2, bf16x8 pa3) {
;     const s16x4 l0 = tr_read<v_rd_off(D0, 0, 0)>(vb), h0 = tr_read<v_rd_off(D0, 0, 1)>(vb), l1 = tr_read<v_rd_off(D0, 1, 0)>(vb), h1 = tr_read<v_rd_off(D0, 1, 1)>(vb);
;     const s16x4 l2 = tr_read<v_rd_off(D0, 2, 0)>(vb), h2 = tr_read<v_rd_off(D0, 2, 1)>(vb), l3 = tr_read<v_rd_off(D0, 3, 0)>(vb), h3 = tr_read<v_rd_off(D0, 3, 1)>(vb);
;     asm volatile("s_waitcnt lgkmcnt(0)" ::: "memory"); SBAR();
;     ...
;     od = __builtin_amdgcn_mfma_f32_32x32x16_bf16(pa0, PK(l0, h0), od, 0, 0, 0);
;     od = __builtin_amdgcn_mfma_f32_32x32x16_bf16(pa1, PK(l1, h1), od, 0, 0, 0);
;     od = __builtin_amdgcn_mfma_f32_32x32x16_bf16(pa2, PK(l2, h2), od, 0, 0, 0);
;     od = __builtin_amdgcn_mfma_f32_32x32x16_bf16(pa3, PK(l3, h3), od, 0, 0, 0);
; __device__ __forceinline__ void partialSM(f32x16& p0, f32x16& p1) {
; #pragma unroll
;     for (int r = 0; r < 16; ++r) p0[r] = __builtin_amdgcn_exp2f(p0[r]);
; }
; __device__ __forceinline__ void finishSM(f32x16& p0, f32x16& p1, float& l_reg, bf16x8& pa0, bf16x8& pa1, bf16x8& pa2, bf16x8& pa3) {
; #pragma unroll
;     for (int r = 0; r < 16; ++r) p1[r] = __builtin_amdgcn_exp2f(p1[r]);
;     float ps = 0;
; #pragma unroll
;     for (int r = 0; r < 16; ++r) ps += p0[r];
; #pragma unroll
;     for (int r = 0; r < 16; ++r) ps += p1[r];
;     l_reg += ps;
;     ...
;     PK8(p0, 0, pa0); PK8(p0, 8, pa1); PK8(p1, 0, pa2); PK8(p1, 8, pa3);
; template <int DQK>
; __device__ __forceinline__ void qkt(f32x16& p0, f32x16& p1, const LAS char* Ks, const bf16x8 (&qr)[DQK / 16], const int (&ka)[8], float nMB) {
;     constexpr int RB = DQK * 2, NA = (RB == 256) ? 8 : 4;
; #pragma unroll
;     for (int r = 0; r < 16; ++r) { p0[r] = nMB; p1[r] = nMB; }
; #pragma unroll
;     for (int d0 = 0; d0 < DQK / 16; ++d0) {
;         const LAS char* a = Ks + ka[d0 % NA] + (d0 / NA) * (NA * 32);
;         const bf16x8 b0 = *(const LAS bf16x8*)(a);
;         const bf16x8 b1 = *(const LAS bf16x8*)(a + 32 * RB);
;         p0 = __builtin_amdgcn_mfma_f32_32x32x16_bf16(b0, qr[d0], p0, 0, 0, 0);
;         p1 = __builtin_amdgcn_mfma_f32_32x32x16_bf16(b1, qr[d0], p1, 0, 0, 0); }
; }
	global_load_lds_dwordx4 v[154:155], off
	s_add_i32 m0, s4, 0xa000
	v_lshl_add_u64 v[2:3], s[60:61], 0, v[2:3]
	global_load_lds_dwordx4 v[156:157], off
	v_lshl_add_u64 v[158:159], v[2:3], 0, v[16:17]
	s_add_i32 m0, s4, 0x18000
	v_lshlrev_b32_e32 v2, 3, v181
	global_load_lds_dwordx4 v[158:159], off
	v_lshlrev_b32_e32 v1, 7, v181
	v_and_b32_e32 v2, 0x70, v2
	v_bitop3_b32 v145, v144, v1, v2 bitop3:0xde
	v_bitop3_b32 v161, v187, v1, v2 bitop3:0xde
	v_bitop3_b32 v198, v191, v1, v2 bitop3:0xde
	v_bitop3_b32 v199, v192, v1, v2 bitop3:0xde
	v_and_b32_e32 v1, 32, v175
	s_movk_i32 s33, 0x118
	v_and_or_b32 v18, v174, s33, v1
	s_mov_b32 s5, 1
	v_lshlrev_b32_e32 v172, 3, v176
	s_mov_b32 s20, 2
	v_mov_b32_e32 v1, v0
	v_mov_b32_e32 v2, v0
	v_mov_b32_e32 v3, v0
	v_mov_b32_e32 v4, v0
	v_mov_b32_e32 v5, v0
	v_mov_b32_e32 v6, v0
	v_mov_b32_e32 v7, v0
	v_mov_b32_e32 v8, v0
	v_mov_b32_e32 v9, v0
	v_mov_b32_e32 v10, v0
	v_mov_b32_e32 v11, v0
	v_mov_b32_e32 v12, v0
	v_mov_b32_e32 v13, v0
	v_mov_b32_e32 v14, v0
	v_mov_b32_e32 v15, v0
	v_add3_u32 v200, v173, 0, v18
	v_lshl_add_u64 v[134:135], s[60:61], 0, v[16:17]
	s_add_i32 s58, s45, 0x40c0
	v_add_u32_e32 v202, 0, v145
	ds_read_b128 v[16:19], v202 offset:49152
	ds_read_b128 v[48:51], v202 offset:53248
	v_add_u32_e32 v203, 0, v161
	v_add_u32_e32 v204, 0, v198
	v_add_u32_e32 v205, 0, v199
	s_waitcnt lgkmcnt(0)
	v_mfma_f32_32x32x16_bf16 v[32:47], v[16:19], v[112:115], v[0:15]
	v_mfma_f32_32x32x16_bf16 v[16:31], v[48:51], v[112:115], v[0:15]
	ds_read_b128 v[48:51], v203 offset:49152
	ds_read_b128 v[52:55], v203 offset:53248
	s_waitcnt lgkmcnt(0)
	v_mfma_f32_32x32x16_bf16 v[32:47], v[48:51], v[116:119], v[32:47]
	v_mfma_f32_32x32x16_bf16 v[16:31], v[52:55], v[116:119], v[16:31]
	ds_read_b128 v[48:51], v204 offset:49152
	ds_read_b128 v[52:55], v204 offset:53248
	s_waitcnt lgkmcnt(0)
	v_mfma_f32_32x32x16_bf16 v[32:47], v[48:51], v[120:123], v[32:47]
	v_mfma_f32_32x32x16_bf16 v[16:31], v[52:55], v[120:123], v[16:31]
	ds_read_b128 v[48:51], v205 offset:49152
	ds_read_b128 v[52:55], v205 offset:53248
	s_waitcnt lgkmcnt(0)
	v_mfma_f32_32x32x16_bf16 v[32:47], v[48:51], v[124:127], v[32:47]
	v_mfma_f32_32x32x16_bf16 v[16:31], v[52:55], v[124:127], v[16:31]
	s_nop 10
	v_exp_f32_e32 v32, v32
	v_exp_f32_e32 v33, v33
	v_exp_f32_e32 v34, v34
	v_exp_f32_e32 v35, v35
	v_exp_f32_e32 v36, v36
	v_add_f32_e32 v48, 0, v32
	v_exp_f32_e32 v37, v37
	v_add_f32_e32 v48, v33, v48
	v_exp_f32_e32 v38, v38
	v_add_f32_e32 v48, v34, v48
	v_exp_f32_e32 v39, v39
	v_add_f32_e32 v48, v35, v48
	v_exp_f32_e32 v40, v40
	v_add_f32_e32 v48, v36, v48
	v_exp_f32_e32 v41, v41
	v_add_f32_e32 v48, v37, v48
	v_exp_f32_e32 v42, v42
	v_add_f32_e32 v48, v38, v48
	v_exp_f32_e32 v43, v43
	v_add_f32_e32 v48, v39, v48
	v_exp_f32_e32 v44, v44
	v_add_f32_e32 v48, v40, v48
	v_exp_f32_e32 v45, v45
	v_add_f32_e32 v48, v41, v48
	v_exp_f32_e32 v46, v46
	v_add_f32_e32 v48, v42, v48
	v_exp_f32_e32 v47, v47
	v_add_f32_e32 v48, v43, v48
	v_exp_f32_e32 v16, v16
	v_add_f32_e32 v48, v44, v48
	v_exp_f32_e32 v17, v17
	v_add_f32_e32 v48, v45, v48
	v_exp_f32_e32 v18, v18
	v_add_f32_e32 v48, v46, v48
	v_exp_f32_e32 v19, v19
	v_add_f32_e32 v48, v47, v48
	v_exp_f32_e32 v20, v20
	v_add_f32_e32 v48, v16, v48
	v_exp_f32_e32 v21, v21
	v_add_f32_e32 v48, v17, v48
	v_exp_f32_e32 v22, v22
	v_add_f32_e32 v48, v18, v48
	v_exp_f32_e32 v23, v23
	v_add_f32_e32 v48, v19, v48
	v_exp_f32_e32 v24, v24
	v_add_f32_e32 v48, v20, v48
	v_exp_f32_e32 v25, v25
	v_add_f32_e32 v48, v21, v48
	v_exp_f32_e32 v26, v26
	v_add_f32_e32 v48, v22, v48
	v_exp_f32_e32 v27, v27
	v_add_f32_e32 v48, v23, v48
	v_exp_f32_e32 v28, v28
	v_add_f32_e32 v48, v24, v48
	v_exp_f32_e32 v29, v29
	v_add_f32_e32 v48, v25, v48
	v_exp_f32_e32 v30, v30
	v_add_f32_e32 v48, v26, v48
	v_exp_f32_e32 v31, v31
	v_add_f32_e32 v48, v27, v48
	v_add_f32_e32 v48, v28, v48
	v_add_f32_e32 v48, v29, v48
	v_add_f32_e32 v48, v30, v48
	v_add_f32_e32 v48, v31, v48
	v_add_f32_e32 v136, 0, v48
	v_cvt_pk_bf16_f32 v64, v32, v33
	v_cvt_pk_bf16_f32 v65, v34, v35
	v_cvt_pk_bf16_f32 v66, v36, v37
	v_cvt_pk_bf16_f32 v67, v38, v39
	v_cvt_pk_bf16_f32 v82, v40, v41
	v_cvt_pk_bf16_f32 v83, v42, v43
	v_cvt_pk_bf16_f32 v84, v44, v45
	v_cvt_pk_bf16_f32 v85, v46, v47
	v_cvt_pk_bf16_f32 v86, v16, v17
	v_cvt_pk_bf16_f32 v87, v18, v19
	v_cvt_pk_bf16_f32 v88, v20, v21
	v_cvt_pk_bf16_f32 v89, v22, v23
	v_cvt_pk_bf16_f32 v90, v24, v25
	v_cvt_pk_bf16_f32 v91, v26, v27
	v_cvt_pk_bf16_f32 v92, v28, v29
	v_cvt_pk_bf16_f32 v93, v30, v31
	ds_read_b64_tr_b16 v[16:17], v200 offset:0
	ds_read_b64_tr_b16 v[18:19], v200 offset:0x800
	ds_read_b64_tr_b16 v[32:33], v200 offset:0x1000
	ds_read_b64_tr_b16 v[34:35], v200 offset:0x1800
	ds_read_b64_tr_b16 v[36:37], v200 offset:0x2000
	ds_read_b64_tr_b16 v[38:39], v200 offset:0x2800
	ds_read_b64_tr_b16 v[40:41], v200 offset:0x3000
	ds_read_b64_tr_b16 v[42:43], v200 offset:0x3800
	s_waitcnt lgkmcnt(0)
	s_nop 0
	v_mfma_f32_32x32x16_bf16 v[16:31], v[64:67], v[16:19], 0
	v_mfma_f32_32x32x16_bf16 v[16:31], v[82:85], v[32:35], v[16:31]
	ds_read_b64_tr_b16 v[32:33], v200 offset:0x200
	ds_read_b64_tr_b16 v[34:35], v200 offset:0xa00
	ds_read_b64_tr_b16 v[48:49], v200 offset:0x1200
	ds_read_b64_tr_b16 v[50:51], v200 offset:0x1a00
	ds_read_b64_tr_b16 v[52:53], v200 offset:0x2200
	ds_read_b64_tr_b16 v[54:55], v200 offset:0x2a00
	ds_read_b64_tr_b16 v[56:57], v200 offset:0x3200
	v_mfma_f32_32x32x16_bf16 v[16:31], v[86:89], v[36:39], v[16:31]
	ds_read_b64_tr_b16 v[58:59], v200 offset:0x3a00
	s_waitcnt lgkmcnt(0)
; #define LAS __attribute__((address_space(3)))
; template <int D0> __device__ __forceinline__ void pv_one(f32x16& od, unsigned vb, bf16x8 pa0, bf16x8 pa1, bf16x8 pa2, bf16x8 pa3) {
;     const s16x4 l0 = tr_read<v_rd_off(D0, 0, 0)>(vb), h0 = tr_read<v_rd_off(D0, 0, 1)>(vb), l1 = tr_read<v_rd_off(D0, 1, 0)>(vb), h1 = tr_read<v_rd_off(D0, 1, 1)>(vb);
;     const s16x4 l2 = tr_read<v_rd_off(D0, 2, 0)>(vb), h2 = tr_read<v_rd_off(D0, 2, 1)>(vb), l3 = tr_read<v_rd_off(D0, 3, 0)>(vb), h3 = tr_read<v_rd_off(D0, 3, 1)>(vb);
;     asm volatile("s_waitcnt lgkmcnt(0)" ::: "memory"); SBAR();
;     ...
;     od = __builtin_amdgcn_mfma_f32_32x32x16_bf16(pa0, PK(l0, h0), od, 0, 0, 0);
;     od = __builtin_amdgcn_mfma_f32_32x32x16_bf16(pa1, PK(l1, h1), od, 0, 0, 0);
;     od = __builtin_amdgcn_mfma_f32_32x32x16_bf16(pa2, PK(l2, h2), od, 0, 0, 0);
;     od = __builtin_amdgcn_mfma_f32_32x32x16_bf16(pa3, PK(l3, h3), od, 0, 0, 0);
;     ...
; }
; __device__ __forceinline__ void pv_d0(f32x16 (&o)[4], unsigned vb, bf16x8 pa0, bf16x8 pa1, bf16x8 pa2, bf16x8 pa3) {
;     pv_one<0>(o[0], vb, pa0, pa1, pa2, pa3); pv_one<1>(o[1], vb, pa0, pa1, pa2, pa3); pv_one<2>(o[2], vb, pa0, pa1, pa2, pa3); pv_one<3>(o[3], vb, pa0, pa1, pa2, pa3);
; }
; template <int DQK>
; __device__ __forceinline__ void qkt(f32x16& p0, f32x16& p1, const LAS char* Ks, const bf16x8 (&qr)[DQK / 16], const int (&ka)[8], float nMB) {
;     constexpr int RB = DQK * 2, NA = (RB == 256) ? 8 : 4;
; #pragma unroll
;     for (int r = 0; r < 16; ++r) { p0[r] = nMB; p1[r] = nMB; }
; #pragma unroll
;     for (int d0 = 0; d0 < DQK / 16; ++d0) {
;         const LAS char* a = Ks + ka[d0 % NA] + (d0 / NA) * (NA * 32);
;         const bf16x8 b0 = *(const LAS bf16x8*)(a);
;         const bf16x8 b1 = *(const LAS bf16x8*)(a + 32 * RB);
;         p0 = __builtin_amdgcn_mfma_f32_32x32x16_bf16(b0, qr[d0], p0, 0, 0, 0);
;         p1 = __builtin_amdgcn_mfma_f32_32x32x16_bf16(b1, qr[d0], p1, 0, 0, 0); }
; }
; template <int DQK, bool DOUBLE> ...
;     ...
;         for (int j = 0; j < NT; ++j) {
;             SBAR(); qkt<DQK>(p0, p1, K_lds + bc * K_STRIDE, qr, ka, nMB);
;             partialSM(p0, p1); finishSM(p0, p1, l_reg, pa0, pa1, pa2, pa3); SBAR();
;             pv_d0(o, vb0 + bc * V_BYTES, pa0, pa1, pa2, pa3);
;             if (j + 1 < NT) { VMW0(); __syncthreads(); if (j + 3 < NT) DMA(j + 3, bc); }
;             { const int _t = bc; bc = bn; bn = bf; bf = _t; }
	v_mfma_f32_32x32x16_bf16 v[16:31], v[90:93], v[40:43], v[16:31]
	v_mfma_f32_32x32x16_bf16 v[32:47], v[64:67], v[32:35], 0
	v_mfma_f32_32x32x16_bf16 v[32:47], v[82:85], v[48:51], v[32:47]
	ds_read_b64_tr_b16 v[48:49], v200 offset:0x400
	ds_read_b64_tr_b16 v[50:51], v200 offset:0xc00
	ds_read_b64_tr_b16 v[68:69], v200 offset:0x1400
	ds_read_b64_tr_b16 v[70:71], v200 offset:0x1c00
	ds_read_b64_tr_b16 v[72:73], v200 offset:0x2400
	ds_read_b64_tr_b16 v[74:75], v200 offset:0x2c00
	ds_read_b64_tr_b16 v[76:77], v200 offset:0x3400
	v_mfma_f32_32x32x16_bf16 v[32:47], v[86:89], v[52:55], v[32:47]
	ds_read_b64_tr_b16 v[78:79], v200 offset:0x3c00
	s_waitcnt lgkmcnt(0)
	v_mfma_f32_32x32x16_bf16 v[32:47], v[90:93], v[56:59], v[32:47]
	v_mfma_f32_32x32x16_bf16 v[48:63], v[64:67], v[48:51], 0
	v_mfma_f32_32x32x16_bf16 v[48:63], v[82:85], v[68:71], v[48:63]
	ds_read_b64_tr_b16 v[68:69], v200 offset:0x600
	ds_read_b64_tr_b16 v[70:71], v200 offset:0xe00
	ds_read_b64_tr_b16 v[94:95], v200 offset:0x1600
	ds_read_b64_tr_b16 v[96:97], v200 offset:0x1e00
	ds_read_b64_tr_b16 v[98:99], v200 offset:0x2600
	ds_read_b64_tr_b16 v[100:101], v200 offset:0x2e00
	ds_read_b64_tr_b16 v[102:103], v200 offset:0x3600
	v_mfma_f32_32x32x16_bf16 v[48:63], v[86:89], v[72:75], v[48:63]
	ds_read_b64_tr_b16 v[104:105], v200 offset:0x3e00
	s_waitcnt lgkmcnt(0)
	v_mfma_f32_32x32x16_bf16 v[48:63], v[90:93], v[76:79], v[48:63]
	v_mfma_f32_32x32x16_bf16 v[64:79], v[64:67], v[68:71], 0
	s_ashr_i32 s59, s58, 31
	v_lshl_add_u64 v[106:107], v[128:129], 0, s[58:59]
	v_lshlrev_b64 v[106:107], 11, v[106:107]
	v_lshl_add_u64 v[106:107], s[56:57], 0, v[106:107]
	v_lshl_add_u64 v[166:167], v[106:107], 0, v[80:81]
	v_lshl_add_u64 v[106:107], v[130:131], 0, s[58:59]
	s_mov_b32 m0, s4
	v_mfma_f32_32x32x16_bf16 v[64:79], v[82:85], v[94:97], v[64:79]
	v_lshlrev_b64 v[82:83], 11, v[106:107]
	v_lshl_add_u64 v[82:83], s[56:57], 0, v[82:83]
	v_lshl_add_u64 v[168:169], v[82:83], 0, v[80:81]
	v_lshl_add_u64 v[82:83], v[132:133], 0, s[58:59]
	s_waitcnt vmcnt(0)
	s_waitcnt vmcnt(0)
	s_barrier
	global_load_lds_dwordx4 v[166:167], off
	s_mov_b32 m0, s2
	v_lshlrev_b64 v[82:83], 11, v[82:83]
	global_load_lds_dwordx4 v[168:169], off
	v_lshl_add_u64 v[170:171], v[134:135], 0, v[82:83]
	s_mov_b32 m0, s21
	v_mfma_f32_32x32x16_bf16 v[64:79], v[86:89], v[98:101], v[64:79]
	global_load_lds_dwordx4 v[170:171], off
	v_lshl_add_u64 v[138:139], s[56:57], 0, v[80:81]
	s_add_i32 s2, s71, -1
	s_mov_b32 s21, 0
	s_mov_b32 s56, s44
	s_mov_b32 s35, 0
	v_mfma_f32_32x32x16_bf16 v[64:79], v[90:93], v[102:105], v[64:79]
	s_waitcnt lgkmcnt(0)
.LBB0_155:
	s_mov_b32 s33, s20
	s_mov_b32 s20, s35
	s_mul_i32 s35, s5, 0x6000
	s_add_i32 s35, s35, 0
	s_lshl_b32 s41, s5, 14
	v_add_u32_e32 v206, s35, v145
	v_add_u32_e32 v207, s35, v161
	v_add_u32_e32 v208, s35, v198
	v_add_u32_e32 v209, s35, v199
	v_add_u32_e32 v137, s41, v200
	ds_read_b128 v[222:225], v206 offset:49152
	ds_read_b128 v[238:241], v207 offset:49152
	ds_read_b128 v[242:245], v208 offset:49152
	s_waitcnt lgkmcnt(2)
	v_mfma_f32_32x32x16_bf16 v[96:111], v[222:225], v[112:115], v[0:15]
	ds_read_b128 v[246:249], v209 offset:49152
	s_waitcnt lgkmcnt(2)
	v_mfma_f32_32x32x16_bf16 v[96:111], v[238:241], v[116:119], v[96:111]
	ds_read_b128 v[222:225], v206 offset:53248
	s_waitcnt lgkmcnt(2)
	v_mfma_f32_32x32x16_bf16 v[96:111], v[242:245], v[120:123], v[96:111]
	ds_read_b128 v[238:241], v207 offset:53248
	s_waitcnt lgkmcnt(2)
	v_mfma_f32_32x32x16_bf16 v[96:111], v[246:249], v[124:127], v[96:111]
	ds_read_b128 v[242:245], v208 offset:53248
	s_waitcnt lgkmcnt(2)
	v_mfma_f32_32x32x16_bf16 v[80:95], v[222:225], v[112:115], v[0:15]
	ds_read_b128 v[246:249], v209 offset:53248
	s_waitcnt lgkmcnt(2)
	v_mfma_f32_32x32x16_bf16 v[80:95], v[238:241], v[116:119], v[80:95]
	ds_read_b64_tr_b16 v[222:223], v137 offset:0
	ds_read_b64_tr_b16 v[224:225], v137 offset:2048
	s_nop 3
	v_exp_f32_e32 v96, v96
	v_exp_f32_e32 v97, v97
	v_exp_f32_e32 v98, v98
	v_exp_f32_e32 v99, v99
	v_exp_f32_e32 v104, v104
	v_exp_f32_e32 v105, v105
	s_waitcnt lgkmcnt(3)
	v_mfma_f32_32x32x16_bf16 v[80:95], v[242:245], v[120:123], v[80:95]
	ds_read_b64_tr_b16 v[238:239], v137 offset:512
	ds_read_b64_tr_b16 v[240:241], v137 offset:2560
	v_exp_f32_e32 v100, v100
	v_exp_f32_e32 v101, v101
	v_exp_f32_e32 v102, v102
	v_exp_f32_e32 v103, v103
	v_exp_f32_e32 v106, v106
	v_exp_f32_e32 v107, v107
	s_waitcnt lgkmcnt(4)
	v_mfma_f32_32x32x16_bf16 v[80:95], v[246:249], v[124:127], v[80:95]
	ds_read_b64_tr_b16 v[242:243], v137 offset:1024
	ds_read_b64_tr_b16 v[244:245], v137 offset:3072
	v_cvt_pk_bf16_f32 v206, v96, v97
	v_cvt_pk_bf16_f32 v207, v98, v99
	v_cvt_pk_bf16_f32 v208, v100, v101
	v_cvt_pk_bf16_f32 v209, v102, v103
	v_exp_f32_e32 v108, v108
	v_exp_f32_e32 v109, v109
	v_add_f32_e32 v96, 0, v96
	v_add_f32_e32 v96, v97, v96
	s_waitcnt lgkmcnt(4)
	v_mfma_f32_32x32x16_bf16 v[16:31], v[206:209], v[222:225], v[16:31]
	ds_read_b64_tr_b16 v[246:247], v137 offset:1536
	ds_read_b64_tr_b16 v[248:249], v137 offset:3584
	v_exp_f32_e32 v110, v110
	v_exp_f32_e32 v111, v111
	v_add_f32_e32 v96, v98, v96
	v_add_f32_e32 v96, v99, v96
	s_waitcnt lgkmcnt(4)
	v_mfma_f32_32x32x16_bf16 v[32:47], v[206:209], v[238:241], v[32:47]
	ds_read_b64_tr_b16 v[222:223], v137 offset:4096
	ds_read_b64_tr_b16 v[224:225], v137 offset:6144
	v_cvt_pk_bf16_f32 v210, v104, v105
	v_cvt_pk_bf16_f32 v211, v106, v107
	v_exp_f32_e32 v80, v80
	v_exp_f32_e32 v81, v81
	v_exp_f32_e32 v88, v88
	v_exp_f32_e32 v89, v89
	v_add_f32_e32 v96, v100, v96
	v_add_f32_e32 v96, v101, v96
	s_waitcnt lgkmcnt(4)
; #define SBAR() __builtin_amdgcn_sched_barrier(0)
; #define PK8(P, BASE, OUT) do { u32x4 w = {cvt_pk_bf16(P[BASE + 0], P[BASE + 1]), cvt_pk_bf16(P[BASE + 2], P[BASE + 3]), cvt_pk_bf16(P[BASE + 4], P[BASE + 5]), cvt_pk_bf16(P[BASE + 6], P[BASE + 7])}; \
;     OUT = *reinterpret_cast<bf16x8*>(&w); } while (0)
; #define VMW0() asm volatile("s_waitcnt vmcnt(0)" ::: "memory")
; template <int D0> __device__ __forceinline__ void pv_one(f32x16& od, unsigned vb, bf16x8 pa0, bf16x8 pa1, bf16x8 pa2, bf16x8 pa3) {
;     const s16x4 l0 = tr_read<v_rd_off(D0, 0, 0)>(vb), h0 = tr_read<v_rd_off(D0, 0, 1)>(vb), l1 = tr_read<v_rd_off(D0, 1, 0)>(vb), h1 = tr_read<v_rd_off(D0, 1, 1)>(vb);
;     const s16x4 l2 = tr_read<v_rd_off(D0, 2, 0)>(vb), h2 = tr_read<v_rd_off(D0, 2, 1)>(vb), l3 = tr_read<v_rd_off(D0, 3, 0)>(vb), h3 = tr_read<v_rd_off(D0, 3, 1)>(vb);
;     asm volatile("s_waitcnt lgkmcnt(0)" ::: "memory"); SBAR();
;     ...
;     od = __builtin_amdgcn_mfma_f32_32x32x16_bf16(pa0, PK(l0, h0), od, 0, 0, 0);
;     od = __builtin_amdgcn_mfma_f32_32x32x16_bf16(pa1, PK(l1, h1), od, 0, 0, 0);
;     od = __builtin_amdgcn_mfma_f32_32x32x16_bf16(pa2, PK(l2, h2), od, 0, 0, 0);
;     od = __builtin_amdgcn_mfma_f32_32x32x16_bf16(pa3, PK(l3, h3), od, 0, 0, 0);
;     ...
; }
; __device__ __forceinline__ void pv_d0(f32x16 (&o)[4], unsigned vb, bf16x8 pa0, bf16x8 pa1, bf16x8 pa2, bf16x8 pa3) {
;     pv_one<0>(o[0], vb, pa0, pa1, pa2, pa3); pv_one<1>(o[1], vb, pa0, pa1, pa2, pa3); pv_one<2>(o[2], vb, pa0, pa1, pa2, pa3); pv_one<3>(o[3], vb, pa0, pa1, pa2, pa3);
; }
; __device__ __forceinline__ void partialSM(f32x16& p0, f32x16& p1) {
; #pragma unroll
;     for (int r = 0; r < 16; ++r) p0[r] = __builtin_amdgcn_exp2f(p0[r]);
; }
; __device__ __forceinline__ void finishSM(f32x16& p0, f32x16& p1, float& l_reg, bf16x8& pa0, bf16x8& pa1, bf16x8& pa2, bf16x8& pa3) {
; #pragma unroll
;     for (int r = 0; r < 16; ++r) p1[r] = __builtin_amdgcn_exp2f(p1[r]);
;     float ps = 0;
; #pragma unroll
;     for (int r = 0; r < 16; ++r) ps += p0[r];
; #pragma unroll
;     for (int r = 0; r < 16; ++r) ps += p1[r];
;     l_reg += ps;
;     ...
;     PK8(p0, 0, pa0); PK8(p0, 8, pa1); PK8(p1, 0, pa2); PK8(p1, 8, pa3);
;     ...
; }
; template <int DQK, bool DOUBLE> ...
;     ...
;             if (j + 1 < NT) { VMW0(); __syncthreads(); if (j + 3 < NT) DMA(j + 3, bc); }
	v_mfma_f32_32x32x16_bf16 v[48:63], v[206:209], v[242:245], v[48:63]
	ds_read_b64_tr_b16 v[238:239], v137 offset:4608
	ds_read_b64_tr_b16 v[240:241], v137 offset:6656
	v_cvt_pk_bf16_f32 v212, v108, v109
	v_exp_f32_e32 v82, v82
	v_exp_f32_e32 v83, v83
	v_exp_f32_e32 v90, v90
	v_add_f32_e32 v96, v102, v96
	v_add_f32_e32 v96, v103, v96
	s_waitcnt lgkmcnt(4)
	v_mfma_f32_32x32x16_bf16 v[64:79], v[206:209], v[246:249], v[64:79]
	ds_read_b64_tr_b16 v[242:243], v137 offset:5120
	ds_read_b64_tr_b16 v[244:245], v137 offset:7168
	v_cvt_pk_bf16_f32 v213, v110, v111
	v_exp_f32_e32 v84, v84
	v_exp_f32_e32 v85, v85
	v_exp_f32_e32 v91, v91
	v_add_f32_e32 v96, v104, v96
	v_add_f32_e32 v96, v105, v96
	s_waitcnt lgkmcnt(4)
	v_mfma_f32_32x32x16_bf16 v[16:31], v[210:213], v[222:225], v[16:31]
	ds_read_b64_tr_b16 v[246:247], v137 offset:5632
	ds_read_b64_tr_b16 v[248:249], v137 offset:7680
	v_exp_f32_e32 v86, v86
	v_exp_f32_e32 v87, v87
	v_exp_f32_e32 v92, v92
	v_add_f32_e32 v96, v106, v96
	v_add_f32_e32 v96, v107, v96
	s_waitcnt lgkmcnt(4)
	v_mfma_f32_32x32x16_bf16 v[32:47], v[210:213], v[238:241], v[32:47]
	ds_read_b64_tr_b16 v[222:223], v137 offset:8192
	ds_read_b64_tr_b16 v[224:225], v137 offset:10240
	v_cvt_pk_bf16_f32 v214, v80, v81
	v_cvt_pk_bf16_f32 v215, v82, v83
	v_exp_f32_e32 v93, v93
	v_add_f32_e32 v96, v108, v96
	v_add_f32_e32 v96, v109, v96
	s_waitcnt lgkmcnt(4)
	v_mfma_f32_32x32x16_bf16 v[48:63], v[210:213], v[242:245], v[48:63]
	ds_read_b64_tr_b16 v[238:239], v137 offset:8704
	ds_read_b64_tr_b16 v[240:241], v137 offset:10752
	v_cvt_pk_bf16_f32 v216, v84, v85
	v_exp_f32_e32 v94, v94
	v_add_f32_e32 v96, v110, v96
	v_add_f32_e32 v96, v111, v96
	s_waitcnt lgkmcnt(4)
	v_mfma_f32_32x32x16_bf16 v[64:79], v[210:213], v[246:249], v[64:79]
	ds_read_b64_tr_b16 v[242:243], v137 offset:9216
	ds_read_b64_tr_b16 v[244:245], v137 offset:11264
	v_cvt_pk_bf16_f32 v217, v86, v87
	v_exp_f32_e32 v95, v95
	v_add_f32_e32 v80, v80, v96
	v_add_f32_e32 v80, v81, v80
	s_waitcnt lgkmcnt(4)
	v_mfma_f32_32x32x16_bf16 v[16:31], v[214:217], v[222:225], v[16:31]
	ds_read_b64_tr_b16 v[246:247], v137 offset:9728
	ds_read_b64_tr_b16 v[248:249], v137 offset:11776
	v_cvt_pk_bf16_f32 v218, v88, v89
	v_add_f32_e32 v80, v82, v80
	v_add_f32_e32 v80, v83, v80
	v_add_f32_e32 v80, v84, v80
	s_waitcnt lgkmcnt(4)
	v_mfma_f32_32x32x16_bf16 v[32:47], v[214:217], v[238:241], v[32:47]
	ds_read_b64_tr_b16 v[222:223], v137 offset:12288
	ds_read_b64_tr_b16 v[224:225], v137 offset:14336
	v_cvt_pk_bf16_f32 v219, v90, v91
	v_add_f32_e32 v80, v85, v80
	v_add_f32_e32 v80, v86, v80
	v_add_f32_e32 v80, v87, v80
	s_waitcnt lgkmcnt(4)
	v_mfma_f32_32x32x16_bf16 v[48:63], v[214:217], v[242:245], v[48:63]
	ds_read_b64_tr_b16 v[238:239], v137 offset:12800
	ds_read_b64_tr_b16 v[240:241], v137 offset:14848
	v_cvt_pk_bf16_f32 v220, v92, v93
	s_waitcnt lgkmcnt(4)
	v_mfma_f32_32x32x16_bf16 v[64:79], v[214:217], v[246:249], v[64:79]
	ds_read_b64_tr_b16 v[242:243], v137 offset:13312
	ds_read_b64_tr_b16 v[244:245], v137 offset:15360
	v_cvt_pk_bf16_f32 v221, v94, v95
	v_add_f32_e32 v80, v88, v80
	v_add_f32_e32 v80, v89, v80
	v_add_f32_e32 v80, v90, v80
	s_waitcnt lgkmcnt(4)
	v_mfma_f32_32x32x16_bf16 v[16:31], v[218:221], v[222:225], v[16:31]
	ds_read_b64_tr_b16 v[246:247], v137 offset:13824
	ds_read_b64_tr_b16 v[248:249], v137 offset:15872
	v_add_f32_e32 v80, v91, v80
	v_add_f32_e32 v80, v92, v80
	v_add_f32_e32 v80, v93, v80
	v_add_f32_e32 v80, v94, v80
	s_waitcnt lgkmcnt(4)
	v_mfma_f32_32x32x16_bf16 v[32:47], v[218:221], v[238:241], v[32:47]
	v_add_f32_e32 v80, v95, v80
	s_waitcnt lgkmcnt(2)
	v_mfma_f32_32x32x16_bf16 v[48:63], v[218:221], v[242:245], v[48:63]
	s_waitcnt lgkmcnt(0)
	v_mfma_f32_32x32x16_bf16 v[64:79], v[218:221], v[246:249], v[64:79]
	s_add_i32 s42, s21, 2
	s_cmp_ge_i32 s42, s71
	s_cbranch_scc1 .LBB0_158
	s_waitcnt vmcnt(0)
	s_add_i32 s42, s21, 4
	s_cmp_ge_i32 s42, s71
	s_waitcnt vmcnt(0)
	s_barrier
	s_cbranch_scc1 .LBB0_158
	s_ashr_i32 s57, s56, 31
	v_lshl_add_u64 v[184:185], s[56:57], 0, v[128:129]
	s_add_i32 s41, s4, s41
	v_lshlrev_b64 v[184:185], 11, v[184:185]
	v_lshl_add_u64 v[184:185], v[138:139], 0, v[184:185]
	s_mov_b32 m0, s41
	s_add_i32 s35, s35, s3
	global_load_lds_dwordx4 v[184:185], off
	v_lshl_add_u64 v[184:185], s[56:57], 0, v[130:131]
	v_lshlrev_b64 v[184:185], 11, v[184:185]
	v_lshl_add_u64 v[184:185], v[138:139], 0, v[184:185]
	s_add_i32 m0, s41, 0x2000
	s_nop 0
	global_load_lds_dwordx4 v[184:185], off
	v_lshl_add_u64 v[184:185], s[56:57], 0, v[132:133]
	v_lshlrev_b64 v[184:185], 11, v[184:185]
	v_lshl_add_u64 v[184:185], v[134:135], 0, v[184:185]
	s_add_i32 m0, s35, 0xc000
	s_nop 0
	global_load_lds_dwordx4 v[184:185], off
.LBB0_158:
	s_add_i32 s56, s56, 64
	s_add_i32 s21, s21, 1
	s_cmp_lg_u32 s2, s21
	v_add_f32_e32 v136, v136, v80
	s_cbranch_scc0 .LBB0_160
	s_mov_b32 s35, s5
	s_mov_b32 s5, s33
	s_branch .LBB0_155
; __device__ __forceinline__ int v_rd_base(int lane) { return ((lane & 3) << 3) | (((lane >> 2) & 3) << 6) | (((lane >> 4) & 1) << 5) | (((lane >> 5) & 1) << 8); }
; #define VMW0() asm volatile("s_waitcnt vmcnt(0)" ::: "memory")
; template <int DQK, bool DOUBLE> ...
;     ...
;     { const bf16_t* Qw = Q + (size_t)(wid * 32 + r32) * ldq + hi * 8;
; #pragma unroll
;       for (int d0 = 0; d0 < DQK / 16; ++d0) qr[d0] = *(const bf16x8*)(Qw + d0 * 16); }
; #pragma unroll
;     for (int d = 0; d < 4; ++d) o[d] = f32x16{};
;     l_reg = 0.f;
;     int vrow[2], vcol[2], krow[NLD], kcol[NLD];
; #pragma unroll
;     for (int i = 0; i < 2; ++i) { const int q = tid + 512 * i, sub = q >> 5, within = q & 31, kk = (sub >> 2) * 8 + (within >> 2);
;         vrow[i] = kk; vcol[i] = (sub & 3) * 32 + (within & 3) * 8; }
; #pragma unroll
;     for (int i = 0; i < NLD; ++i) { const int q = tid + 512 * i, row = q / NCH, chp = q % NCH; const int x = (RB == 256) ? (row & 15) : ((row >> 1) & 7);
;         krow[i] = row; kcol[i] = (chp ^ x) * 8; }
;     const unsigned vb0 = (unsigned)(uintptr_t)V_lds + v_rd_base(lane);
;     int ka[8];
; #pragma unroll
;     for (int q = 0; q < 8; ++q) ka[q] = kswz<RB>(r32, q * 32 + hi * 16);
;     ...
;     bf16x8 pa0, pa1, pa2, pa3;
;     __syncthreads();
;     DMA(0, 0); DMA(1, 1); VMW0(); __syncthreads();
; __device__ __forceinline__ void attn_item(const AttnBufs& T, int type, int b, int h, int qrow0, int NT, LAS char* lds, int tid_) {
;     ...
;         att::row_recip(l_reg, rli, li, r32, hi);
;         f32x4* scr = (f32x4*)(T.SCR + ((size_t)blockIdx.x * 512 + tid) * 64);
; #pragma unroll
;         for (int d0 = 0; d0 < 4; ++d0)
; #pragma unroll
;             for (int q = 0; q < 4; ++q) scr[d0 * 4 + q] = (f32x4){o[d0][q * 4] * rli[q * 4], o[d0][q * 4 + 1] * rli[q * 4 + 1], o[d0][q * 4 + 2] * rli[q * 4 + 2], o[d0][q * 4 + 3] * rli[q * 4 + 3]};
;         att::attn_pass<64, ATT_DBL>(T.QC + (size_t)qrow0 * 1024 + h * 128 + 64, 1024, T.KC + h * 128 + 64, 1024, T.VC + h * 128, 1024, rowc, rowl, NT,
.LBB0_160:
	s_nop 11
	v_mov_b32_e32 v0, v136
	s_nop 1
	v_permlane32_swap_b32_e32 v136, v0
	v_cmp_gt_u32_e32 vcc, 32, v182
	s_and_saveexec_b64 s[56:57], vcc
	v_lshl_add_u32 v1, v181, 2, s90
	v_add_f32_e32 v0, v136, v0
	ds_write_b32 v1, v0
	s_or_b64 exec, exec, s[56:57]
	s_waitcnt lgkmcnt(0)
	v_add_u32_e32 v201, s90, v144
	ds_read_b128 v[0:3], v201
	ds_read_b128 v[4:7], v201 offset:32
	v_readlane_b32 s4, v253, 11
	v_readlane_b32 s5, v253, 12
	v_readfirstlane_b32 s3, v164
	s_waitcnt lgkmcnt(0)
	v_rcp_f32_e32 v8, v0
	v_rcp_f32_e32 v9, v1
	v_rcp_f32_e32 v10, v2
	v_rcp_f32_e32 v11, v3
	ds_read_b128 v[0:3], v201 offset:64
	v_rcp_f32_e32 v12, v4
	v_rcp_f32_e32 v13, v5
	v_rcp_f32_e32 v14, v6
	v_rcp_f32_e32 v15, v7
	ds_read_b128 v[4:7], v201 offset:96
	s_waitcnt lgkmcnt(0)
	v_rcp_f32_e32 v80, v0
	v_rcp_f32_e32 v81, v1
	v_rcp_f32_e32 v82, v2
	v_rcp_f32_e32 v83, v3
	v_rcp_f32_e32 v4, v4
	v_rcp_f32_e32 v5, v5
	v_rcp_f32_e32 v6, v6
	v_rcp_f32_e32 v7, v7
	v_lshlrev_b64 v[0:1], 8, v[164:165]
	v_lshl_add_u64 v[136:137], s[4:5], 0, v[0:1]
	v_pk_mul_f32 v[0:1], v[16:17], v[8:9]
	v_pk_mul_f32 v[2:3], v[18:19], v[10:11]
	s_waitcnt lgkmcnt(0)
	global_store_dwordx4 v[136:137], v[0:3], off
	s_ashr_i32 s3, s3, 6
	s_mov_b32 s5, 1
	v_pk_mul_f32 v[0:1], v[20:21], v[12:13]
	v_pk_mul_f32 v[2:3], v[22:23], v[14:15]
	global_store_dwordx4 v[136:137], v[0:3], off offset:16
	s_nop 1
	v_pk_mul_f32 v[0:1], v[24:25], v[80:81]
	v_pk_mul_f32 v[2:3], v[26:27], v[82:83]
	global_store_dwordx4 v[136:137], v[0:3], off offset:32
	s_nop 1
	v_pk_mul_f32 v[0:1], v[28:29], v[4:5]
	v_pk_mul_f32 v[2:3], v[30:31], v[6:7]
	global_store_dwordx4 v[136:137], v[0:3], off offset:48
	s_nop 1
	v_pk_mul_f32 v[0:1], v[32:33], v[8:9]
	v_pk_mul_f32 v[2:3], v[34:35], v[10:11]
	global_store_dwordx4 v[136:137], v[0:3], off offset:64
	s_nop 1
	v_pk_mul_f32 v[0:1], v[36:37], v[12:13]
	v_pk_mul_f32 v[2:3], v[38:39], v[14:15]
	global_store_dwordx4 v[136:137], v[0:3], off offset:80
	s_nop 1
	v_pk_mul_f32 v[0:1], v[40:41], v[80:81]
	v_pk_mul_f32 v[2:3], v[42:43], v[82:83]
	global_store_dwordx4 v[136:137], v[0:3], off offset:96
	s_nop 1
	v_pk_mul_f32 v[0:1], v[44:45], v[4:5]
	v_pk_mul_f32 v[2:3], v[46:47], v[6:7]
	global_store_dwordx4 v[136:137], v[0:3], off offset:112
	s_nop 1
	v_pk_mul_f32 v[0:1], v[48:49], v[8:9]
	v_pk_mul_f32 v[2:3], v[50:51], v[10:11]
	global_store_dwordx4 v[136:137], v[0:3], off offset:128
	s_nop 1
	v_pk_mul_f32 v[0:1], v[52:53], v[12:13]
	v_pk_mul_f32 v[2:3], v[54:55], v[14:15]
	global_store_dwordx4 v[136:137], v[0:3], off offset:144
	s_nop 1
	v_pk_mul_f32 v[0:1], v[56:57], v[80:81]
	v_pk_mul_f32 v[2:3], v[58:59], v[82:83]
	global_store_dwordx4 v[136:137], v[0:3], off offset:160
	s_nop 1
	v_pk_mul_f32 v[0:1], v[60:61], v[4:5]
	v_pk_mul_f32 v[2:3], v[62:63], v[6:7]
	global_store_dwordx4 v[136:137], v[0:3], off offset:176
	s_nop 1
	v_pk_mul_f32 v[0:1], v[64:65], v[8:9]
	v_pk_mul_f32 v[2:3], v[66:67], v[10:11]
	global_store_dwordx4 v[136:137], v[0:3], off offset:192
	s_nop 1
	v_pk_mul_f32 v[0:1], v[68:69], v[12:13]
	v_pk_mul_f32 v[2:3], v[70:71], v[14:15]
	global_store_dwordx4 v[136:137], v[0:3], off offset:208
	s_nop 1
	v_pk_mul_f32 v[0:1], v[72:73], v[80:81]
	v_pk_mul_f32 v[2:3], v[74:75], v[82:83]
	global_store_dwordx4 v[136:137], v[0:3], off offset:224
	s_nop 1
	v_pk_mul_f32 v[0:1], v[76:77], v[4:5]
	v_pk_mul_f32 v[2:3], v[78:79], v[6:7]
	global_store_dwordx4 v[136:137], v[0:3], off offset:240
	global_load_dword v48, v177, s[14:15] offset:12
	s_waitcnt vmcnt(0)
	v_mov_b32_e32 v49, v48
	v_lshl_or_b32 v0, s3, 5, v181
	v_ashrrev_i32_e32 v1, 31, v0
	v_lshlrev_b64 v[0:1], 11, v[0:1]
	s_lshl_b32 s3, s3, 10
	v_lshl_add_u64 v[0:1], s[50:51], 0, v[0:1]
	v_lshlrev_b32_e32 v2, 1, v172
	v_mov_b32_e32 v3, v177
	s_add_i32 s4, s3, 0
	v_lshl_add_u64 v[0:1], v[0:1], 0, v[2:3]
	s_mov_b32 m0, s4
	s_add_i32 s20, s4, 0x2000
	global_load_dwordx4 v[112:115], v[0:1], off offset:128
	global_load_dwordx4 v[116:119], v[0:1], off offset:160
	global_load_dwordx4 v[120:123], v[0:1], off offset:192
	global_load_dwordx4 v[124:127], v[0:1], off offset:224
	s_barrier
	global_load_lds_dwordx4 v[140:141], off
	s_mov_b32 m0, s20
	s_add_i32 s21, s4, 0xc000
	global_load_lds_dwordx4 v[142:143], off
	v_lshl_add_u64 v[0:1], v[146:147], 0, s[0:1]
	s_mov_b32 m0, s21
	v_mov_b32_e32 v50, v48
	global_load_lds_dwordx4 v[0:1], off
	s_add_i32 m0, s4, 0x4000
	v_lshl_add_u64 v[0:1], v[152:153], 0, s[0:1]
	global_load_lds_dwordx4 v[148:149], off
	s_add_i32 m0, s4, 0x6000
	v_mov_b32_e32 v51, v48
	global_load_lds_dwordx4 v[150:151], off
	s_add_i32 m0, s4, 0x12000
	v_mov_b32_e32 v52, v48
	global_load_lds_dwordx4 v[0:1], off
	s_add_i32 m0, s4, 0x8000
	s_waitcnt vmcnt(0)
	s_waitcnt vmcnt(0) lgkmcnt(0)
	s_barrier
; #define SBAR() __builtin_amdgcn_sched_barrier(0)
; #define VMW0() asm volatile("s_waitcnt vmcnt(0)" ::: "memory")
; template <int D0> __device__ __forceinline__ void pv_one(f32x16& od, unsigned vb, bf16x8 pa0, bf16x8 pa1, bf16x8 pa2, bf16x8 pa3) {
;     const s16x4 l0 = tr_read<v_rd_off(D0, 0, 0)>(vb), h0 = tr_read<v_rd_off(D0, 0, 1)>(vb), l1 = tr_read<v_rd_off(D0, 1, 0)>(vb), h1 = tr_read<v_rd_off(D0, 1, 1)>(vb);
;     const s16x4 l2 = tr_read<v_rd_off(D0, 2, 0)>(vb), h2 = tr_read<v_rd_off(D0, 2, 1)>(vb), l3 = tr_read<v_rd_off(D0, 3, 0)>(vb), h3 = tr_read<v_rd_off(D0, 3, 1)>(vb);
;     asm volatile("s_waitcnt lgkmcnt(0)" ::: "memory"); SBAR();
;     ...
;     od = __builtin_amdgcn_mfma_f32_32x32x16_bf16(pa0, PK(l0, h0), od, 0, 0, 0);
;     od = __builtin_amdgcn_mfma_f32_32x32x16_bf16(pa1, PK(l1, h1), od, 0, 0, 0);
;     od = __builtin_amdgcn_mfma_f32_32x32x16_bf16(pa2, PK(l2, h2), od, 0, 0, 0);
;     od = __builtin_amdgcn_mfma_f32_32x32x16_bf16(pa3, PK(l3, h3), od, 0, 0, 0);
;     ...
; }
; __device__ __forceinline__ void pv_d0(f32x16 (&o)[4], unsigned vb, bf16x8 pa0, bf16x8 pa1, bf16x8 pa2, bf16x8 pa3) {
;     pv_one<0>(o[0], vb, pa0, pa1, pa2, pa3); pv_one<1>(o[1], vb, pa0, pa1, pa2, pa3); pv_one<2>(o[2], vb, pa0, pa1, pa2, pa3); pv_one<3>(o[3], vb, pa0, pa1, pa2, pa3);
; }
; __device__ __forceinline__ void partialSM(f32x16& p0, f32x16& p1) {
; #pragma unroll
;     for (int r = 0; r < 16; ++r) p0[r] = __builtin_amdgcn_exp2f(p0[r]);
; }
; __device__ __forceinline__ void finishSM(f32x16& p0, f32x16& p1, float& l_reg, bf16x8& pa0, bf16x8& pa1, bf16x8& pa2, bf16x8& pa3) {
; #pragma unroll
;     for (int r = 0; r < 16; ++r) p1[r] = __builtin_amdgcn_exp2f(p1[r]);
;     float ps = 0;
; #pragma unroll
;     for (int r = 0; r < 16; ++r) ps += p0[r];
; #pragma unroll
;     for (int r = 0; r < 16; ++r) ps += p1[r];
;     l_reg += ps;
;     ...
;     PK8(p0, 0, pa0); PK8(p0, 8, pa1); PK8(p1, 0, pa2); PK8(p1, 8, pa3);
;     ...
; }
; template <int DQK, bool DOUBLE> ...
;     ...
;             SBAR(); qkt<DQK>(p0, p1, K_lds + bc * K_STRIDE, qr, ka, nMB);
;             partialSM(p0, p1); finishSM(p0, p1, l_reg, pa0, pa1, pa2, pa3); SBAR();
;             pv_d0(o, vb0 + bc * V_BYTES, pa0, pa1, pa2, pa3);
;             if (j + 1 < NT) { VMW0(); __syncthreads(); if (j + 3 < NT) DMA(j + 3, bc); }
;             { const int _t = bc; bc = bn; bn = bf; bf = _t; }
	global_load_lds_dwordx4 v[154:155], off
	s_add_i32 m0, s4, 0xa000
	v_lshl_add_u64 v[0:1], v[158:159], 0, s[0:1]
	global_load_lds_dwordx4 v[156:157], off
	s_add_i32 m0, s4, 0x18000
	v_mov_b32_e32 v53, v48
	global_load_lds_dwordx4 v[0:1], off
	v_mov_b32_e32 v54, v48
	v_mov_b32_e32 v55, v48
	v_mov_b32_e32 v56, v48
	v_mov_b32_e32 v57, v48
	v_mov_b32_e32 v58, v48
	v_mov_b32_e32 v59, v48
	v_mov_b32_e32 v60, v48
	v_mov_b32_e32 v61, v48
	v_mov_b32_e32 v62, v48
	v_mov_b32_e32 v63, v48
	ds_read_b128 v[0:3], v202 offset:49152
	ds_read_b128 v[32:35], v202 offset:53248
	s_waitcnt lgkmcnt(0)
	v_mfma_f32_32x32x16_bf16 v[16:31], v[0:3], v[112:115], v[48:63]
	v_mfma_f32_32x32x16_bf16 v[0:15], v[32:35], v[112:115], v[48:63]
	ds_read_b128 v[32:35], v203 offset:49152
	ds_read_b128 v[36:39], v203 offset:53248
	s_waitcnt lgkmcnt(0)
	v_mfma_f32_32x32x16_bf16 v[16:31], v[32:35], v[116:119], v[16:31]
	v_mfma_f32_32x32x16_bf16 v[0:15], v[36:39], v[116:119], v[0:15]
	ds_read_b128 v[32:35], v204 offset:49152
	ds_read_b128 v[36:39], v204 offset:53248
	s_waitcnt lgkmcnt(0)
	v_mfma_f32_32x32x16_bf16 v[16:31], v[32:35], v[120:123], v[16:31]
	v_mfma_f32_32x32x16_bf16 v[0:15], v[36:39], v[120:123], v[0:15]
	ds_read_b128 v[32:35], v205 offset:49152
	ds_read_b128 v[36:39], v205 offset:53248
	s_waitcnt lgkmcnt(0)
	v_mfma_f32_32x32x16_bf16 v[16:31], v[32:35], v[124:127], v[16:31]
	v_mfma_f32_32x32x16_bf16 v[0:15], v[36:39], v[124:127], v[0:15]
	s_nop 10
	v_exp_f32_e32 v16, v16
	v_exp_f32_e32 v17, v17
	v_exp_f32_e32 v18, v18
	v_exp_f32_e32 v19, v19
	v_exp_f32_e32 v20, v20
	v_exp_f32_e32 v21, v21
	v_exp_f32_e32 v22, v22
	v_exp_f32_e32 v32, v0
	v_add_f32_e32 v0, 0, v16
	v_add_f32_e32 v0, v17, v0
	v_add_f32_e32 v0, v18, v0
	v_exp_f32_e32 v23, v23
	v_add_f32_e32 v0, v19, v0
	v_exp_f32_e32 v24, v24
	v_add_f32_e32 v0, v20, v0
	v_exp_f32_e32 v25, v25
	v_add_f32_e32 v0, v21, v0
	v_exp_f32_e32 v26, v26
	v_add_f32_e32 v0, v22, v0
	v_exp_f32_e32 v27, v27
	v_add_f32_e32 v0, v23, v0
	v_exp_f32_e32 v28, v28
	v_add_f32_e32 v0, v24, v0
	v_exp_f32_e32 v29, v29
	v_add_f32_e32 v0, v25, v0
	v_exp_f32_e32 v30, v30
	v_add_f32_e32 v0, v26, v0
	v_exp_f32_e32 v31, v31
	v_add_f32_e32 v0, v27, v0
	v_add_f32_e32 v0, v28, v0
	v_exp_f32_e32 v33, v1
	v_add_f32_e32 v0, v29, v0
	v_exp_f32_e32 v34, v2
	v_add_f32_e32 v0, v30, v0
	v_exp_f32_e32 v35, v3
	v_add_f32_e32 v0, v31, v0
	v_exp_f32_e32 v4, v4
	v_add_f32_e32 v0, v32, v0
	v_exp_f32_e32 v5, v5
	v_add_f32_e32 v0, v33, v0
	v_exp_f32_e32 v6, v6
	v_add_f32_e32 v0, v34, v0
	v_exp_f32_e32 v7, v7
	v_add_f32_e32 v0, v35, v0
	v_exp_f32_e32 v8, v8
	v_add_f32_e32 v0, v4, v0
	v_exp_f32_e32 v9, v9
	v_add_f32_e32 v0, v5, v0
	v_exp_f32_e32 v10, v10
	v_add_f32_e32 v0, v6, v0
	v_exp_f32_e32 v11, v11
	v_add_f32_e32 v0, v7, v0
	v_exp_f32_e32 v12, v12
	v_add_f32_e32 v0, v8, v0
	v_exp_f32_e32 v13, v13
	v_add_f32_e32 v0, v9, v0
	v_exp_f32_e32 v14, v14
	v_add_f32_e32 v0, v10, v0
	v_exp_f32_e32 v15, v15
	v_add_f32_e32 v0, v11, v0
	v_add_f32_e32 v0, v12, v0
	v_add_f32_e32 v0, v13, v0
	v_add_f32_e32 v0, v14, v0
	v_add_f32_e32 v0, v15, v0
	v_add_f32_e32 v140, 0, v0
	v_cvt_pk_bf16_f32 v0, v16, v17
	v_cvt_pk_bf16_f32 v1, v18, v19
	v_cvt_pk_bf16_f32 v2, v20, v21
	v_cvt_pk_bf16_f32 v3, v22, v23
	v_cvt_pk_bf16_f32 v80, v24, v25
	v_cvt_pk_bf16_f32 v81, v26, v27
	v_cvt_pk_bf16_f32 v82, v28, v29
	v_cvt_pk_bf16_f32 v83, v30, v31
	v_cvt_pk_bf16_f32 v84, v32, v33
	v_cvt_pk_bf16_f32 v85, v34, v35
	v_cvt_pk_bf16_f32 v86, v4, v5
	v_cvt_pk_bf16_f32 v87, v6, v7
	v_cvt_pk_bf16_f32 v88, v8, v9
	v_cvt_pk_bf16_f32 v89, v10, v11
	v_cvt_pk_bf16_f32 v90, v12, v13
	v_cvt_pk_bf16_f32 v91, v14, v15
	ds_read_b64_tr_b16 v[4:5], v200 offset:0
	ds_read_b64_tr_b16 v[6:7], v200 offset:0x800
	ds_read_b64_tr_b16 v[8:9], v200 offset:0x1000
	ds_read_b64_tr_b16 v[10:11], v200 offset:0x1800
	ds_read_b64_tr_b16 v[12:13], v200 offset:0x2000
	ds_read_b64_tr_b16 v[14:15], v200 offset:0x2800
	ds_read_b64_tr_b16 v[16:17], v200 offset:0x3000
	ds_read_b64_tr_b16 v[18:19], v200 offset:0x3800
	s_waitcnt lgkmcnt(0)
	s_nop 0
	v_mfma_f32_32x32x16_bf16 v[64:79], v[0:3], v[4:7], 0
	ds_read_b64_tr_b16 v[4:5], v200 offset:0x200
	ds_read_b64_tr_b16 v[6:7], v200 offset:0xa00
	v_mfma_f32_32x32x16_bf16 v[64:79], v[80:83], v[8:11], v[64:79]
	ds_read_b64_tr_b16 v[8:9], v200 offset:0x1200
	ds_read_b64_tr_b16 v[10:11], v200 offset:0x1a00
	v_mfma_f32_32x32x16_bf16 v[64:79], v[84:87], v[12:15], v[64:79]
	ds_read_b64_tr_b16 v[12:13], v200 offset:0x2200
	ds_read_b64_tr_b16 v[14:15], v200 offset:0x2a00
	v_mfma_f32_32x32x16_bf16 v[64:79], v[88:91], v[16:19], v[64:79]
	ds_read_b64_tr_b16 v[16:17], v200 offset:0x3200
	ds_read_b64_tr_b16 v[18:19], v200 offset:0x3a00
	s_waitcnt lgkmcnt(0)
	v_mfma_f32_32x32x16_bf16 v[32:47], v[0:3], v[4:7], 0
	ds_read_b64_tr_b16 v[4:5], v200 offset:0x400
	ds_read_b64_tr_b16 v[6:7], v200 offset:0xc00
	v_mfma_f32_32x32x16_bf16 v[32:47], v[80:83], v[8:11], v[32:47]
	ds_read_b64_tr_b16 v[8:9], v200 offset:0x1400
	ds_read_b64_tr_b16 v[10:11], v200 offset:0x1c00
	v_mfma_f32_32x32x16_bf16 v[32:47], v[84:87], v[12:15], v[32:47]
	ds_read_b64_tr_b16 v[12:13], v200 offset:0x2400
	ds_read_b64_tr_b16 v[14:15], v200 offset:0x2c00
	ds_read_b64_tr_b16 v[92:93], v200 offset:0x3400
	ds_read_b64_tr_b16 v[94:95], v200 offset:0x3c00
	s_waitcnt lgkmcnt(0)
	v_mfma_f32_32x32x16_bf16 v[32:47], v[88:91], v[16:19], v[32:47]
	v_mfma_f32_32x32x16_bf16 v[16:31], v[0:3], v[4:7], 0
	ds_read_b64_tr_b16 v[4:5], v200 offset:0x600
	ds_read_b64_tr_b16 v[6:7], v200 offset:0xe00
	v_mfma_f32_32x32x16_bf16 v[16:31], v[80:83], v[8:11], v[16:31]
	v_mfma_f32_32x32x16_bf16 v[16:31], v[84:87], v[12:15], v[16:31]
	v_mfma_f32_32x32x16_bf16 v[16:31], v[88:91], v[92:95], v[16:31]
	ds_read_b64_tr_b16 v[92:93], v200 offset:0x1600
	ds_read_b64_tr_b16 v[94:95], v200 offset:0x1e00
	ds_read_b64_tr_b16 v[96:97], v200 offset:0x2600
	ds_read_b64_tr_b16 v[98:99], v200 offset:0x2e00
	ds_read_b64_tr_b16 v[100:101], v200 offset:0x3600
	ds_read_b64_tr_b16 v[102:103], v200 offset:0x3e00
	s_waitcnt lgkmcnt(0)
	v_mfma_f32_32x32x16_bf16 v[0:15], v[0:3], v[4:7], 0
	s_mov_b32 m0, s4
	s_waitcnt vmcnt(0)
	s_waitcnt vmcnt(0)
	s_barrier
	global_load_lds_dwordx4 v[166:167], off
	s_mov_b32 m0, s20
	v_mfma_f32_32x32x16_bf16 v[0:15], v[80:83], v[92:95], v[0:15]
	global_load_lds_dwordx4 v[168:169], off
	v_lshl_add_u64 v[80:81], v[170:171], 0, s[0:1]
	s_mov_b32 m0, s21
	s_mov_b32 s21, 2
	global_load_lds_dwordx4 v[80:81], off
	v_mfma_f32_32x32x16_bf16 v[0:15], v[84:87], v[96:99], v[0:15]
	s_mov_b32 s20, 0
	s_mov_b32 s50, s44
	s_mov_b32 s35, 0
	v_mfma_f32_32x32x16_bf16 v[0:15], v[88:91], v[100:103], v[0:15]
	s_waitcnt lgkmcnt(0)
; #define LAS __attribute__((address_space(3)))
; template <int D0> __device__ __forceinline__ void pv_one(f32x16& od, unsigned vb, bf16x8 pa0, bf16x8 pa1, bf16x8 pa2, bf16x8 pa3) {
;     const s16x4 l0 = tr_read<v_rd_off(D0, 0, 0)>(vb), h0 = tr_read<v_rd_off(D0, 0, 1)>(vb), l1 = tr_read<v_rd_off(D0, 1, 0)>(vb), h1 = tr_read<v_rd_off(D0, 1, 1)>(vb);
;     const s16x4 l2 = tr_read<v_rd_off(D0, 2, 0)>(vb), h2 = tr_read<v_rd_off(D0, 2, 1)>(vb), l3 = tr_read<v_rd_off(D0, 3, 0)>(vb), h3 = tr_read<v_rd_off(D0, 3, 1)>(vb);
;     asm volatile("s_waitcnt lgkmcnt(0)" ::: "memory"); SBAR();
;     ...
;     od = __builtin_amdgcn_mfma_f32_32x32x16_bf16(pa0, PK(l0, h0), od, 0, 0, 0);
;     od = __builtin_amdgcn_mfma_f32_32x32x16_bf16(pa1, PK(l1, h1), od, 0, 0, 0);
;     od = __builtin_amdgcn_mfma_f32_32x32x16_bf16(pa2, PK(l2, h2), od, 0, 0, 0);
;     od = __builtin_amdgcn_mfma_f32_32x32x16_bf16(pa3, PK(l3, h3), od, 0, 0, 0);
;     ...
; }
; __device__ __forceinline__ void pv_d0(f32x16 (&o)[4], unsigned vb, bf16x8 pa0, bf16x8 pa1, bf16x8 pa2, bf16x8 pa3) {
; __device__ __forceinline__ void partialSM(f32x16& p0, f32x16& p1) {
; #pragma unroll
;     for (int r = 0; r < 16; ++r) p0[r] = __builtin_amdgcn_exp2f(p0[r]);
; }
; __device__ __forceinline__ void finishSM(f32x16& p0, f32x16& p1, float& l_reg, bf16x8& pa0, bf16x8& pa1, bf16x8& pa2, bf16x8& pa3) {
; #pragma unroll
;     for (int r = 0; r < 16; ++r) p1[r] = __builtin_amdgcn_exp2f(p1[r]);
;     float ps = 0;
; #pragma unroll
;     for (int r = 0; r < 16; ++r) ps += p0[r];
; #pragma unroll
;     for (int r = 0; r < 16; ++r) ps += p1[r];
;     l_reg += ps;
;     ...
;     PK8(p0, 0, pa0); PK8(p0, 8, pa1); PK8(p1, 0, pa2); PK8(p1, 8, pa3);
; template <int DQK>
; __device__ __forceinline__ void qkt(f32x16& p0, f32x16& p1, const LAS char* Ks, const bf16x8 (&qr)[DQK / 16], const int (&ka)[8], float nMB) {
;     constexpr int RB = DQK * 2, NA = (RB == 256) ? 8 : 4;
; #pragma unroll
;     for (int r = 0; r < 16; ++r) { p0[r] = nMB; p1[r] = nMB; }
; #pragma unroll
;     for (int d0 = 0; d0 < DQK / 16; ++d0) {
;         const LAS char* a = Ks + ka[d0 % NA] + (d0 / NA) * (NA * 32);
;         const bf16x8 b0 = *(const LAS bf16x8*)(a);
;         const bf16x8 b1 = *(const LAS bf16x8*)(a + 32 * RB);
;         p0 = __builtin_amdgcn_mfma_f32_32x32x16_bf16(b0, qr[d0], p0, 0, 0, 0);
;         p1 = __builtin_amdgcn_mfma_f32_32x32x16_bf16(b1, qr[d0], p1, 0, 0, 0); }
; }
.LBB0_163:
	s_mov_b32 s33, s21
	s_mov_b32 s21, s35
	s_mul_i32 s35, s5, 0x6000
	s_add_i32 s35, s35, 0
	s_lshl_b32 s41, s5, 14
	v_add_u32_e32 v146, s35, v145
	v_add_u32_e32 v147, s35, v161
	v_add_u32_e32 v148, s35, v198
	v_add_u32_e32 v149, s35, v199
	v_add_u32_e32 v141, s41, v200
	ds_read_b128 v[202:205], v146 offset:49152
	ds_read_b128 v[206:209], v147 offset:49152
	ds_read_b128 v[210:213], v148 offset:49152
	s_waitcnt lgkmcnt(2)
	v_mfma_f32_32x32x16_bf16 v[96:111], v[202:205], v[112:115], v[48:63]
	ds_read_b128 v[214:217], v149 offset:49152
	s_waitcnt lgkmcnt(2)
	v_mfma_f32_32x32x16_bf16 v[96:111], v[206:209], v[116:119], v[96:111]
	ds_read_b128 v[202:205], v146 offset:53248
	s_waitcnt lgkmcnt(2)
	v_mfma_f32_32x32x16_bf16 v[96:111], v[210:213], v[120:123], v[96:111]
	ds_read_b128 v[206:209], v147 offset:53248
	s_waitcnt lgkmcnt(2)
	v_mfma_f32_32x32x16_bf16 v[96:111], v[214:217], v[124:127], v[96:111]
	ds_read_b128 v[210:213], v148 offset:53248
	s_waitcnt lgkmcnt(2)
	v_mfma_f32_32x32x16_bf16 v[80:95], v[202:205], v[112:115], v[48:63]
	ds_read_b128 v[214:217], v149 offset:53248
	s_waitcnt lgkmcnt(2)
	v_mfma_f32_32x32x16_bf16 v[80:95], v[206:209], v[116:119], v[80:95]
	ds_read_b64_tr_b16 v[202:203], v141 offset:0
	ds_read_b64_tr_b16 v[204:205], v141 offset:2048
	s_nop 3
	v_exp_f32_e32 v96, v96
	v_exp_f32_e32 v97, v97
	v_exp_f32_e32 v98, v98
	v_exp_f32_e32 v99, v99
	v_exp_f32_e32 v104, v104
	v_exp_f32_e32 v105, v105
	s_waitcnt lgkmcnt(3)
	v_mfma_f32_32x32x16_bf16 v[80:95], v[210:213], v[120:123], v[80:95]
	ds_read_b64_tr_b16 v[206:207], v141 offset:512
	ds_read_b64_tr_b16 v[208:209], v141 offset:2560
	v_exp_f32_e32 v100, v100
	v_exp_f32_e32 v101, v101
	v_exp_f32_e32 v102, v102
	v_exp_f32_e32 v103, v103
	v_exp_f32_e32 v106, v106
	v_exp_f32_e32 v107, v107
	s_waitcnt lgkmcnt(4)
	v_mfma_f32_32x32x16_bf16 v[80:95], v[214:217], v[124:127], v[80:95]
	ds_read_b64_tr_b16 v[210:211], v141 offset:1024
	ds_read_b64_tr_b16 v[212:213], v141 offset:3072
	v_cvt_pk_bf16_f32 v146, v96, v97
	v_cvt_pk_bf16_f32 v147, v98, v99
	v_cvt_pk_bf16_f32 v148, v100, v101
	v_cvt_pk_bf16_f32 v149, v102, v103
	v_exp_f32_e32 v108, v108
	v_exp_f32_e32 v109, v109
	v_add_f32_e32 v96, 0, v96
	v_add_f32_e32 v96, v97, v96
	s_waitcnt lgkmcnt(4)
	v_mfma_f32_32x32x16_bf16 v[64:79], v[146:149], v[202:205], v[64:79]
	ds_read_b64_tr_b16 v[214:215], v141 offset:1536
	ds_read_b64_tr_b16 v[216:217], v141 offset:3584
	v_exp_f32_e32 v110, v110
	v_exp_f32_e32 v111, v111
	v_add_f32_e32 v96, v98, v96
	v_add_f32_e32 v96, v99, v96
	s_waitcnt lgkmcnt(4)
	v_mfma_f32_32x32x16_bf16 v[32:47], v[146:149], v[206:209], v[32:47]
	ds_read_b64_tr_b16 v[202:203], v141 offset:4096
	ds_read_b64_tr_b16 v[204:205], v141 offset:6144
	v_cvt_pk_bf16_f32 v150, v104, v105
	v_cvt_pk_bf16_f32 v151, v106, v107
	v_exp_f32_e32 v80, v80
	v_exp_f32_e32 v81, v81
	v_exp_f32_e32 v88, v88
	v_exp_f32_e32 v89, v89
	v_add_f32_e32 v96, v100, v96
	v_add_f32_e32 v96, v101, v96
	s_waitcnt lgkmcnt(4)
	v_mfma_f32_32x32x16_bf16 v[16:31], v[146:149], v[210:213], v[16:31]
	ds_read_b64_tr_b16 v[206:207], v141 offset:4608
	ds_read_b64_tr_b16 v[208:209], v141 offset:6656
	v_cvt_pk_bf16_f32 v152, v108, v109
	v_exp_f32_e32 v82, v82
	v_exp_f32_e32 v83, v83
	v_exp_f32_e32 v90, v90
	v_add_f32_e32 v96, v102, v96
	v_add_f32_e32 v96, v103, v96
	s_waitcnt lgkmcnt(4)
	v_mfma_f32_32x32x16_bf16 v[0:15], v[146:149], v[214:217], v[0:15]
	ds_read_b64_tr_b16 v[210:211], v141 offset:5120
	ds_read_b64_tr_b16 v[212:213], v141 offset:7168
	v_cvt_pk_bf16_f32 v153, v110, v111
	v_exp_f32_e32 v84, v84
	v_exp_f32_e32 v85, v85
	v_exp_f32_e32 v91, v91
	v_add_f32_e32 v96, v104, v96
	v_add_f32_e32 v96, v105, v96
	s_waitcnt lgkmcnt(4)
	v_mfma_f32_32x32x16_bf16 v[64:79], v[150:153], v[202:205], v[64:79]
	ds_read_b64_tr_b16 v[214:215], v141 offset:5632
	ds_read_b64_tr_b16 v[216:217], v141 offset:7680
	v_exp_f32_e32 v86, v86
	v_exp_f32_e32 v87, v87
	v_exp_f32_e32 v92, v92
	v_add_f32_e32 v96, v106, v96
	v_add_f32_e32 v96, v107, v96
	s_waitcnt lgkmcnt(4)
	v_mfma_f32_32x32x16_bf16 v[32:47], v[150:153], v[206:209], v[32:47]
	ds_read_b64_tr_b16 v[202:203], v141 offset:8192
	ds_read_b64_tr_b16 v[204:205], v141 offset:10240
	v_cvt_pk_bf16_f32 v154, v80, v81
	v_cvt_pk_bf16_f32 v155, v82, v83
	v_exp_f32_e32 v93, v93
	v_add_f32_e32 v96, v108, v96
	v_add_f32_e32 v96, v109, v96
	s_waitcnt lgkmcnt(4)
	v_mfma_f32_32x32x16_bf16 v[16:31], v[150:153], v[210:213], v[16:31]
	ds_read_b64_tr_b16 v[206:207], v141 offset:8704
	ds_read_b64_tr_b16 v[208:209], v141 offset:10752
	v_cvt_pk_bf16_f32 v156, v84, v85
	v_exp_f32_e32 v94, v94
	v_add_f32_e32 v96, v110, v96
	v_add_f32_e32 v96, v111, v96
	s_waitcnt lgkmcnt(4)
	v_mfma_f32_32x32x16_bf16 v[0:15], v[150:153], v[214:217], v[0:15]
	ds_read_b64_tr_b16 v[210:211], v141 offset:9216
	ds_read_b64_tr_b16 v[212:213], v141 offset:11264
	v_cvt_pk_bf16_f32 v157, v86, v87
	v_exp_f32_e32 v95, v95
	v_add_f32_e32 v80, v80, v96
	v_add_f32_e32 v80, v81, v80
	s_waitcnt lgkmcnt(4)
	v_mfma_f32_32x32x16_bf16 v[64:79], v[154:157], v[202:205], v[64:79]
	ds_read_b64_tr_b16 v[214:215], v141 offset:9728
	ds_read_b64_tr_b16 v[216:217], v141 offset:11776
	v_cvt_pk_bf16_f32 v166, v88, v89
	v_add_f32_e32 v80, v82, v80
	v_add_f32_e32 v80, v83, v80
	v_add_f32_e32 v80, v84, v80
	s_waitcnt lgkmcnt(4)
	v_mfma_f32_32x32x16_bf16 v[32:47], v[154:157], v[206:209], v[32:47]
	ds_read_b64_tr_b16 v[202:203], v141 offset:12288
	ds_read_b64_tr_b16 v[204:205], v141 offset:14336
	v_cvt_pk_bf16_f32 v167, v90, v91
	v_add_f32_e32 v80, v85, v80
	v_add_f32_e32 v80, v86, v80
	v_add_f32_e32 v80, v87, v80
	s_waitcnt lgkmcnt(4)
	v_mfma_f32_32x32x16_bf16 v[16:31], v[154:157], v[210:213], v[16:31]
	ds_read_b64_tr_b16 v[206:207], v141 offset:12800
	ds_read_b64_tr_b16 v[208:209], v141 offset:14848
	v_cvt_pk_bf16_f32 v168, v92, v93
	s_waitcnt lgkmcnt(4)
	v_mfma_f32_32x32x16_bf16 v[0:15], v[154:157], v[214:217], v[0:15]
	ds_read_b64_tr_b16 v[210:211], v141 offset:13312
	ds_read_b64_tr_b16 v[212:213], v141 offset:15360
	v_cvt_pk_bf16_f32 v169, v94, v95
	v_add_f32_e32 v80, v88, v80
	v_add_f32_e32 v80, v89, v80
	v_add_f32_e32 v80, v90, v80
	s_waitcnt lgkmcnt(4)
	v_mfma_f32_32x32x16_bf16 v[64:79], v[166:169], v[202:205], v[64:79]
	ds_read_b64_tr_b16 v[214:215], v141 offset:13824
	ds_read_b64_tr_b16 v[216:217], v141 offset:15872
	v_add_f32_e32 v80, v91, v80
	v_add_f32_e32 v80, v92, v80
	v_add_f32_e32 v80, v93, v80
	v_add_f32_e32 v80, v94, v80
	s_waitcnt lgkmcnt(4)
	v_mfma_f32_32x32x16_bf16 v[32:47], v[166:169], v[206:209], v[32:47]
	v_add_f32_e32 v80, v95, v80
	s_waitcnt lgkmcnt(2)
	v_mfma_f32_32x32x16_bf16 v[16:31], v[166:169], v[210:213], v[16:31]
	s_waitcnt lgkmcnt(0)
	v_mfma_f32_32x32x16_bf16 v[0:15], v[166:169], v[214:217], v[0:15]
	s_add_i32 s42, s20, 2
	s_cmp_ge_i32 s42, s71
	s_cbranch_scc1 .LBB0_166
; #define VMW0() asm volatile("s_waitcnt vmcnt(0)" ::: "memory")
; template <int DQK, bool DOUBLE> ...
;     ...
;             if (j + 1 < NT) { VMW0(); __syncthreads(); if (j + 3 < NT) DMA(j + 3, bc); }
;             { const int _t = bc; bc = bn; bn = bf; bf = _t; }
; __device__ __forceinline__ void attn_item(const AttnBufs& T, int type, int b, int h, int qrow0, int NT, LAS char* lds, int tid_) {
;     ...
;         att::row_recip(l_reg, rli, li, r32, hi);
;         const float lam = T.lamv[0];
; #pragma unroll
;         for (int d0 = 0; d0 < 4; ++d0)
; #pragma unroll
;             for (int q = 0; q < 4; ++q) { const f32x4 a = scr[d0 * 4 + q];
; #pragma unroll
;                 for (int j = 0; j < 4; ++j) o[d0][q * 4 + j] = a[j] - lam * (o[d0][q * 4 + j] * rli[q * 4 + j]); }
	s_waitcnt vmcnt(0)
	s_add_i32 s42, s20, 4
	s_cmp_ge_i32 s42, s71
	s_waitcnt vmcnt(0)
	s_barrier
	s_cbranch_scc1 .LBB0_166
	s_ashr_i32 s51, s50, 31
	v_lshl_add_u64 v[142:143], s[50:51], 0, v[128:129]
	s_add_i32 s41, s4, s41
	v_lshlrev_b64 v[142:143], 11, v[142:143]
	v_lshl_add_u64 v[142:143], v[138:139], 0, v[142:143]
	s_mov_b32 m0, s41
	s_add_i32 s35, s35, s3
	global_load_lds_dwordx4 v[142:143], off
	v_lshl_add_u64 v[142:143], s[50:51], 0, v[130:131]
	v_lshlrev_b64 v[142:143], 11, v[142:143]
	v_lshl_add_u64 v[142:143], v[138:139], 0, v[142:143]
	s_add_i32 m0, s41, 0x2000
	s_nop 0
	global_load_lds_dwordx4 v[142:143], off
	v_lshl_add_u64 v[142:143], s[50:51], 0, v[132:133]
	v_lshlrev_b64 v[142:143], 11, v[142:143]
	v_lshl_add_u64 v[142:143], v[134:135], 0, v[142:143]
	v_lshl_add_u64 v[142:143], v[142:143], 0, s[0:1]
	s_add_i32 m0, s35, 0xc000
	s_nop 0
	global_load_lds_dwordx4 v[142:143], off
.LBB0_166:
	s_add_i32 s50, s50, 64
	s_add_i32 s20, s20, 1
	s_cmp_lg_u32 s2, s20
	v_add_f32_e32 v140, v140, v80
	s_cbranch_scc0 .LBB0_168
	s_mov_b32 s35, s5
	s_mov_b32 s5, s33
	s_branch .LBB0_163
.LBB0_168:
	s_nop 11
	v_mov_b32_e32 v48, v140
	s_nop 1
	v_permlane32_swap_b32_e32 v140, v48
	s_and_saveexec_b64 s[50:51], vcc
	v_lshl_add_u32 v49, v181, 2, s90
	v_add_f32_e32 v48, v140, v48
	ds_write_b32 v49, v48
	s_or_b64 exec, exec, s[50:51]
	s_waitcnt lgkmcnt(0)
	ds_read_b128 v[48:51], v201
	ds_read_b128 v[52:55], v201 offset:32
	s_add_i32 s2, s48, 0x800
	s_movk_i32 s4, 0x1800
	s_mov_b32 s5, 0xf000
	s_waitcnt lgkmcnt(0)
	v_rcp_f32_e32 v87, v48
	v_rcp_f32_e32 v86, v49
	v_rcp_f32_e32 v85, v50
	v_rcp_f32_e32 v84, v51
	ds_read_b128 v[48:51], v201 offset:64
	v_rcp_f32_e32 v83, v52
	v_rcp_f32_e32 v82, v53
	v_rcp_f32_e32 v81, v54
	v_rcp_f32_e32 v80, v55
	s_waitcnt lgkmcnt(0)
	v_rcp_f32_e32 v91, v48
	v_rcp_f32_e32 v90, v49
	v_rcp_f32_e32 v89, v50
	v_rcp_f32_e32 v88, v51
	ds_read_b128 v[48:51], v201 offset:96
	s_waitcnt lgkmcnt(0)
	v_mul_f32_e32 v64, v64, v87
	v_mul_f32_e32 v32, v32, v87
	v_mul_f32_e32 v16, v16, v87
	s_waitcnt lgkmcnt(0)
	v_rcp_f32_e32 v95, v48
	v_rcp_f32_e32 v94, v49
	v_rcp_f32_e32 v93, v50
	v_rcp_f32_e32 v92, v51
	global_load_dword v96, v177, s[14:15]
	global_load_dwordx4 v[60:63], v[136:137], off offset:48
	global_load_dwordx4 v[56:59], v[136:137], off offset:32
	global_load_dwordx4 v[52:55], v[136:137], off offset:16
	global_load_dwordx4 v[48:51], v[136:137], off
	v_mul_f32_e32 v0, v0, v87
	s_mov_b32 s20, 0x15000
	s_mov_b32 s21, 0x1b000
	s_mov_b32 s33, 0x27000
	v_mov_b32_e32 v161, v160
	s_mov_b64 s[48:49], 0
	s_waitcnt vmcnt(0)
	v_fma_f32 v48, -v64, v96, v48
	v_mul_f32_e32 v64, v65, v86
	v_fma_f32 v49, -v64, v96, v49
	v_mul_f32_e32 v64, v66, v85
	v_fma_f32 v50, -v64, v96, v50
	v_mul_f32_e32 v64, v67, v84
	v_fma_f32 v51, -v64, v96, v51
	v_mul_f32_e32 v64, v68, v83
	v_fma_f32 v52, -v64, v96, v52
	v_mul_f32_e32 v64, v69, v82
	v_fma_f32 v53, -v64, v96, v53
	v_mul_f32_e32 v64, v70, v81
	v_fma_f32 v54, -v64, v96, v54
	v_mul_f32_e32 v64, v71, v80
	v_fma_f32 v55, -v64, v96, v55
	v_mul_f32_e32 v64, v72, v91
	v_fma_f32 v56, -v64, v96, v56
	v_mul_f32_e32 v64, v73, v90
	v_fma_f32 v57, -v64, v96, v57
	v_mul_f32_e32 v64, v74, v89
	v_fma_f32 v58, -v64, v96, v58
	v_mul_f32_e32 v64, v75, v88
	v_fma_f32 v59, -v64, v96, v59
	v_mul_f32_e32 v64, v76, v95
	v_fma_f32 v60, -v64, v96, v60
	v_mul_f32_e32 v64, v77, v94
	v_fma_f32 v61, -v64, v96, v61
	v_mul_f32_e32 v64, v78, v93
	v_fma_f32 v62, -v64, v96, v62
	v_mul_f32_e32 v64, v79, v92
	v_fma_f32 v63, -v96, v64, v63
	global_load_dwordx4 v[70:73], v[136:137], off offset:112
	global_load_dwordx4 v[74:77], v[136:137], off offset:96
	global_load_dwordx4 v[98:101], v[136:137], off offset:80
	global_load_dwordx4 v[64:67], v[136:137], off offset:64
	s_waitcnt vmcnt(0)
	v_fma_f32 v64, -v32, v96, v64
	v_mul_f32_e32 v32, v33, v86
	v_fma_f32 v65, -v32, v96, v65
	v_mul_f32_e32 v32, v34, v85
	v_fma_f32 v66, -v32, v96, v66
	v_mul_f32_e32 v32, v35, v84
	v_fma_f32 v67, -v32, v96, v67
	v_mul_f32_e32 v32, v36, v83
	v_fma_f32 v68, -v32, v96, v98
	v_mul_f32_e32 v32, v37, v82
	v_fma_f32 v69, -v32, v96, v99
	v_mul_f32_e32 v32, v38, v81
	v_fma_f32 v38, -v32, v96, v100
	v_mul_f32_e32 v32, v39, v80
	v_fma_f32 v39, -v32, v96, v101
	v_mul_f32_e32 v32, v40, v91
	v_fma_f32 v40, -v32, v96, v74
	v_mul_f32_e32 v32, v41, v90
	v_fma_f32 v41, -v32, v96, v75
	v_mul_f32_e32 v32, v42, v89
	v_fma_f32 v42, -v32, v96, v76
	v_mul_f32_e32 v32, v43, v88
	v_fma_f32 v43, -v32, v96, v77
	v_mul_f32_e32 v32, v44, v95
	v_fma_f32 v44, -v32, v96, v70
	v_mul_f32_e32 v32, v45, v94
	v_fma_f32 v45, -v32, v96, v71
	v_mul_f32_e32 v32, v46, v93
	v_fma_f32 v46, -v32, v96, v72
	v_mul_f32_e32 v32, v47, v92
	v_fma_f32 v47, -v96, v32, v73
	global_load_dwordx4 v[32:35], v[136:137], off offset:176
	global_load_dwordx4 v[98:101], v[136:137], off offset:160
	global_load_dwordx4 v[74:77], v[136:137], off offset:144
	global_load_dwordx4 v[70:73], v[136:137], off offset:128
	s_waitcnt vmcnt(0)
	v_fma_f32 v70, -v16, v96, v70
	v_mul_f32_e32 v16, v17, v86
	v_fma_f32 v71, -v16, v96, v71
	v_mul_f32_e32 v16, v18, v85
	v_fma_f32 v72, -v16, v96, v72
	v_mul_f32_e32 v16, v19, v84
	v_fma_f32 v73, -v16, v96, v73
	v_mul_f32_e32 v16, v20, v83
	v_fma_f32 v74, -v16, v96, v74
	v_mul_f32_e32 v16, v21, v82
	v_fma_f32 v75, -v16, v96, v75
	v_mul_f32_e32 v16, v22, v81
	v_fma_f32 v76, -v16, v96, v76
	v_mul_f32_e32 v16, v23, v80
	v_fma_f32 v77, -v16, v96, v77
	v_mul_f32_e32 v16, v24, v91
	v_fma_f32 v78, -v16, v96, v98
	v_mul_f32_e32 v16, v25, v90
	v_fma_f32 v79, -v16, v96, v99
	v_mul_f32_e32 v16, v26, v89
	v_fma_f32 v97, -v16, v96, v100
	v_mul_f32_e32 v16, v27, v88
	v_fma_f32 v98, -v16, v96, v101
	v_mul_f32_e32 v16, v28, v95
	v_fma_f32 v99, -v16, v96, v32
	v_mul_f32_e32 v16, v29, v94
	v_fma_f32 v100, -v16, v96, v33
	v_mul_f32_e32 v16, v30, v93
	v_fma_f32 v101, -v16, v96, v34
	v_mul_f32_e32 v16, v31, v92
	v_fma_f32 v102, -v96, v16, v35
	global_load_dwordx4 v[16:19], v[136:137], off offset:240
	global_load_dwordx4 v[20:23], v[136:137], off offset:224
	global_load_dwordx4 v[24:27], v[136:137], off offset:208
	global_load_dwordx4 v[28:31], v[136:137], off offset:192
	s_waitcnt vmcnt(0)
; #define LAS __attribute__((address_space(3)))
; __device__ __forceinline__ int crow(int r, int hi) { return (r & 3) + 8 * (r >> 2) + 4 * hi; }
; template <bool SUBLN>
; __device__ __forceinline__ void attn_out(const AttnBufs& T, f32x16 (&o)[4], int type, int h, size_t orow0, LAS char* lds, int wid, int lane, int r32, int hi) {
;     const int rr = lane >> 5, c4 = (lane & 31) * 4;
;     const int col = type * 1024 + h * 128 + c4;
;     const bf16_t* gp = T.GATE + (orow0 + rr) * 3072 + col; bf16_t* op = T.BR + (orow0 + rr) * 3072 + col;
;     u32x2 gg[16];
; #pragma unroll
;     for (int i = 0; i < 16; ++i) gg[i] = *(const u32x2*)(gp + (size_t)i * 2 * 3072);
;     __syncthreads();
;     LAS float* stg = (LAS float*)(lds + wid * 16896);
; #pragma unroll
;     for (int d0 = 0; d0 < 4; ++d0)
; #pragma unroll
;         for (int r = 0; r < 16; ++r) stg[att::crow(r, hi) * 132 + d0 * 32 + r32] = o[d0][r];
; __device__ __forceinline__ void attn_item(const AttnBufs& T, int type, int b, int h, int qrow0, int NT, LAS char* lds, int tid_) {
;     ...
;             for (int q = 0; q < 4; ++q) { const f32x4 a = scr[d0 * 4 + q];
; #pragma unroll
;                 for (int j = 0; j < 4; ++j) o[d0][q * 4 + j] = a[j] - lam * (o[d0][q * 4 + j] * rli[q * 4 + j]); }
	v_fma_f32 v87, -v0, v96, v28
	v_mul_f32_e32 v0, v1, v86
	v_fma_f32 v86, -v0, v96, v29
	v_mul_f32_e32 v0, v2, v85
	v_fma_f32 v85, -v0, v96, v30
	v_mul_f32_e32 v0, v3, v84
	v_fma_f32 v84, -v0, v96, v31
	v_mul_f32_e32 v0, v4, v83
	v_fma_f32 v83, -v0, v96, v24
	v_mul_f32_e32 v0, v5, v82
	v_fma_f32 v82, -v0, v96, v25
	v_mul_f32_e32 v0, v6, v81
	v_fma_f32 v81, -v0, v96, v26
	v_mul_f32_e32 v0, v7, v80
	v_fma_f32 v80, -v0, v96, v27
	v_mul_f32_e32 v0, v8, v91
	v_fma_f32 v91, -v0, v96, v20
	v_mul_f32_e32 v0, v9, v90
	v_fma_f32 v90, -v0, v96, v21
	v_mul_f32_e32 v0, v10, v89
	v_fma_f32 v89, -v0, v96, v22
	v_mul_f32_e32 v0, v11, v88
	v_fma_f32 v88, -v0, v96, v23
	v_mul_f32_e32 v0, v12, v95
	v_fma_f32 v95, -v0, v96, v16
	v_mul_f32_e32 v0, v13, v94
	v_fma_f32 v94, -v0, v96, v17
	v_mul_f32_e32 v0, v14, v93
	v_fma_f32 v93, -v0, v96, v18
	v_mul_f32_e32 v0, v15, v92
	v_fma_f32 v92, -v96, v0, v19
	v_lshlrev_b32_e32 v0, 2, v182
	v_and_b32_e32 v96, 0x7c, v0
	v_or_b32_e32 v0, s2, v96
	v_readlane_b32 s2, v251, 46
	v_readlane_b32 s3, v251, 47
	v_lshl_add_u64 v[2:3], s[36:37], 0, v[176:177]
	v_ashrrev_i32_e32 v1, 31, v0
	v_mov_b64_e32 v[4:5], s[2:3]
	v_mad_u64_u32 v[4:5], s[2:3], v2, s4, v[4:5]
	v_readlane_b32 s2, v251, 48
	v_mad_i32_i24 v5, v3, s4, v5
	v_lshlrev_b64 v[0:1], 1, v[0:1]
	v_readlane_b32 s3, v251, 49
	v_lshl_add_u64 v[6:7], v[4:5], 0, v[0:1]
	global_load_dwordx2 v[36:37], v[6:7], off
	v_mov_b64_e32 v[4:5], s[2:3]
	v_mad_u64_u32 v[8:9], s[2:3], v2, s4, v[4:5]
	v_add_co_u32_e32 v2, vcc, s40, v6
	v_mad_i32_i24 v9, v3, s4, v9
	s_nop 0
	v_addc_co_u32_e32 v3, vcc, 0, v7, vcc
	global_load_dwordx2 v[34:35], v[2:3], off
	v_add_co_u32_e32 v2, vcc, s82, v6
	s_mov_b32 s4, 0x9000
	s_nop 0
	v_addc_co_u32_e32 v3, vcc, 0, v7, vcc
	global_load_dwordx2 v[32:33], v[2:3], off
	v_add_co_u32_e32 v2, vcc, s4, v6
	s_mov_b32 s3, 0x21000
	s_nop 0
	v_addc_co_u32_e32 v3, vcc, 0, v7, vcc
	global_load_dwordx2 v[30:31], v[2:3], off
	v_add_co_u32_e32 v2, vcc, s77, v6
	s_mov_b32 s2, 0x2d000
	s_nop 0
	v_addc_co_u32_e32 v3, vcc, 0, v7, vcc
	global_load_dwordx2 v[28:29], v[2:3], off
	v_add_co_u32_e32 v2, vcc, s5, v6
	v_lshl_add_u64 v[0:1], v[8:9], 0, v[0:1]
	s_nop 0
	v_addc_co_u32_e32 v3, vcc, 0, v7, vcc
	global_load_dwordx2 v[26:27], v[2:3], off
	v_add_co_u32_e32 v2, vcc, s85, v6
	s_nop 1
	v_addc_co_u32_e32 v3, vcc, 0, v7, vcc
	global_load_dwordx2 v[24:25], v[2:3], off
	v_add_co_u32_e32 v2, vcc, s20, v6
	s_nop 1
	v_addc_co_u32_e32 v3, vcc, 0, v7, vcc
	global_load_dwordx2 v[22:23], v[2:3], off
	v_add_co_u32_e32 v2, vcc, s76, v6
	s_nop 1
	v_addc_co_u32_e32 v3, vcc, 0, v7, vcc
	global_load_dwordx2 v[20:21], v[2:3], off
	v_add_co_u32_e32 v2, vcc, s21, v6
	s_nop 1
	v_addc_co_u32_e32 v3, vcc, 0, v7, vcc
	global_load_dwordx2 v[18:19], v[2:3], off
	v_add_co_u32_e32 v2, vcc, s92, v6
	s_nop 1
	v_addc_co_u32_e32 v3, vcc, 0, v7, vcc
	global_load_dwordx2 v[16:17], v[2:3], off
	v_add_co_u32_e32 v2, vcc, s3, v6
	s_nop 1
	v_addc_co_u32_e32 v3, vcc, 0, v7, vcc
	global_load_dwordx2 v[14:15], v[2:3], off
	v_add_co_u32_e32 v2, vcc, s91, v6
	s_nop 1
	v_addc_co_u32_e32 v3, vcc, 0, v7, vcc
	global_load_dwordx2 v[12:13], v[2:3], off
	v_add_co_u32_e32 v2, vcc, s33, v6
	s_nop 1
	v_addc_co_u32_e32 v3, vcc, 0, v7, vcc
	global_load_dwordx2 v[10:11], v[2:3], off
	v_add_co_u32_e32 v2, vcc, s94, v6
	s_nop 1
	v_addc_co_u32_e32 v3, vcc, 0, v7, vcc
	global_load_dwordx2 v[4:5], v[2:3], off
	v_add_co_u32_e32 v2, vcc, s2, v6
	s_add_i32 s2, s73, 0
	s_nop 0
	v_addc_co_u32_e32 v3, vcc, 0, v7, vcc
	v_lshlrev_b32_e32 v6, 2, v181
	v_mul_u32_u24_e32 v7, 0x840, v176
	v_add3_u32 v6, s2, v6, v7
	global_load_dwordx2 v[2:3], v[2:3], off
	s_barrier
	ds_write2_b32 v6, v48, v64 offset1:32
	ds_write2_b32 v6, v49, v65 offset0:132 offset1:164
	v_add_u32_e32 v7, 0x400, v6
	v_add_u32_e32 v48, 0x1000, v6
	v_add_u32_e32 v49, 0x1400, v6
	ds_write2_b32 v7, v50, v66 offset0:8 offset1:40
	ds_write2_b32 v7, v51, v67 offset0:140 offset1:172
	ds_write2_b32 v48, v52, v68 offset0:32 offset1:64
	ds_write2_b32 v48, v53, v69 offset0:164 offset1:196
	ds_write2_b32 v49, v54, v38 offset0:40 offset1:72
	ds_write2_b32 v49, v55, v39 offset0:172 offset1:204
	v_add_u32_e32 v38, 0x2000, v6
	ds_write2_b32 v38, v56, v40 offset0:64 offset1:96
	ds_write2_b32 v38, v57, v41 offset0:196 offset1:228
	v_add_u32_e32 v39, 0x2400, v6
	v_add_u32_e32 v41, 0x3200, v6
	ds_write2_b32 v39, v58, v42 offset0:72 offset1:104
	ds_write2_b32 v39, v59, v43 offset0:204 offset1:236
	v_add_u32_e32 v40, 0x3000, v6
	ds_write2_b32 v41, v61, v45 offset0:100 offset1:132
	v_add_u32_e32 v41, 0x3400, v6
	v_add_u32_e32 v42, 0x3600, v6
	ds_write2_b32 v40, v60, v44 offset0:96 offset1:128
	ds_write2_b32 v41, v62, v46 offset0:104 offset1:136
	ds_write2_b32 v42, v63, v47 offset0:108 offset1:140
	ds_write2_b32 v6, v70, v87 offset0:64 offset1:96
	ds_write2_b32 v6, v71, v86 offset0:196 offset1:228
	ds_write2_b32 v7, v72, v85 offset0:72 offset1:104
	ds_write2_b32 v7, v73, v84 offset0:204 offset1:236
	ds_write2_b32 v48, v74, v83 offset0:96 offset1:128
	v_add_u32_e32 v7, 0x1200, v6
	ds_write2_b32 v7, v75, v82 offset0:100 offset1:132
	ds_write2_b32 v49, v76, v81 offset0:104 offset1:136
	v_add_u32_e32 v7, 0x1600, v6
	ds_write2_b32 v7, v77, v80 offset0:108 offset1:140
	ds_write2_b32 v38, v78, v91 offset0:128 offset1:160
	ds_write2_b32 v39, v79, v90 offset0:4 offset1:36
	ds_write2_b32 v39, v97, v89 offset0:136 offset1:168
	v_add_u32_e32 v7, 0x2800, v6
	v_add_u32_e32 v6, 0x3800, v6
	ds_write2_b32 v7, v98, v88 offset0:12 offset1:44
	ds_write2_b32 v40, v99, v95 offset0:160 offset1:192
	ds_write2_b32 v41, v100, v94 offset0:36 offset1:68
	ds_write2_b32 v41, v101, v93 offset0:168 offset1:200
	ds_write2_b32 v6, v102, v92 offset0:44 offset1:76
	s_waitcnt lgkmcnt(0)
; #define LAS __attribute__((address_space(3)))
; __device__ __forceinline__ float bf2f(unsigned h) { return __uint_as_float(h << 16); }
; __device__ __forceinline__ unsigned cvt_pk_bf16(float lo, float hi) { unsigned r; asm volatile("v_cvt_pk_bf16_f32 %0, %1, %2" : "=v"(r) : "v"(lo), "v"(hi)); return r; }
; template <bool SUBLN>
; __device__ __forceinline__ void attn_out(const AttnBufs& T, f32x16 (&o)[4], int type, int h, size_t orow0, LAS char* lds, int wid, int lane, int r32, int hi) {
;     ...
;     f32x4 wsub = {1.f, 1.f, 1.f, 1.f};
;     if (SUBLN) { wsub = *(const f32x4*)(T.subln + c4) * (1.f - T.lam_init); }
; #pragma unroll
;     for (int i = 0; i < 16; ++i) {
;         f32x4 v = *(const LAS f32x4*)(stg + (2 * i + rr) * 132 + c4);
;         if (SUBLN) {
;             float s = (v[0] * v[0] + v[1] * v[1]) + (v[2] * v[2] + v[3] * v[3]);
;             s += __shfl_xor(s, 1); s += __shfl_xor(s, 2); s += __shfl_xor(s, 4); s += __shfl_xor(s, 8); s += __shfl_xor(s, 16);
;             v = v * (rsqrtf(s * (1.f / 128.f) + EPS)) * wsub;
;         }
;         u32x2 w; w.x = cvt_pk_bf16(v[0] * bf2f(gg[i].x & 0xffffu), v[1] * bf2f(gg[i].x >> 16)); w.y = cvt_pk_bf16(v[2] * bf2f(gg[i].y & 0xffffu), v[3] * bf2f(gg[i].y >> 16));
;         *(u32x2*)(op + (size_t)i * 2 * 3072) = w;
	v_lshlrev_b32_e32 v43, 2, v96
	global_load_dwordx4 v[38:41], v43, s[26:27]
	v_xor_b32_e32 v44, 16, v228
	s_waitcnt vmcnt(0)
	v_pk_mul_f32 v[8:9], v[162:163], v[38:39]
	v_and_b32_e32 v39, 64, v228
	v_xor_b32_e32 v38, 1, v228
	v_add_u32_e32 v42, 64, v39
	v_cmp_lt_i32_e32 vcc, v38, v42
	v_xor_b32_e32 v39, 2, v228
	v_pk_mul_f32 v[6:7], v[160:161], v[40:41]
	v_cndmask_b32_e32 v38, v228, v38, vcc
	v_cmp_lt_i32_e32 vcc, v39, v42
	v_xor_b32_e32 v40, 4, v228
	v_xor_b32_e32 v41, 8, v228
	v_cndmask_b32_e32 v39, v228, v39, vcc
	v_cmp_lt_i32_e32 vcc, v40, v42
	v_lshlrev_b32_e32 v38, 2, v38
	v_lshlrev_b32_e32 v39, 2, v39
	v_cndmask_b32_e32 v40, v228, v40, vcc
	v_cmp_lt_i32_e32 vcc, v41, v42
	v_lshlrev_b32_e32 v40, 2, v40
	s_nop 0
	v_cndmask_b32_e32 v41, v228, v41, vcc
	v_cmp_lt_i32_e32 vcc, v44, v42
	v_lshlrev_b32_e32 v41, 2, v41
	s_nop 0
	v_cndmask_b32_e32 v42, v228, v44, vcc
	v_mul_u32_u24_e32 v44, 0x210, v176
	v_add3_u32 v43, s2, v43, v44
	ds_read_b128 v[44:47], v43
	v_lshlrev_b32_e32 v42, 2, v42
	s_mov_b32 s2, 0x800000
	s_waitcnt lgkmcnt(0)
	v_pk_mul_f32 v[48:49], v[46:47], v[46:47]
	v_pk_mul_f32 v[50:51], v[44:45], v[44:45]
	s_nop 0
	v_pk_mov_b32 v[52:53], v[50:51], v[48:49] op_sel:[1,0]
	v_mov_b32_e32 v51, v49
	v_pk_add_f32 v[48:49], v[52:53], v[50:51]
	s_nop 0
	v_add_f32_e32 v48, v48, v49
	ds_bpermute_b32 v49, v38, v48
	s_waitcnt lgkmcnt(0)
	v_add_f32_e32 v48, v48, v49
	ds_bpermute_b32 v49, v39, v48
	s_waitcnt lgkmcnt(0)
	v_add_f32_e32 v48, v48, v49
	ds_bpermute_b32 v49, v40, v48
	s_waitcnt lgkmcnt(0)
	v_add_f32_e32 v48, v48, v49
	ds_bpermute_b32 v49, v41, v48
	s_waitcnt lgkmcnt(0)
	v_add_f32_e32 v48, v48, v49
	ds_bpermute_b32 v49, v42, v48
	s_waitcnt lgkmcnt(0)
	v_add_f32_e32 v48, v48, v49
	v_fmamk_f32 v48, v48, 0x3c000000, v178
	v_cmp_gt_f32_e32 vcc, s2, v48
	v_mul_f32_e32 v49, 0x4b800000, v48
	s_nop 0
	v_cndmask_b32_e32 v48, v48, v49, vcc
	v_rsq_f32_e32 v48, v48
	s_nop 0
	v_mul_f32_e32 v49, 0x45800000, v48
	v_cndmask_b32_e32 v48, v48, v49, vcc
	v_pk_mul_f32 v[44:45], v[44:45], v[48:49] op_sel_hi:[1,0]
	v_pk_mul_f32 v[46:47], v[46:47], v[48:49] op_sel_hi:[1,0]
	v_pk_mul_f32 v[44:45], v[8:9], v[44:45]
	v_lshlrev_b32_e32 v48, 16, v36
	v_and_b32_e32 v36, 0xffff0000, v36
	v_mul_f32_e32 v44, v44, v48
	v_mul_f32_e32 v36, v45, v36
	v_pk_mul_f32 v[46:47], v[6:7], v[46:47]
	v_cvt_pk_bf16_f32 v36, v44, v36
	v_lshlrev_b32_e32 v44, 16, v37
	v_and_b32_e32 v37, 0xffff0000, v37
	v_mul_f32_e32 v44, v46, v44
	v_mul_f32_e32 v37, v47, v37
	v_cvt_pk_bf16_f32 v37, v44, v37
	ds_read_b128 v[44:47], v43 offset:1056
	global_store_dwordx2 v[0:1], v[36:37], off
	s_waitcnt lgkmcnt(0)
	v_pk_mul_f32 v[36:37], v[46:47], v[46:47]
	v_pk_mul_f32 v[48:49], v[44:45], v[44:45]
	s_nop 0
	v_pk_mov_b32 v[50:51], v[48:49], v[36:37] op_sel:[1,0]
	v_mov_b32_e32 v49, v37
	v_pk_add_f32 v[36:37], v[50:51], v[48:49]
	s_nop 0
	v_add_f32_e32 v36, v36, v37
	ds_bpermute_b32 v37, v38, v36
	s_waitcnt lgkmcnt(0)
	v_add_f32_e32 v36, v36, v37
	ds_bpermute_b32 v37, v39, v36
	s_waitcnt lgkmcnt(0)
	v_add_f32_e32 v36, v36, v37
	ds_bpermute_b32 v37, v40, v36
	s_waitcnt lgkmcnt(0)
	v_add_f32_e32 v36, v36, v37
	ds_bpermute_b32 v37, v41, v36
	s_waitcnt lgkmcnt(0)
	v_add_f32_e32 v36, v36, v37
	ds_bpermute_b32 v37, v42, v36
	s_waitcnt lgkmcnt(0)
	v_add_f32_e32 v36, v36, v37
	v_fmamk_f32 v36, v36, 0x3c000000, v178
	v_cmp_gt_f32_e32 vcc, s2, v36
	v_mul_f32_e32 v37, 0x4b800000, v36
	s_nop 0
	v_cndmask_b32_e32 v36, v36, v37, vcc
	v_rsq_f32_e32 v36, v36
	s_nop 0
	v_mul_f32_e32 v37, 0x45800000, v36
	v_cndmask_b32_e32 v36, v36, v37, vcc
	v_pk_mul_f32 v[44:45], v[44:45], v[36:37] op_sel_hi:[1,0]
	v_pk_mul_f32 v[36:37], v[46:47], v[36:37] op_sel_hi:[1,0]
	v_pk_mul_f32 v[44:45], v[8:9], v[44:45]
	v_lshlrev_b32_e32 v46, 16, v34
	v_and_b32_e32 v34, 0xffff0000, v34
	v_mul_f32_e32 v44, v44, v46
	v_mul_f32_e32 v34, v45, v34
	v_pk_mul_f32 v[36:37], v[6:7], v[36:37]
	v_cvt_pk_bf16_f32 v34, v44, v34
	v_lshlrev_b32_e32 v44, 16, v35
	v_and_b32_e32 v35, 0xffff0000, v35
	v_mul_f32_e32 v36, v36, v44
	v_mul_f32_e32 v35, v37, v35
	v_cvt_pk_bf16_f32 v35, v36, v35
	v_add_co_u32_e32 v36, vcc, s40, v0
	s_nop 1
	v_addc_co_u32_e32 v37, vcc, 0, v1, vcc
	global_store_dwordx2 v[36:37], v[34:35], off
	ds_read_b128 v[34:37], v43 offset:2112
	s_waitcnt lgkmcnt(0)
	v_pk_mul_f32 v[44:45], v[36:37], v[36:37]
	v_pk_mul_f32 v[46:47], v[34:35], v[34:35]
	s_nop 0
	v_pk_mov_b32 v[48:49], v[46:47], v[44:45] op_sel:[1,0]
	v_mov_b32_e32 v47, v45
	v_pk_add_f32 v[44:45], v[48:49], v[46:47]
	s_nop 0
	v_add_f32_e32 v44, v44, v45
	ds_bpermute_b32 v45, v38, v44
	s_waitcnt lgkmcnt(0)
	v_add_f32_e32 v44, v44, v45
	ds_bpermute_b32 v45, v39, v44
	s_waitcnt lgkmcnt(0)
	v_add_f32_e32 v44, v44, v45
	ds_bpermute_b32 v45, v40, v44
	s_waitcnt lgkmcnt(0)
	v_add_f32_e32 v44, v44, v45
	ds_bpermute_b32 v45, v41, v44
	s_waitcnt lgkmcnt(0)
	v_add_f32_e32 v44, v44, v45
	ds_bpermute_b32 v45, v42, v44
	s_waitcnt lgkmcnt(0)
	v_add_f32_e32 v44, v44, v45
	v_fmamk_f32 v44, v44, 0x3c000000, v178
	v_cmp_gt_f32_e32 vcc, s2, v44
	v_mul_f32_e32 v45, 0x4b800000, v44
	s_nop 0
	v_cndmask_b32_e32 v44, v44, v45, vcc
	v_rsq_f32_e32 v44, v44
	s_nop 0
	v_mul_f32_e32 v45, 0x45800000, v44
	v_cndmask_b32_e32 v44, v44, v45, vcc
	v_pk_mul_f32 v[34:35], v[34:35], v[44:45] op_sel_hi:[1,0]
	v_pk_mul_f32 v[36:37], v[36:37], v[44:45] op_sel_hi:[1,0]
	v_pk_mul_f32 v[34:35], v[8:9], v[34:35]
	v_lshlrev_b32_e32 v44, 16, v32
	v_and_b32_e32 v32, 0xffff0000, v32
	v_mul_f32_e32 v34, v34, v44
	v_mul_f32_e32 v32, v35, v32
	v_pk_mul_f32 v[36:37], v[6:7], v[36:37]
	v_cvt_pk_bf16_f32 v32, v34, v32
	v_lshlrev_b32_e32 v34, 16, v33
	v_and_b32_e32 v33, 0xffff0000, v33
	v_mul_f32_e32 v34, v36, v34
	v_mul_f32_e32 v33, v37, v33
	v_cvt_pk_bf16_f32 v33, v34, v33
	v_add_co_u32_e32 v34, vcc, s82, v0
	s_nop 1
	v_addc_co_u32_e32 v35, vcc, 0, v1, vcc
	global_store_dwordx2 v[34:35], v[32:33], off
	ds_read_b128 v[32:35], v43 offset:3168
	s_waitcnt lgkmcnt(0)
; #define LAS __attribute__((address_space(3)))
; __device__ __forceinline__ float bf2f(unsigned h) { return __uint_as_float(h << 16); }
; __device__ __forceinline__ unsigned cvt_pk_bf16(float lo, float hi) { unsigned r; asm volatile("v_cvt_pk_bf16_f32 %0, %1, %2" : "=v"(r) : "v"(lo), "v"(hi)); return r; }
; template <bool SUBLN>
; __device__ __forceinline__ void attn_out(const AttnBufs& T, f32x16 (&o)[4], int type, int h, size_t orow0, LAS char* lds, int wid, int lane, int r32, int hi) {
;     ...
;     for (int i = 0; i < 16; ++i) {
;         f32x4 v = *(const LAS f32x4*)(stg + (2 * i + rr) * 132 + c4);
;         if (SUBLN) {
;             float s = (v[0] * v[0] + v[1] * v[1]) + (v[2] * v[2] + v[3] * v[3]);
;             s += __shfl_xor(s, 1); s += __shfl_xor(s, 2); s += __shfl_xor(s, 4); s += __shfl_xor(s, 8); s += __shfl_xor(s, 16);
;             v = v * (rsqrtf(s * (1.f / 128.f) + EPS)) * wsub;
;         }
;         u32x2 w; w.x = cvt_pk_bf16(v[0] * bf2f(gg[i].x & 0xffffu), v[1] * bf2f(gg[i].x >> 16)); w.y = cvt_pk_bf16(v[2] * bf2f(gg[i].y & 0xffffu), v[3] * bf2f(gg[i].y >> 16));
;         *(u32x2*)(op + (size_t)i * 2 * 3072) = w;
;     }
	v_pk_mul_f32 v[36:37], v[34:35], v[34:35]
	v_pk_mul_f32 v[44:45], v[32:33], v[32:33]
	s_nop 0
	v_pk_mov_b32 v[46:47], v[44:45], v[36:37] op_sel:[1,0]
	v_mov_b32_e32 v45, v37
	v_pk_add_f32 v[36:37], v[46:47], v[44:45]
	s_nop 0
	v_add_f32_e32 v36, v36, v37
	ds_bpermute_b32 v37, v38, v36
	s_waitcnt lgkmcnt(0)
	v_add_f32_e32 v36, v36, v37
	ds_bpermute_b32 v37, v39, v36
	s_waitcnt lgkmcnt(0)
	v_add_f32_e32 v36, v36, v37
	ds_bpermute_b32 v37, v40, v36
	s_waitcnt lgkmcnt(0)
	v_add_f32_e32 v36, v36, v37
	ds_bpermute_b32 v37, v41, v36
	s_waitcnt lgkmcnt(0)
	v_add_f32_e32 v36, v36, v37
	ds_bpermute_b32 v37, v42, v36
	s_waitcnt lgkmcnt(0)
	v_add_f32_e32 v36, v36, v37
	v_fmamk_f32 v36, v36, 0x3c000000, v178
	v_cmp_gt_f32_e32 vcc, s2, v36
	v_mul_f32_e32 v37, 0x4b800000, v36
	s_nop 0
	v_cndmask_b32_e32 v36, v36, v37, vcc
	v_rsq_f32_e32 v36, v36
	s_nop 0
	v_mul_f32_e32 v37, 0x45800000, v36
	v_cndmask_b32_e32 v36, v36, v37, vcc
	v_pk_mul_f32 v[32:33], v[32:33], v[36:37] op_sel_hi:[1,0]
	v_pk_mul_f32 v[34:35], v[34:35], v[36:37] op_sel_hi:[1,0]
	v_pk_mul_f32 v[32:33], v[8:9], v[32:33]
	v_lshlrev_b32_e32 v36, 16, v30
	v_and_b32_e32 v30, 0xffff0000, v30
	v_mul_f32_e32 v32, v32, v36
	v_mul_f32_e32 v30, v33, v30
	v_pk_mul_f32 v[34:35], v[6:7], v[34:35]
	v_cvt_pk_bf16_f32 v30, v32, v30
	v_lshlrev_b32_e32 v32, 16, v31
	v_and_b32_e32 v31, 0xffff0000, v31
	v_mul_f32_e32 v32, v34, v32
	v_mul_f32_e32 v31, v35, v31
	v_cvt_pk_bf16_f32 v31, v32, v31
	v_add_co_u32_e32 v32, vcc, s4, v0
	s_nop 1
	v_addc_co_u32_e32 v33, vcc, 0, v1, vcc
	global_store_dwordx2 v[32:33], v[30:31], off
	ds_read_b128 v[30:33], v43 offset:4224
	s_waitcnt lgkmcnt(0)
	v_pk_mul_f32 v[34:35], v[32:33], v[32:33]
	v_pk_mul_f32 v[36:37], v[30:31], v[30:31]
	s_nop 0
	v_pk_mov_b32 v[44:45], v[36:37], v[34:35] op_sel:[1,0]
	v_mov_b32_e32 v37, v35
	v_pk_add_f32 v[34:35], v[44:45], v[36:37]
	s_nop 0
	v_add_f32_e32 v34, v34, v35
	ds_bpermute_b32 v35, v38, v34
	s_waitcnt lgkmcnt(0)
	v_add_f32_e32 v34, v34, v35
	ds_bpermute_b32 v35, v39, v34
	s_waitcnt lgkmcnt(0)
	v_add_f32_e32 v34, v34, v35
	ds_bpermute_b32 v35, v40, v34
	s_waitcnt lgkmcnt(0)
	v_add_f32_e32 v34, v34, v35
	ds_bpermute_b32 v35, v41, v34
	s_waitcnt lgkmcnt(0)
	v_add_f32_e32 v34, v34, v35
	ds_bpermute_b32 v35, v42, v34
	s_waitcnt lgkmcnt(0)
	v_add_f32_e32 v34, v34, v35
	v_fmamk_f32 v34, v34, 0x3c000000, v178
	v_cmp_gt_f32_e32 vcc, s2, v34
	v_mul_f32_e32 v35, 0x4b800000, v34
	s_nop 0
	v_cndmask_b32_e32 v34, v34, v35, vcc
	v_rsq_f32_e32 v34, v34
	s_nop 0
	v_mul_f32_e32 v35, 0x45800000, v34
	v_cndmask_b32_e32 v34, v34, v35, vcc
	v_pk_mul_f32 v[30:31], v[30:31], v[34:35] op_sel_hi:[1,0]
	v_pk_mul_f32 v[32:33], v[32:33], v[34:35] op_sel_hi:[1,0]
	v_pk_mul_f32 v[30:31], v[8:9], v[30:31]
	v_lshlrev_b32_e32 v34, 16, v28
	v_and_b32_e32 v28, 0xffff0000, v28
	v_mul_f32_e32 v30, v30, v34
	v_mul_f32_e32 v28, v31, v28
	v_pk_mul_f32 v[32:33], v[6:7], v[32:33]
	v_cvt_pk_bf16_f32 v28, v30, v28
	v_lshlrev_b32_e32 v30, 16, v29
	v_and_b32_e32 v29, 0xffff0000, v29
	v_mul_f32_e32 v30, v32, v30
	v_mul_f32_e32 v29, v33, v29
	v_cvt_pk_bf16_f32 v29, v30, v29
	v_add_co_u32_e32 v30, vcc, s77, v0
	s_nop 1
	v_addc_co_u32_e32 v31, vcc, 0, v1, vcc
	global_store_dwordx2 v[30:31], v[28:29], off
	ds_read_b128 v[28:31], v43 offset:5280
	s_waitcnt lgkmcnt(0)
	v_pk_mul_f32 v[32:33], v[30:31], v[30:31]
	v_pk_mul_f32 v[34:35], v[28:29], v[28:29]
	s_nop 0
	v_pk_mov_b32 v[36:37], v[34:35], v[32:33] op_sel:[1,0]
	v_mov_b32_e32 v35, v33
	v_pk_add_f32 v[32:33], v[36:37], v[34:35]
	s_nop 0
	v_add_f32_e32 v32, v32, v33
	ds_bpermute_b32 v33, v38, v32
	s_waitcnt lgkmcnt(0)
	v_add_f32_e32 v32, v32, v33
	ds_bpermute_b32 v33, v39, v32
	s_waitcnt lgkmcnt(0)
	v_add_f32_e32 v32, v32, v33
	ds_bpermute_b32 v33, v40, v32
	s_waitcnt lgkmcnt(0)
	v_add_f32_e32 v32, v32, v33
	ds_bpermute_b32 v33, v41, v32
	s_waitcnt lgkmcnt(0)
	v_add_f32_e32 v32, v32, v33
	ds_bpermute_b32 v33, v42, v32
	s_waitcnt lgkmcnt(0)
	v_add_f32_e32 v32, v32, v33
	v_fmamk_f32 v32, v32, 0x3c000000, v178
	v_cmp_gt_f32_e32 vcc, s2, v32
	v_mul_f32_e32 v33, 0x4b800000, v32
	s_nop 0
	v_cndmask_b32_e32 v32, v32, v33, vcc
	v_rsq_f32_e32 v32, v32
	s_nop 0
	v_mul_f32_e32 v33, 0x45800000, v32
	v_cndmask_b32_e32 v32, v32, v33, vcc
	v_pk_mul_f32 v[28:29], v[28:29], v[32:33] op_sel_hi:[1,0]
	v_pk_mul_f32 v[30:31], v[30:31], v[32:33] op_sel_hi:[1,0]
	v_pk_mul_f32 v[28:29], v[8:9], v[28:29]
	v_lshlrev_b32_e32 v32, 16, v26
	v_and_b32_e32 v26, 0xffff0000, v26
	v_mul_f32_e32 v28, v28, v32
	v_mul_f32_e32 v26, v29, v26
	v_pk_mul_f32 v[30:31], v[6:7], v[30:31]
	v_cvt_pk_bf16_f32 v26, v28, v26
	v_lshlrev_b32_e32 v28, 16, v27
	v_and_b32_e32 v27, 0xffff0000, v27
	v_mul_f32_e32 v28, v30, v28
	v_mul_f32_e32 v27, v31, v27
	v_cvt_pk_bf16_f32 v27, v28, v27
	v_add_co_u32_e32 v28, vcc, s5, v0
	s_nop 1
	v_addc_co_u32_e32 v29, vcc, 0, v1, vcc
	global_store_dwordx2 v[28:29], v[26:27], off
	ds_read_b128 v[26:29], v43 offset:6336
	s_waitcnt lgkmcnt(0)
	v_pk_mul_f32 v[30:31], v[28:29], v[28:29]
	v_pk_mul_f32 v[32:33], v[26:27], v[26:27]
	s_nop 0
	v_pk_mov_b32 v[34:35], v[32:33], v[30:31] op_sel:[1,0]
	v_mov_b32_e32 v33, v31
	v_pk_add_f32 v[30:31], v[34:35], v[32:33]
	s_nop 0
	v_add_f32_e32 v30, v30, v31
	ds_bpermute_b32 v31, v38, v30
	s_waitcnt lgkmcnt(0)
	v_add_f32_e32 v30, v30, v31
	ds_bpermute_b32 v31, v39, v30
	s_waitcnt lgkmcnt(0)
	v_add_f32_e32 v30, v30, v31
	ds_bpermute_b32 v31, v40, v30
	s_waitcnt lgkmcnt(0)
	v_add_f32_e32 v30, v30, v31
	ds_bpermute_b32 v31, v41, v30
	s_waitcnt lgkmcnt(0)
	v_add_f32_e32 v30, v30, v31
	ds_bpermute_b32 v31, v42, v30
	s_waitcnt lgkmcnt(0)
; #define LAS __attribute__((address_space(3)))
; __device__ __forceinline__ float bf2f(unsigned h) { return __uint_as_float(h << 16); }
; __device__ __forceinline__ unsigned cvt_pk_bf16(float lo, float hi) { unsigned r; asm volatile("v_cvt_pk_bf16_f32 %0, %1, %2" : "=v"(r) : "v"(lo), "v"(hi)); return r; }
; template <bool SUBLN>
; __device__ __forceinline__ void attn_out(const AttnBufs& T, f32x16 (&o)[4], int type, int h, size_t orow0, LAS char* lds, int wid, int lane, int r32, int hi) {
;     ...
;     for (int i = 0; i < 16; ++i) {
;         f32x4 v = *(const LAS f32x4*)(stg + (2 * i + rr) * 132 + c4);
;         if (SUBLN) {
;             float s = (v[0] * v[0] + v[1] * v[1]) + (v[2] * v[2] + v[3] * v[3]);
;             s += __shfl_xor(s, 1); s += __shfl_xor(s, 2); s += __shfl_xor(s, 4); s += __shfl_xor(s, 8); s += __shfl_xor(s, 16);
;             v = v * (rsqrtf(s * (1.f / 128.f) + EPS)) * wsub;
;         }
;         u32x2 w; w.x = cvt_pk_bf16(v[0] * bf2f(gg[i].x & 0xffffu), v[1] * bf2f(gg[i].x >> 16)); w.y = cvt_pk_bf16(v[2] * bf2f(gg[i].y & 0xffffu), v[3] * bf2f(gg[i].y >> 16));
;         *(u32x2*)(op + (size_t)i * 2 * 3072) = w;
;     }
	v_add_f32_e32 v30, v30, v31
	v_fmamk_f32 v30, v30, 0x3c000000, v178
	v_cmp_gt_f32_e32 vcc, s2, v30
	v_mul_f32_e32 v31, 0x4b800000, v30
	s_nop 0
	v_cndmask_b32_e32 v30, v30, v31, vcc
	v_rsq_f32_e32 v30, v30
	s_nop 0
	v_mul_f32_e32 v31, 0x45800000, v30
	v_cndmask_b32_e32 v30, v30, v31, vcc
	v_pk_mul_f32 v[26:27], v[26:27], v[30:31] op_sel_hi:[1,0]
	v_pk_mul_f32 v[28:29], v[28:29], v[30:31] op_sel_hi:[1,0]
	v_pk_mul_f32 v[26:27], v[8:9], v[26:27]
	v_lshlrev_b32_e32 v30, 16, v24
	v_and_b32_e32 v24, 0xffff0000, v24
	v_mul_f32_e32 v26, v26, v30
	v_mul_f32_e32 v24, v27, v24
	v_pk_mul_f32 v[28:29], v[6:7], v[28:29]
	v_cvt_pk_bf16_f32 v24, v26, v24
	v_lshlrev_b32_e32 v26, 16, v25
	v_and_b32_e32 v25, 0xffff0000, v25
	v_mul_f32_e32 v26, v28, v26
	v_mul_f32_e32 v25, v29, v25
	v_cvt_pk_bf16_f32 v25, v26, v25
	v_add_co_u32_e32 v26, vcc, s85, v0
	s_nop 1
	v_addc_co_u32_e32 v27, vcc, 0, v1, vcc
	global_store_dwordx2 v[26:27], v[24:25], off
	ds_read_b128 v[24:27], v43 offset:7392
	s_waitcnt lgkmcnt(0)
	v_pk_mul_f32 v[28:29], v[26:27], v[26:27]
	v_pk_mul_f32 v[30:31], v[24:25], v[24:25]
	s_nop 0
	v_pk_mov_b32 v[32:33], v[30:31], v[28:29] op_sel:[1,0]
	v_mov_b32_e32 v31, v29
	v_pk_add_f32 v[28:29], v[32:33], v[30:31]
	s_nop 0
	v_add_f32_e32 v28, v28, v29
	ds_bpermute_b32 v29, v38, v28
	s_waitcnt lgkmcnt(0)
	v_add_f32_e32 v28, v28, v29
	ds_bpermute_b32 v29, v39, v28
	s_waitcnt lgkmcnt(0)
	v_add_f32_e32 v28, v28, v29
	ds_bpermute_b32 v29, v40, v28
	s_waitcnt lgkmcnt(0)
	v_add_f32_e32 v28, v28, v29
	ds_bpermute_b32 v29, v41, v28
	s_waitcnt lgkmcnt(0)
	v_add_f32_e32 v28, v28, v29
	ds_bpermute_b32 v29, v42, v28
	s_waitcnt lgkmcnt(0)
	v_add_f32_e32 v28, v28, v29
	v_fmamk_f32 v28, v28, 0x3c000000, v178
	v_cmp_gt_f32_e32 vcc, s2, v28
	v_mul_f32_e32 v29, 0x4b800000, v28
	s_nop 0
	v_cndmask_b32_e32 v28, v28, v29, vcc
	v_rsq_f32_e32 v28, v28
	s_nop 0
	v_mul_f32_e32 v29, 0x45800000, v28
	v_cndmask_b32_e32 v28, v28, v29, vcc
	v_pk_mul_f32 v[24:25], v[24:25], v[28:29] op_sel_hi:[1,0]
	v_pk_mul_f32 v[26:27], v[26:27], v[28:29] op_sel_hi:[1,0]
	v_pk_mul_f32 v[24:25], v[8:9], v[24:25]
	v_lshlrev_b32_e32 v28, 16, v22
	v_and_b32_e32 v22, 0xffff0000, v22
	v_mul_f32_e32 v24, v24, v28
	v_mul_f32_e32 v22, v25, v22
	v_pk_mul_f32 v[26:27], v[6:7], v[26:27]
	v_cvt_pk_bf16_f32 v22, v24, v22
	v_lshlrev_b32_e32 v24, 16, v23
	v_and_b32_e32 v23, 0xffff0000, v23
	v_mul_f32_e32 v24, v26, v24
	v_mul_f32_e32 v23, v27, v23
	v_cvt_pk_bf16_f32 v23, v24, v23
	v_add_co_u32_e32 v24, vcc, s20, v0
	s_nop 1
	v_addc_co_u32_e32 v25, vcc, 0, v1, vcc
	global_store_dwordx2 v[24:25], v[22:23], off
	ds_read_b128 v[22:25], v43 offset:8448
	s_waitcnt lgkmcnt(0)
	v_pk_mul_f32 v[26:27], v[24:25], v[24:25]
	v_pk_mul_f32 v[28:29], v[22:23], v[22:23]
	s_nop 0
	v_pk_mov_b32 v[30:31], v[28:29], v[26:27] op_sel:[1,0]
	v_mov_b32_e32 v29, v27
	v_pk_add_f32 v[26:27], v[30:31], v[28:29]
	s_nop 0
	v_add_f32_e32 v26, v26, v27
	ds_bpermute_b32 v27, v38, v26
	s_waitcnt lgkmcnt(0)
	v_add_f32_e32 v26, v26, v27
	ds_bpermute_b32 v27, v39, v26
	s_waitcnt lgkmcnt(0)
	v_add_f32_e32 v26, v26, v27
	ds_bpermute_b32 v27, v40, v26
	s_waitcnt lgkmcnt(0)
	v_add_f32_e32 v26, v26, v27
	ds_bpermute_b32 v27, v41, v26
	s_waitcnt lgkmcnt(0)
	v_add_f32_e32 v26, v26, v27
	ds_bpermute_b32 v27, v42, v26
	s_waitcnt lgkmcnt(0)
	v_add_f32_e32 v26, v26, v27
	v_fmamk_f32 v26, v26, 0x3c000000, v178
	v_cmp_gt_f32_e32 vcc, s2, v26
	v_mul_f32_e32 v27, 0x4b800000, v26
	s_nop 0
	v_cndmask_b32_e32 v26, v26, v27, vcc
	v_rsq_f32_e32 v26, v26
	s_nop 0
	v_mul_f32_e32 v27, 0x45800000, v26
	v_cndmask_b32_e32 v26, v26, v27, vcc
	v_pk_mul_f32 v[22:23], v[22:23], v[26:27] op_sel_hi:[1,0]
	v_pk_mul_f32 v[24:25], v[24:25], v[26:27] op_sel_hi:[1,0]
	v_pk_mul_f32 v[22:23], v[8:9], v[22:23]
	v_lshlrev_b32_e32 v26, 16, v20
	v_and_b32_e32 v20, 0xffff0000, v20
	v_mul_f32_e32 v22, v22, v26
	v_mul_f32_e32 v20, v23, v20
	v_pk_mul_f32 v[24:25], v[6:7], v[24:25]
	v_cvt_pk_bf16_f32 v20, v22, v20
	v_lshlrev_b32_e32 v22, 16, v21
	v_and_b32_e32 v21, 0xffff0000, v21
	v_mul_f32_e32 v22, v24, v22
	v_mul_f32_e32 v21, v25, v21
	v_cvt_pk_bf16_f32 v21, v22, v21
	v_add_co_u32_e32 v22, vcc, s76, v0
	s_nop 1
	v_addc_co_u32_e32 v23, vcc, 0, v1, vcc
	global_store_dwordx2 v[22:23], v[20:21], off
	ds_read_b128 v[20:23], v43 offset:9504
	s_waitcnt lgkmcnt(0)
	v_pk_mul_f32 v[24:25], v[22:23], v[22:23]
	v_pk_mul_f32 v[26:27], v[20:21], v[20:21]
	s_nop 0
	v_pk_mov_b32 v[28:29], v[26:27], v[24:25] op_sel:[1,0]
	v_mov_b32_e32 v27, v25
	v_pk_add_f32 v[24:25], v[28:29], v[26:27]
	s_nop 0
	v_add_f32_e32 v24, v24, v25
	ds_bpermute_b32 v25, v38, v24
	s_waitcnt lgkmcnt(0)
	v_add_f32_e32 v24, v24, v25
	ds_bpermute_b32 v25, v39, v24
	s_waitcnt lgkmcnt(0)
	v_add_f32_e32 v24, v24, v25
	ds_bpermute_b32 v25, v40, v24
	s_waitcnt lgkmcnt(0)
	v_add_f32_e32 v24, v24, v25
	ds_bpermute_b32 v25, v41, v24
	s_waitcnt lgkmcnt(0)
	v_add_f32_e32 v24, v24, v25
	ds_bpermute_b32 v25, v42, v24
	s_waitcnt lgkmcnt(0)
	v_add_f32_e32 v24, v24, v25
	v_fmamk_f32 v24, v24, 0x3c000000, v178
	v_cmp_gt_f32_e32 vcc, s2, v24
	v_mul_f32_e32 v25, 0x4b800000, v24
	s_nop 0
	v_cndmask_b32_e32 v24, v24, v25, vcc
	v_rsq_f32_e32 v24, v24
	s_nop 0
	v_mul_f32_e32 v25, 0x45800000, v24
	v_cndmask_b32_e32 v24, v24, v25, vcc
	v_pk_mul_f32 v[20:21], v[20:21], v[24:25] op_sel_hi:[1,0]
	v_pk_mul_f32 v[22:23], v[22:23], v[24:25] op_sel_hi:[1,0]
	v_pk_mul_f32 v[20:21], v[8:9], v[20:21]
	v_lshlrev_b32_e32 v24, 16, v18
	v_and_b32_e32 v18, 0xffff0000, v18
	v_mul_f32_e32 v20, v20, v24
	v_mul_f32_e32 v18, v21, v18
	v_pk_mul_f32 v[22:23], v[6:7], v[22:23]
	v_cvt_pk_bf16_f32 v18, v20, v18
	v_lshlrev_b32_e32 v20, 16, v19
	v_and_b32_e32 v19, 0xffff0000, v19
	v_mul_f32_e32 v20, v22, v20
	v_mul_f32_e32 v19, v23, v19
	v_cvt_pk_bf16_f32 v19, v20, v19
	v_add_co_u32_e32 v20, vcc, s21, v0
	s_nop 1
	v_addc_co_u32_e32 v21, vcc, 0, v1, vcc
	global_store_dwordx2 v[20:21], v[18:19], off
	ds_read_b128 v[18:21], v43 offset:10560
	s_waitcnt lgkmcnt(0)
; #define LAS __attribute__((address_space(3)))
; __device__ __forceinline__ float bf2f(unsigned h) { return __uint_as_float(h << 16); }
; __device__ __forceinline__ unsigned cvt_pk_bf16(float lo, float hi) { unsigned r; asm volatile("v_cvt_pk_bf16_f32 %0, %1, %2" : "=v"(r) : "v"(lo), "v"(hi)); return r; }
; template <bool SUBLN>
; __device__ __forceinline__ void attn_out(const AttnBufs& T, f32x16 (&o)[4], int type, int h, size_t orow0, LAS char* lds, int wid, int lane, int r32, int hi) {
;     ...
;     for (int i = 0; i < 16; ++i) {
;         f32x4 v = *(const LAS f32x4*)(stg + (2 * i + rr) * 132 + c4);
;         if (SUBLN) {
;             float s = (v[0] * v[0] + v[1] * v[1]) + (v[2] * v[2] + v[3] * v[3]);
;             s += __shfl_xor(s, 1); s += __shfl_xor(s, 2); s += __shfl_xor(s, 4); s += __shfl_xor(s, 8); s += __shfl_xor(s, 16);
;             v = v * (rsqrtf(s * (1.f / 128.f) + EPS)) * wsub;
;         }
;         u32x2 w; w.x = cvt_pk_bf16(v[0] * bf2f(gg[i].x & 0xffffu), v[1] * bf2f(gg[i].x >> 16)); w.y = cvt_pk_bf16(v[2] * bf2f(gg[i].y & 0xffffu), v[3] * bf2f(gg[i].y >> 16));
;         *(u32x2*)(op + (size_t)i * 2 * 3072) = w;
;     }
	v_pk_mul_f32 v[22:23], v[20:21], v[20:21]
	v_pk_mul_f32 v[24:25], v[18:19], v[18:19]
	s_nop 0
	v_pk_mov_b32 v[26:27], v[24:25], v[22:23] op_sel:[1,0]
	v_mov_b32_e32 v25, v23
	v_pk_add_f32 v[22:23], v[26:27], v[24:25]
	s_nop 0
	v_add_f32_e32 v22, v22, v23
	ds_bpermute_b32 v23, v38, v22
	s_waitcnt lgkmcnt(0)
	v_add_f32_e32 v22, v22, v23
	ds_bpermute_b32 v23, v39, v22
	s_waitcnt lgkmcnt(0)
	v_add_f32_e32 v22, v22, v23
	ds_bpermute_b32 v23, v40, v22
	s_waitcnt lgkmcnt(0)
	v_add_f32_e32 v22, v22, v23
	ds_bpermute_b32 v23, v41, v22
	s_waitcnt lgkmcnt(0)
	v_add_f32_e32 v22, v22, v23
	ds_bpermute_b32 v23, v42, v22
	s_waitcnt lgkmcnt(0)
	v_add_f32_e32 v22, v22, v23
	v_fmamk_f32 v22, v22, 0x3c000000, v178
	v_cmp_gt_f32_e32 vcc, s2, v22
	v_mul_f32_e32 v23, 0x4b800000, v22
	s_nop 0
	v_cndmask_b32_e32 v22, v22, v23, vcc
	v_rsq_f32_e32 v22, v22
	s_nop 0
	v_mul_f32_e32 v23, 0x45800000, v22
	v_cndmask_b32_e32 v22, v22, v23, vcc
	v_pk_mul_f32 v[18:19], v[18:19], v[22:23] op_sel_hi:[1,0]
	v_pk_mul_f32 v[20:21], v[20:21], v[22:23] op_sel_hi:[1,0]
	v_pk_mul_f32 v[18:19], v[8:9], v[18:19]
	v_lshlrev_b32_e32 v22, 16, v16
	v_and_b32_e32 v16, 0xffff0000, v16
	v_mul_f32_e32 v18, v18, v22
	v_mul_f32_e32 v16, v19, v16
	v_pk_mul_f32 v[20:21], v[6:7], v[20:21]
	v_cvt_pk_bf16_f32 v16, v18, v16
	v_lshlrev_b32_e32 v18, 16, v17
	v_and_b32_e32 v17, 0xffff0000, v17
	v_mul_f32_e32 v18, v20, v18
	v_mul_f32_e32 v17, v21, v17
	v_cvt_pk_bf16_f32 v17, v18, v17
	v_add_co_u32_e32 v18, vcc, s92, v0
	s_nop 1
	v_addc_co_u32_e32 v19, vcc, 0, v1, vcc
	global_store_dwordx2 v[18:19], v[16:17], off
	ds_read_b128 v[16:19], v43 offset:11616
	s_waitcnt lgkmcnt(0)
	v_pk_mul_f32 v[20:21], v[18:19], v[18:19]
	v_pk_mul_f32 v[22:23], v[16:17], v[16:17]
	s_nop 0
	v_pk_mov_b32 v[24:25], v[22:23], v[20:21] op_sel:[1,0]
	v_mov_b32_e32 v23, v21
	v_pk_add_f32 v[20:21], v[24:25], v[22:23]
	s_nop 0
	v_add_f32_e32 v20, v20, v21
	ds_bpermute_b32 v21, v38, v20
	s_waitcnt lgkmcnt(0)
	v_add_f32_e32 v20, v20, v21
	ds_bpermute_b32 v21, v39, v20
	s_waitcnt lgkmcnt(0)
	v_add_f32_e32 v20, v20, v21
	ds_bpermute_b32 v21, v40, v20
	s_waitcnt lgkmcnt(0)
	v_add_f32_e32 v20, v20, v21
	ds_bpermute_b32 v21, v41, v20
	s_waitcnt lgkmcnt(0)
	v_add_f32_e32 v20, v20, v21
	ds_bpermute_b32 v21, v42, v20
	s_waitcnt lgkmcnt(0)
	v_add_f32_e32 v20, v20, v21
	v_fmamk_f32 v20, v20, 0x3c000000, v178
	v_cmp_gt_f32_e32 vcc, s2, v20
	v_mul_f32_e32 v21, 0x4b800000, v20
	s_nop 0
	v_cndmask_b32_e32 v20, v20, v21, vcc
	v_rsq_f32_e32 v20, v20
	s_nop 0
	v_mul_f32_e32 v21, 0x45800000, v20
	v_cndmask_b32_e32 v20, v20, v21, vcc
	v_pk_mul_f32 v[16:17], v[16:17], v[20:21] op_sel_hi:[1,0]
	v_pk_mul_f32 v[18:19], v[18:19], v[20:21] op_sel_hi:[1,0]
	v_pk_mul_f32 v[16:17], v[8:9], v[16:17]
	v_lshlrev_b32_e32 v20, 16, v14
	v_and_b32_e32 v14, 0xffff0000, v14
	v_mul_f32_e32 v16, v16, v20
	v_mul_f32_e32 v14, v17, v14
	v_pk_mul_f32 v[18:19], v[6:7], v[18:19]
	v_cvt_pk_bf16_f32 v14, v16, v14
	v_lshlrev_b32_e32 v16, 16, v15
	v_and_b32_e32 v15, 0xffff0000, v15
	v_mul_f32_e32 v16, v18, v16
	v_mul_f32_e32 v15, v19, v15
	v_cvt_pk_bf16_f32 v15, v16, v15
	v_add_co_u32_e32 v16, vcc, s3, v0
	s_nop 1
	v_addc_co_u32_e32 v17, vcc, 0, v1, vcc
	global_store_dwordx2 v[16:17], v[14:15], off
	ds_read_b128 v[14:17], v43 offset:12672
	s_waitcnt lgkmcnt(0)
	v_pk_mul_f32 v[18:19], v[16:17], v[16:17]
	v_pk_mul_f32 v[20:21], v[14:15], v[14:15]
	s_nop 0
	v_pk_mov_b32 v[22:23], v[20:21], v[18:19] op_sel:[1,0]
	v_mov_b32_e32 v21, v19
	v_pk_add_f32 v[18:19], v[22:23], v[20:21]
	s_nop 0
	v_add_f32_e32 v18, v18, v19
	ds_bpermute_b32 v19, v38, v18
	s_waitcnt lgkmcnt(0)
	v_add_f32_e32 v18, v18, v19
	ds_bpermute_b32 v19, v39, v18
	s_waitcnt lgkmcnt(0)
	v_add_f32_e32 v18, v18, v19
	ds_bpermute_b32 v19, v40, v18
	s_waitcnt lgkmcnt(0)
	v_add_f32_e32 v18, v18, v19
	ds_bpermute_b32 v19, v41, v18
	s_waitcnt lgkmcnt(0)
	v_add_f32_e32 v18, v18, v19
	ds_bpermute_b32 v19, v42, v18
	s_waitcnt lgkmcnt(0)
	v_add_f32_e32 v18, v18, v19
	v_fmamk_f32 v18, v18, 0x3c000000, v178
	v_cmp_gt_f32_e32 vcc, s2, v18
	v_mul_f32_e32 v19, 0x4b800000, v18
	s_nop 0
	v_cndmask_b32_e32 v18, v18, v19, vcc
	v_rsq_f32_e32 v18, v18
	s_nop 0
	v_mul_f32_e32 v19, 0x45800000, v18
	v_cndmask_b32_e32 v18, v18, v19, vcc
	v_pk_mul_f32 v[14:15], v[14:15], v[18:19] op_sel_hi:[1,0]
	v_pk_mul_f32 v[16:17], v[16:17], v[18:19] op_sel_hi:[1,0]
	v_pk_mul_f32 v[14:15], v[8:9], v[14:15]
	v_lshlrev_b32_e32 v18, 16, v12
	v_and_b32_e32 v12, 0xffff0000, v12
	v_mul_f32_e32 v14, v14, v18
	v_mul_f32_e32 v12, v15, v12
	v_pk_mul_f32 v[16:17], v[6:7], v[16:17]
	v_cvt_pk_bf16_f32 v12, v14, v12
	v_lshlrev_b32_e32 v14, 16, v13
	v_and_b32_e32 v13, 0xffff0000, v13
	v_mul_f32_e32 v14, v16, v14
	v_mul_f32_e32 v13, v17, v13
	v_cvt_pk_bf16_f32 v13, v14, v13
	v_add_co_u32_e32 v14, vcc, s91, v0
	s_nop 1
	v_addc_co_u32_e32 v15, vcc, 0, v1, vcc
	global_store_dwordx2 v[14:15], v[12:13], off
	ds_read_b128 v[12:15], v43 offset:13728
	s_waitcnt lgkmcnt(0)
	v_pk_mul_f32 v[16:17], v[14:15], v[14:15]
	v_pk_mul_f32 v[18:19], v[12:13], v[12:13]
	s_nop 0
	v_pk_mov_b32 v[20:21], v[18:19], v[16:17] op_sel:[1,0]
	v_mov_b32_e32 v19, v17
	v_pk_add_f32 v[16:17], v[20:21], v[18:19]
	s_nop 0
	v_add_f32_e32 v16, v16, v17
	ds_bpermute_b32 v17, v38, v16
	s_waitcnt lgkmcnt(0)
	v_add_f32_e32 v16, v16, v17
	ds_bpermute_b32 v17, v39, v16
	s_waitcnt lgkmcnt(0)
	v_add_f32_e32 v16, v16, v17
	ds_bpermute_b32 v17, v40, v16
	s_waitcnt lgkmcnt(0)
	v_add_f32_e32 v16, v16, v17
	ds_bpermute_b32 v17, v41, v16
	s_waitcnt lgkmcnt(0)
	v_add_f32_e32 v16, v16, v17
	ds_bpermute_b32 v17, v42, v16
	s_waitcnt lgkmcnt(0)
; #define LAS __attribute__((address_space(3)))
; __device__ __forceinline__ float bf2f(unsigned h) { return __uint_as_float(h << 16); }
; __device__ __forceinline__ unsigned cvt_pk_bf16(float lo, float hi) { unsigned r; asm volatile("v_cvt_pk_bf16_f32 %0, %1, %2" : "=v"(r) : "v"(lo), "v"(hi)); return r; }
; #define VMW0() asm volatile("s_waitcnt vmcnt(0)" ::: "memory")
; template <int DQK, bool DOUBLE> ...
;     ...
;     { const bf16_t* Qw = Q + (size_t)(wid * 32 + r32) * ldq + hi * 8;
; #pragma unroll
;       for (int d0 = 0; d0 < DQK / 16; ++d0) qr[d0] = *(const bf16x8*)(Qw + d0 * 16); }
; #pragma unroll
;     for (int d = 0; d < 4; ++d) o[d] = f32x16{};
;     l_reg = 0.f;
;     int vrow[2], vcol[2], krow[NLD], kcol[NLD];
; #pragma unroll
;     for (int i = 0; i < 2; ++i) { const int q = tid + 512 * i, sub = q >> 5, within = q & 31, kk = (sub >> 2) * 8 + (within >> 2);
;         vrow[i] = kk; vcol[i] = (sub & 3) * 32 + (within & 3) * 8; }
; #pragma unroll
;     for (int i = 0; i < NLD; ++i) { const int q = tid + 512 * i, row = q / NCH, chp = q % NCH; const int x = (RB == 256) ? (row & 15) : ((row >> 1) & 7);
;         krow[i] = row; kcol[i] = (chp ^ x) * 8; }
;     const unsigned vb0 = (unsigned)(uintptr_t)V_lds + v_rd_base(lane);
;     int ka[8];
; #pragma unroll
;     for (int q = 0; q < 8; ++q) ka[q] = kswz<RB>(r32, q * 32 + hi * 16);
;     ...
;     bf16x8 pa0, pa1, pa2, pa3;
;     __syncthreads();
;     DMA(0, 0); DMA(1, 1); VMW0(); __syncthreads();
; template <bool SUBLN>
; __device__ __forceinline__ void attn_out(const AttnBufs& T, f32x16 (&o)[4], int type, int h, size_t orow0, LAS char* lds, int wid, int lane, int r32, int hi) {
;     ...
;     for (int i = 0; i < 16; ++i) {
;         f32x4 v = *(const LAS f32x4*)(stg + (2 * i + rr) * 132 + c4);
;         if (SUBLN) {
;             float s = (v[0] * v[0] + v[1] * v[1]) + (v[2] * v[2] + v[3] * v[3]);
;             s += __shfl_xor(s, 1); s += __shfl_xor(s, 2); s += __shfl_xor(s, 4); s += __shfl_xor(s, 8); s += __shfl_xor(s, 16);
;             v = v * (rsqrtf(s * (1.f / 128.f) + EPS)) * wsub;
;         }
;         u32x2 w; w.x = cvt_pk_bf16(v[0] * bf2f(gg[i].x & 0xffffu), v[1] * bf2f(gg[i].x >> 16)); w.y = cvt_pk_bf16(v[2] * bf2f(gg[i].y & 0xffffu), v[3] * bf2f(gg[i].y >> 16));
;         *(u32x2*)(op + (size_t)i * 2 * 3072) = w;
;     }
	v_add_f32_e32 v16, v16, v17
	v_fmamk_f32 v16, v16, 0x3c000000, v178
	v_cmp_gt_f32_e32 vcc, s2, v16
	v_mul_f32_e32 v17, 0x4b800000, v16
	s_nop 0
	v_cndmask_b32_e32 v16, v16, v17, vcc
	v_rsq_f32_e32 v16, v16
	s_nop 0
	v_mul_f32_e32 v17, 0x45800000, v16
	v_cndmask_b32_e32 v16, v16, v17, vcc
	v_pk_mul_f32 v[12:13], v[12:13], v[16:17] op_sel_hi:[1,0]
	v_pk_mul_f32 v[14:15], v[14:15], v[16:17] op_sel_hi:[1,0]
	v_pk_mul_f32 v[12:13], v[8:9], v[12:13]
	v_lshlrev_b32_e32 v16, 16, v10
	v_and_b32_e32 v10, 0xffff0000, v10
	v_mul_f32_e32 v12, v12, v16
	v_mul_f32_e32 v10, v13, v10
	v_pk_mul_f32 v[14:15], v[6:7], v[14:15]
	v_cvt_pk_bf16_f32 v10, v12, v10
	v_lshlrev_b32_e32 v12, 16, v11
	v_and_b32_e32 v11, 0xffff0000, v11
	v_mul_f32_e32 v12, v14, v12
	v_mul_f32_e32 v11, v15, v11
	v_cvt_pk_bf16_f32 v11, v12, v11
	v_add_co_u32_e32 v12, vcc, s33, v0
	s_nop 1
	v_addc_co_u32_e32 v13, vcc, 0, v1, vcc
	global_store_dwordx2 v[12:13], v[10:11], off
	ds_read_b128 v[10:13], v43 offset:14784
	s_waitcnt lgkmcnt(0)
	v_pk_mul_f32 v[14:15], v[12:13], v[12:13]
	v_pk_mul_f32 v[16:17], v[10:11], v[10:11]
	s_nop 0
	v_pk_mov_b32 v[18:19], v[16:17], v[14:15] op_sel:[1,0]
	v_mov_b32_e32 v17, v15
	v_pk_add_f32 v[14:15], v[18:19], v[16:17]
	s_nop 0
	v_add_f32_e32 v14, v14, v15
	ds_bpermute_b32 v15, v38, v14
	s_waitcnt lgkmcnt(0)
	v_add_f32_e32 v14, v14, v15
	ds_bpermute_b32 v15, v39, v14
	s_waitcnt lgkmcnt(0)
	v_add_f32_e32 v14, v14, v15
	ds_bpermute_b32 v15, v40, v14
	s_waitcnt lgkmcnt(0)
	v_add_f32_e32 v14, v14, v15
	ds_bpermute_b32 v15, v41, v14
	s_waitcnt lgkmcnt(0)
	v_add_f32_e32 v14, v14, v15
	ds_bpermute_b32 v15, v42, v14
	s_waitcnt lgkmcnt(0)
	v_add_f32_e32 v14, v14, v15
	v_fmamk_f32 v14, v14, 0x3c000000, v178
	v_cmp_gt_f32_e32 vcc, s2, v14
	v_mul_f32_e32 v15, 0x4b800000, v14
	s_nop 0
	v_cndmask_b32_e32 v14, v14, v15, vcc
	v_rsq_f32_e32 v14, v14
	s_nop 0
	v_mul_f32_e32 v15, 0x45800000, v14
	v_cndmask_b32_e32 v14, v14, v15, vcc
	v_pk_mul_f32 v[10:11], v[10:11], v[14:15] op_sel_hi:[1,0]
	v_pk_mul_f32 v[12:13], v[12:13], v[14:15] op_sel_hi:[1,0]
	v_pk_mul_f32 v[10:11], v[8:9], v[10:11]
	v_lshlrev_b32_e32 v14, 16, v4
	v_and_b32_e32 v4, 0xffff0000, v4
	v_mul_f32_e32 v10, v10, v14
	v_mul_f32_e32 v4, v11, v4
	v_pk_mul_f32 v[12:13], v[6:7], v[12:13]
	v_cvt_pk_bf16_f32 v4, v10, v4
	v_lshlrev_b32_e32 v10, 16, v5
	v_and_b32_e32 v5, 0xffff0000, v5
	v_mul_f32_e32 v10, v12, v10
	v_mul_f32_e32 v5, v13, v5
	v_cvt_pk_bf16_f32 v5, v10, v5
	v_add_co_u32_e32 v10, vcc, s94, v0
	s_nop 1
	v_addc_co_u32_e32 v11, vcc, 0, v1, vcc
	global_store_dwordx2 v[10:11], v[4:5], off
	ds_read_b128 v[10:13], v43 offset:15840
	s_waitcnt lgkmcnt(0)
	v_pk_mul_f32 v[4:5], v[12:13], v[12:13]
	v_pk_mul_f32 v[14:15], v[10:11], v[10:11]
	s_nop 0
	v_pk_mov_b32 v[16:17], v[14:15], v[4:5] op_sel:[1,0]
	v_mov_b32_e32 v15, v5
	v_pk_add_f32 v[4:5], v[16:17], v[14:15]
	s_nop 0
	v_add_f32_e32 v4, v4, v5
	ds_bpermute_b32 v5, v38, v4
	s_waitcnt lgkmcnt(0)
	v_add_f32_e32 v4, v4, v5
	ds_bpermute_b32 v5, v39, v4
	s_waitcnt lgkmcnt(0)
	v_add_f32_e32 v4, v4, v5
	ds_bpermute_b32 v5, v40, v4
	s_waitcnt lgkmcnt(0)
	v_add_f32_e32 v4, v4, v5
	ds_bpermute_b32 v5, v41, v4
	s_waitcnt lgkmcnt(0)
	v_add_f32_e32 v4, v4, v5
	ds_bpermute_b32 v5, v42, v4
	s_waitcnt lgkmcnt(0)
	v_add_f32_e32 v4, v4, v5
	v_fmamk_f32 v4, v4, 0x3c000000, v178
	v_cmp_gt_f32_e32 vcc, s2, v4
	v_mul_f32_e32 v5, 0x4b800000, v4
	s_nop 0
	v_cndmask_b32_e32 v4, v4, v5, vcc
	v_rsq_f32_e32 v4, v4
	s_nop 0
	v_mul_f32_e32 v5, 0x45800000, v4
	v_cndmask_b32_e32 v4, v4, v5, vcc
	v_pk_mul_f32 v[10:11], v[10:11], v[4:5] op_sel_hi:[1,0]
	v_pk_mul_f32 v[4:5], v[12:13], v[4:5] op_sel_hi:[1,0]
	s_nop 0
	v_pk_mul_f32 v[4:5], v[6:7], v[4:5]
	v_pk_mul_f32 v[6:7], v[8:9], v[10:11]
	v_lshlrev_b32_e32 v8, 16, v2
	v_and_b32_e32 v2, 0xffff0000, v2
	v_mul_f32_e32 v6, v6, v8
	v_mul_f32_e32 v2, v7, v2
	v_cvt_pk_bf16_f32 v2, v6, v2
	v_lshlrev_b32_e32 v6, 16, v3
	v_and_b32_e32 v3, 0xffff0000, v3
	v_mul_f32_e32 v3, v5, v3
	v_mul_f32_e32 v4, v4, v6
	v_cvt_pk_bf16_f32 v3, v4, v3
.LBB0_171:
	s_and_b64 vcc, exec, s[48:49]
	s_cbranch_vccz .LBB0_108
	s_lshl_b64 s[2:3], s[30:31], 11
	v_readlane_b32 s4, v251, 26
	v_readlane_b32 s5, v251, 27
	s_add_u32 s4, s4, s2
	s_addc_u32 s5, s5, s3
	s_lshl_b32 s48, s72, 7
	s_ashr_i32 s49, s48, 31
	s_lshl_b64 s[2:3], s[48:49], 1
	s_add_u32 s2, s4, s2
	s_addc_u32 s3, s5, s3
	s_lshl_b32 s4, s72, 5
	s_and_b32 s4, s4, 0xffffff80
	s_ashr_i32 s5, s4, 31
	s_lshl_b64 s[4:5], s[4:5], 1
	v_readlane_b32 s20, v251, 28
	v_readlane_b32 s21, v251, 29
	s_add_u32 s50, s20, s4
	s_addc_u32 s51, s21, s5
	v_readlane_b32 s20, v251, 30
	v_readlane_b32 s21, v251, 31
	s_add_u32 s56, s20, s4
	v_readfirstlane_b32 s4, v164
	s_addc_u32 s57, s21, s5
	s_ashr_i32 s4, s4, 6
	v_lshl_or_b32 v2, s4, 5, v181
	v_bfi_b32 v146, -8, v195, v196
	v_ashrrev_i32_e32 v3, 31, v2
	s_ashr_i32 s47, s46, 31
	v_ashrrev_i32_e32 v147, 31, v146
	v_lshlrev_b64 v[2:3], 11, v[2:3]
	v_lshl_add_u64 v[6:7], v[146:147], 0, s[46:47]
	v_lshl_add_u64 v[2:3], s[2:3], 0, v[2:3]
	v_lshrrev_b32_e32 v1, 28, v165
	s_lshl_b32 s2, s4, 10
	v_lshlrev_b64 v[6:7], 9, v[6:7]
	v_mov_b32_e32 v145, v177
	v_bfi_b32 v148, -8, v197, v196
	v_add_u32_e32 v1, v164, v1
	s_add_i32 s3, s2, 0
	v_lshl_add_u64 v[6:7], s[56:57], 0, v[6:7]
	v_lshlrev_b32_e32 v80, 1, v193
	v_mov_b32_e32 v81, v177
	v_lshl_add_u64 v[2:3], v[2:3], 0, v[144:145]
	v_ashrrev_i32_e32 v150, 4, v1
	v_and_b32_e32 v1, 0x1ffffff0, v1
	v_lshl_add_u64 v[6:7], v[6:7], 0, v[80:81]
	s_mov_b32 m0, s3
	v_ashrrev_i32_e32 v149, 31, v148
	global_load_dword v0, v177, s[14:15] offset:4
	global_load_dwordx4 v[112:115], v[2:3], off
	global_load_dwordx4 v[116:119], v[2:3], off offset:32
	global_load_dwordx4 v[120:123], v[2:3], off offset:64
	global_load_dwordx4 v[124:127], v[2:3], off offset:96
	s_waitcnt lgkmcnt(0)
	global_load_dwordx4 v[128:131], v[2:3], off offset:128
	global_load_dwordx4 v[132:135], v[2:3], off offset:160
	global_load_dwordx4 v[136:139], v[2:3], off offset:192
	global_load_dwordx4 v[140:143], v[2:3], off offset:224
	v_sub_u32_e32 v1, v164, v1
	s_barrier
; #define LAS __attribute__((address_space(3)))
; #define VMW0() asm volatile("s_waitcnt vmcnt(0)" ::: "memory")
; template <int DQK>
; __device__ __forceinline__ void qkt(f32x16& p0, f32x16& p1, const LAS char* Ks, const bf16x8 (&qr)[DQK / 16], const int (&ka)[8], float nMB) {
;     constexpr int RB = DQK * 2, NA = (RB == 256) ? 8 : 4;
; #pragma unroll
;     for (int r = 0; r < 16; ++r) { p0[r] = nMB; p1[r] = nMB; }
; #pragma unroll
;     for (int d0 = 0; d0 < DQK / 16; ++d0) {
;         const LAS char* a = Ks + ka[d0 % NA] + (d0 / NA) * (NA * 32);
;         const bf16x8 b0 = *(const LAS bf16x8*)(a);
;         const bf16x8 b1 = *(const LAS bf16x8*)(a + 32 * RB);
;         p0 = __builtin_amdgcn_mfma_f32_32x32x16_bf16(b0, qr[d0], p0, 0, 0, 0);
;         p1 = __builtin_amdgcn_mfma_f32_32x32x16_bf16(b1, qr[d0], p1, 0, 0, 0); }
; }
; template <int DQK, bool DOUBLE> ...
;     ...
;     bf16x8 pa0, pa1, pa2, pa3;
;     __syncthreads();
;     DMA(0, 0); DMA(1, 1); VMW0(); __syncthreads();
	global_load_lds_dwordx4 v[6:7], off
	v_lshl_add_u64 v[6:7], v[148:149], 0, s[46:47]
	v_bitop3_b32 v1, v150, v1, 15 bitop3:0x6c
	v_lshlrev_b64 v[6:7], 9, v[6:7]
	v_lshlrev_b32_e32 v2, 3, v1
	v_ashrrev_i32_e32 v1, 31, v194
	v_lshl_add_u64 v[6:7], s[56:57], 0, v[6:7]
	s_add_i32 s21, s3, 0x2000
	v_lshrrev_b32_e32 v1, 28, v1
	v_lshl_add_u64 v[6:7], v[6:7], 0, v[80:81]
	s_mov_b32 m0, s21
	v_ashrrev_i32_e32 v151, 31, v150
	v_add_u32_e32 v1, v194, v1
	global_load_lds_dwordx4 v[6:7], off
	v_lshl_add_u64 v[6:7], v[150:151], 0, s[46:47]
	v_ashrrev_i32_e32 v152, 4, v1
	v_and_b32_e32 v1, 0x1ffffff0, v1
	v_lshlrev_b64 v[6:7], 9, v[6:7]
	v_ashrrev_i32_e32 v3, 31, v2
	v_sub_u32_e32 v1, v194, v1
	s_add_i32 s20, s3, 0xc000
	v_lshl_add_u64 v[6:7], s[50:51], 0, v[6:7]
	v_lshlrev_b64 v[82:83], 1, v[2:3]
	v_bitop3_b32 v1, v152, v1, 15 bitop3:0x6c
	v_lshl_add_u64 v[2:3], v[6:7], 0, v[82:83]
	s_mov_b32 m0, s20
	v_ashrrev_i32_e32 v153, 31, v152
	v_lshlrev_b32_e32 v4, 3, v1
	global_load_lds_dwordx4 v[2:3], off
	v_lshl_add_u64 v[2:3], v[152:153], 0, s[46:47]
	v_lshlrev_b64 v[2:3], 9, v[2:3]
	v_ashrrev_i32_e32 v5, 31, v4
	v_lshl_add_u64 v[2:3], s[50:51], 0, v[2:3]
	v_lshlrev_b64 v[84:85], 1, v[4:5]
	s_add_i32 s31, s3, 0xe000
	s_add_i32 s4, s45, 0x4040
	v_lshl_add_u64 v[2:3], v[2:3], 0, v[84:85]
	s_mov_b32 m0, s31
	s_ashr_i32 s5, s4, 31
	global_load_lds_dwordx4 v[2:3], off
	v_lshl_add_u64 v[2:3], v[146:147], 0, s[4:5]
	v_lshlrev_b64 v[2:3], 9, v[2:3]
	v_lshl_add_u64 v[2:3], s[56:57], 0, v[2:3]
	s_add_i32 m0, s3, 0x4000
	v_lshl_add_u64 v[2:3], v[2:3], 0, v[80:81]
	global_load_lds_dwordx4 v[2:3], off
	v_lshl_add_u64 v[2:3], v[148:149], 0, s[4:5]
	v_lshlrev_b64 v[2:3], 9, v[2:3]
	v_lshl_add_u64 v[2:3], s[56:57], 0, v[2:3]
	v_lshl_add_u64 v[2:3], v[2:3], 0, v[80:81]
	s_add_i32 m0, s3, 0x6000
	v_lshlrev_b32_e32 v1, 8, v181
	global_load_lds_dwordx4 v[2:3], off
	v_lshl_add_u64 v[2:3], v[150:151], 0, s[4:5]
	v_lshlrev_b64 v[2:3], 9, v[2:3]
	v_lshl_add_u64 v[2:3], s[50:51], 0, v[2:3]
	s_add_i32 m0, s3, 0x12000
	v_lshl_add_u64 v[2:3], v[2:3], 0, v[82:83]
	global_load_lds_dwordx4 v[2:3], off
	v_lshl_add_u64 v[2:3], v[152:153], 0, s[4:5]
	v_lshlrev_b64 v[2:3], 9, v[2:3]
	v_lshl_add_u64 v[2:3], s[50:51], 0, v[2:3]
	s_add_i32 s4, s45, 0x4080
	v_lshl_add_u64 v[2:3], v[2:3], 0, v[84:85]
	s_add_i32 m0, s3, 0x14000
	s_ashr_i32 s5, s4, 31
	global_load_lds_dwordx4 v[2:3], off
	v_lshl_add_u64 v[2:3], v[146:147], 0, s[4:5]
	v_lshlrev_b64 v[2:3], 9, v[2:3]
	v_lshl_add_u64 v[2:3], s[56:57], 0, v[2:3]
	s_add_i32 m0, s3, 0x8000
	v_lshl_add_u64 v[2:3], v[2:3], 0, v[80:81]
	s_waitcnt vmcnt(0)
	s_waitcnt vmcnt(0) lgkmcnt(0)
	s_barrier
	global_load_lds_dwordx4 v[2:3], off
	v_lshl_add_u64 v[2:3], v[148:149], 0, s[4:5]
	v_lshlrev_b64 v[2:3], 9, v[2:3]
	v_lshl_add_u64 v[2:3], s[56:57], 0, v[2:3]
	v_lshl_add_u64 v[2:3], v[2:3], 0, v[80:81]
	s_add_i32 m0, s3, 0xa000
	s_movk_i32 s33, 0x118
	global_load_lds_dwordx4 v[2:3], off
	v_lshl_add_u64 v[2:3], v[150:151], 0, s[4:5]
	v_lshlrev_b64 v[2:3], 9, v[2:3]
	v_lshl_add_u64 v[2:3], s[50:51], 0, v[2:3]
	s_add_i32 m0, s3, 0x18000
	v_lshl_add_u64 v[2:3], v[2:3], 0, v[82:83]
	global_load_lds_dwordx4 v[2:3], off
	v_lshl_add_u64 v[2:3], v[152:153], 0, s[4:5]
	v_lshlrev_b64 v[2:3], 9, v[2:3]
	v_lshl_add_u64 v[2:3], s[50:51], 0, v[2:3]
	v_lshl_add_u64 v[2:3], v[2:3], 0, v[84:85]
	s_add_i32 m0, s3, 0x1a000
	s_mov_b32 s5, 1
	global_load_lds_dwordx4 v[2:3], off
	v_lshlrev_b32_e32 v2, 4, v181
	v_and_b32_e32 v2, 0xf0, v2
	v_or_b32_e32 v3, 0x80, v144
	v_bitop3_b32 v166, v3, v1, v2 bitop3:0xde
	v_or_b32_e32 v3, 0xa0, v144
	v_bitop3_b32 v167, v3, v1, v2 bitop3:0xde
	v_or_b32_e32 v3, 0xc0, v144
	v_bitop3_b32 v168, v3, v1, v2 bitop3:0xde
	v_or_b32_e32 v3, 0xe0, v144
	v_bitop3_b32 v145, v144, v1, v2 bitop3:0xde
	v_bitop3_b32 v161, v187, v1, v2 bitop3:0xde
	v_bitop3_b32 v164, v191, v1, v2 bitop3:0xde
	v_bitop3_b32 v165, v192, v1, v2 bitop3:0xde
	v_bitop3_b32 v169, v3, v1, v2 bitop3:0xde
	v_and_b32_e32 v1, 32, v175
	v_and_or_b32 v16, v174, s33, v1
	s_mov_b32 s4, 2
	v_mov_b32_e32 v1, v0
	v_mov_b32_e32 v2, v0
	v_mov_b32_e32 v3, v0
	v_mov_b32_e32 v4, v0
	v_mov_b32_e32 v5, v0
	v_mov_b32_e32 v6, v0
	v_mov_b32_e32 v7, v0
	v_mov_b32_e32 v8, v0
	v_mov_b32_e32 v9, v0
	v_mov_b32_e32 v10, v0
	v_mov_b32_e32 v11, v0
	v_mov_b32_e32 v12, v0
	v_mov_b32_e32 v13, v0
	v_mov_b32_e32 v14, v0
	v_mov_b32_e32 v15, v0
	v_add3_u32 v170, v173, 0, v16
	s_add_i32 s46, s45, 0x40c0
	v_add_u32_e32 v20, 0, v145
	ds_read_b128 v[16:19], v20 offset:49152
	ds_read_b128 v[48:51], v20 offset:57344
	v_add_u32_e32 v52, 0, v161
	s_waitcnt lgkmcnt(0)
	v_mfma_f32_32x32x16_bf16 v[32:47], v[16:19], v[112:115], v[0:15]
	v_mfma_f32_32x32x16_bf16 v[16:31], v[48:51], v[112:115], v[0:15]
	ds_read_b128 v[48:51], v52 offset:49152
	ds_read_b128 v[52:55], v52 offset:57344
	s_waitcnt lgkmcnt(0)
	v_mfma_f32_32x32x16_bf16 v[32:47], v[48:51], v[116:119], v[32:47]
	v_mfma_f32_32x32x16_bf16 v[16:31], v[52:55], v[116:119], v[16:31]
	v_add_u32_e32 v52, 0, v164
	ds_read_b128 v[48:51], v52 offset:49152
	ds_read_b128 v[52:55], v52 offset:57344
	s_waitcnt lgkmcnt(0)
	v_mfma_f32_32x32x16_bf16 v[32:47], v[48:51], v[120:123], v[32:47]
	v_mfma_f32_32x32x16_bf16 v[16:31], v[52:55], v[120:123], v[16:31]
	v_add_u32_e32 v52, 0, v165
	ds_read_b128 v[48:51], v52 offset:49152
	ds_read_b128 v[52:55], v52 offset:57344
	s_waitcnt lgkmcnt(0)
	v_mfma_f32_32x32x16_bf16 v[32:47], v[48:51], v[124:127], v[32:47]
	v_mfma_f32_32x32x16_bf16 v[16:31], v[52:55], v[124:127], v[16:31]
	v_add_u32_e32 v52, 0, v166
	ds_read_b128 v[48:51], v52 offset:49152
	ds_read_b128 v[52:55], v52 offset:57344
	s_waitcnt lgkmcnt(0)
; template <int D0> __device__ __forceinline__ void pv_one(f32x16& od, unsigned vb, bf16x8 pa0, bf16x8 pa1, bf16x8 pa2, bf16x8 pa3) {
;     const s16x4 l0 = tr_read<v_rd_off(D0, 0, 0)>(vb), h0 = tr_read<v_rd_off(D0, 0, 1)>(vb), l1 = tr_read<v_rd_off(D0, 1, 0)>(vb), h1 = tr_read<v_rd_off(D0, 1, 1)>(vb);
;     const s16x4 l2 = tr_read<v_rd_off(D0, 2, 0)>(vb), h2 = tr_read<v_rd_off(D0, 2, 1)>(vb), l3 = tr_read<v_rd_off(D0, 3, 0)>(vb), h3 = tr_read<v_rd_off(D0, 3, 1)>(vb);
;     asm volatile("s_waitcnt lgkmcnt(0)" ::: "memory"); SBAR();
;     ...
;     od = __builtin_amdgcn_mfma_f32_32x32x16_bf16(pa0, PK(l0, h0), od, 0, 0, 0);
;     od = __builtin_amdgcn_mfma_f32_32x32x16_bf16(pa1, PK(l1, h1), od, 0, 0, 0);
;     od = __builtin_amdgcn_mfma_f32_32x32x16_bf16(pa2, PK(l2, h2), od, 0, 0, 0);
;     od = __builtin_amdgcn_mfma_f32_32x32x16_bf16(pa3, PK(l3, h3), od, 0, 0, 0);
;     ...
; }
; __device__ __forceinline__ void pv_d0(f32x16 (&o)[4], unsigned vb, bf16x8 pa0, bf16x8 pa1, bf16x8 pa2, bf16x8 pa3) {
; __device__ __forceinline__ void partialSM(f32x16& p0, f32x16& p1) {
; #pragma unroll
;     for (int r = 0; r < 16; ++r) p0[r] = __builtin_amdgcn_exp2f(p0[r]);
; }
; __device__ __forceinline__ void finishSM(f32x16& p0, f32x16& p1, float& l_reg, bf16x8& pa0, bf16x8& pa1, bf16x8& pa2, bf16x8& pa3) {
; #pragma unroll
;     for (int r = 0; r < 16; ++r) p1[r] = __builtin_amdgcn_exp2f(p1[r]);
;     float ps = 0;
; #pragma unroll
;     for (int r = 0; r < 16; ++r) ps += p0[r];
; #pragma unroll
;     for (int r = 0; r < 16; ++r) ps += p1[r];
;     l_reg += ps;
;     ...
;     PK8(p0, 0, pa0); PK8(p0, 8, pa1); PK8(p1, 0, pa2); PK8(p1, 8, pa3);
;     ...
; }
; template <int DQK>
; __device__ __forceinline__ void qkt(f32x16& p0, f32x16& p1, const LAS char* Ks, const bf16x8 (&qr)[DQK / 16], const int (&ka)[8], float nMB) {
;     constexpr int RB = DQK * 2, NA = (RB == 256) ? 8 : 4;
; #pragma unroll
;     for (int r = 0; r < 16; ++r) { p0[r] = nMB; p1[r] = nMB; }
; #pragma unroll
;     for (int d0 = 0; d0 < DQK / 16; ++d0) {
;         const LAS char* a = Ks + ka[d0 % NA] + (d0 / NA) * (NA * 32);
;         const bf16x8 b0 = *(const LAS bf16x8*)(a);
;         const bf16x8 b1 = *(const LAS bf16x8*)(a + 32 * RB);
;         p0 = __builtin_amdgcn_mfma_f32_32x32x16_bf16(b0, qr[d0], p0, 0, 0, 0);
;         p1 = __builtin_amdgcn_mfma_f32_32x32x16_bf16(b1, qr[d0], p1, 0, 0, 0); }
; }
	v_mfma_f32_32x32x16_bf16 v[32:47], v[48:51], v[128:131], v[32:47]
	v_mfma_f32_32x32x16_bf16 v[16:31], v[52:55], v[128:131], v[16:31]
	v_add_u32_e32 v52, 0, v167
	ds_read_b128 v[48:51], v52 offset:49152
	ds_read_b128 v[52:55], v52 offset:57344
	s_waitcnt lgkmcnt(0)
	v_mfma_f32_32x32x16_bf16 v[32:47], v[48:51], v[132:135], v[32:47]
	v_mfma_f32_32x32x16_bf16 v[16:31], v[52:55], v[132:135], v[16:31]
	v_add_u32_e32 v52, 0, v168
	ds_read_b128 v[48:51], v52 offset:49152
	ds_read_b128 v[52:55], v52 offset:57344
	s_waitcnt lgkmcnt(0)
	v_mfma_f32_32x32x16_bf16 v[32:47], v[48:51], v[136:139], v[32:47]
	v_mfma_f32_32x32x16_bf16 v[16:31], v[52:55], v[136:139], v[16:31]
	v_add_u32_e32 v52, 0, v169
	ds_read_b128 v[48:51], v52 offset:49152
	ds_read_b128 v[52:55], v52 offset:57344
	s_waitcnt lgkmcnt(0)
	v_mfma_f32_32x32x16_bf16 v[32:47], v[48:51], v[140:143], v[32:47]
	v_mfma_f32_32x32x16_bf16 v[16:31], v[52:55], v[140:143], v[16:31]
	s_nop 10
	v_exp_f32_e32 v32, v32
	v_exp_f32_e32 v33, v33
	v_exp_f32_e32 v34, v34
	v_exp_f32_e32 v35, v35
	v_exp_f32_e32 v36, v36
	v_add_f32_e32 v48, 0, v32
	v_exp_f32_e32 v37, v37
	v_add_f32_e32 v48, v33, v48
	v_exp_f32_e32 v38, v38
	v_add_f32_e32 v48, v34, v48
	v_exp_f32_e32 v39, v39
	v_add_f32_e32 v48, v35, v48
	v_exp_f32_e32 v40, v40
	v_add_f32_e32 v48, v36, v48
	v_exp_f32_e32 v41, v41
	v_add_f32_e32 v48, v37, v48
	v_exp_f32_e32 v42, v42
	v_add_f32_e32 v48, v38, v48
	v_exp_f32_e32 v43, v43
	v_add_f32_e32 v48, v39, v48
	v_exp_f32_e32 v44, v44
	v_add_f32_e32 v48, v40, v48
	v_exp_f32_e32 v45, v45
	v_add_f32_e32 v48, v41, v48
	v_exp_f32_e32 v46, v46
	v_add_f32_e32 v48, v42, v48
	v_exp_f32_e32 v47, v47
	v_add_f32_e32 v48, v43, v48
	v_exp_f32_e32 v16, v16
	v_add_f32_e32 v48, v44, v48
	v_exp_f32_e32 v17, v17
	v_add_f32_e32 v48, v45, v48
	v_exp_f32_e32 v18, v18
	v_add_f32_e32 v48, v46, v48
	v_exp_f32_e32 v19, v19
	v_add_f32_e32 v48, v47, v48
	v_exp_f32_e32 v20, v20
	v_add_f32_e32 v48, v16, v48
	v_exp_f32_e32 v21, v21
	v_add_f32_e32 v48, v17, v48
	v_exp_f32_e32 v22, v22
	v_add_f32_e32 v48, v18, v48
	v_exp_f32_e32 v23, v23
	v_add_f32_e32 v48, v19, v48
	v_exp_f32_e32 v24, v24
	v_add_f32_e32 v48, v20, v48
	v_exp_f32_e32 v25, v25
	v_add_f32_e32 v48, v21, v48
	v_exp_f32_e32 v26, v26
	v_add_f32_e32 v48, v22, v48
	v_exp_f32_e32 v27, v27
	v_add_f32_e32 v48, v23, v48
	v_exp_f32_e32 v28, v28
	v_add_f32_e32 v48, v24, v48
	v_exp_f32_e32 v29, v29
	v_add_f32_e32 v48, v25, v48
	v_exp_f32_e32 v30, v30
	v_add_f32_e32 v48, v26, v48
	v_exp_f32_e32 v31, v31
	v_add_f32_e32 v48, v27, v48
	v_add_f32_e32 v48, v28, v48
	v_add_f32_e32 v48, v29, v48
	v_add_f32_e32 v48, v30, v48
	v_add_f32_e32 v48, v31, v48
	v_add_f32_e32 v171, 0, v48
	v_cvt_pk_bf16_f32 v64, v32, v33
	v_cvt_pk_bf16_f32 v65, v34, v35
	v_cvt_pk_bf16_f32 v66, v36, v37
	v_cvt_pk_bf16_f32 v67, v38, v39
	v_cvt_pk_bf16_f32 v86, v40, v41
	v_cvt_pk_bf16_f32 v87, v42, v43
	v_cvt_pk_bf16_f32 v88, v44, v45
	v_cvt_pk_bf16_f32 v89, v46, v47
	v_cvt_pk_bf16_f32 v90, v16, v17
	v_cvt_pk_bf16_f32 v91, v18, v19
	v_cvt_pk_bf16_f32 v92, v20, v21
	v_cvt_pk_bf16_f32 v93, v22, v23
	v_cvt_pk_bf16_f32 v94, v24, v25
	v_cvt_pk_bf16_f32 v95, v26, v27
	v_cvt_pk_bf16_f32 v96, v28, v29
	v_cvt_pk_bf16_f32 v97, v30, v31
	ds_read_b64_tr_b16 v[16:17], v170 offset:0
	ds_read_b64_tr_b16 v[18:19], v170 offset:0x800
	ds_read_b64_tr_b16 v[32:33], v170 offset:0x1000
	ds_read_b64_tr_b16 v[34:35], v170 offset:0x1800
	ds_read_b64_tr_b16 v[36:37], v170 offset:0x2000
	ds_read_b64_tr_b16 v[38:39], v170 offset:0x2800
	ds_read_b64_tr_b16 v[40:41], v170 offset:0x3000
	ds_read_b64_tr_b16 v[42:43], v170 offset:0x3800
	s_waitcnt lgkmcnt(0)
	s_nop 0
	v_mfma_f32_32x32x16_bf16 v[16:31], v[64:67], v[16:19], 0
	v_mfma_f32_32x32x16_bf16 v[16:31], v[86:89], v[32:35], v[16:31]
	ds_read_b64_tr_b16 v[32:33], v170 offset:0x200
	ds_read_b64_tr_b16 v[34:35], v170 offset:0xa00
	ds_read_b64_tr_b16 v[48:49], v170 offset:0x1200
	ds_read_b64_tr_b16 v[50:51], v170 offset:0x1a00
	ds_read_b64_tr_b16 v[52:53], v170 offset:0x2200
	ds_read_b64_tr_b16 v[54:55], v170 offset:0x2a00
	ds_read_b64_tr_b16 v[56:57], v170 offset:0x3200
	v_mfma_f32_32x32x16_bf16 v[16:31], v[90:93], v[36:39], v[16:31]
	ds_read_b64_tr_b16 v[58:59], v170 offset:0x3a00
	s_waitcnt lgkmcnt(0)
	v_mfma_f32_32x32x16_bf16 v[16:31], v[94:97], v[40:43], v[16:31]
	v_mfma_f32_32x32x16_bf16 v[32:47], v[64:67], v[32:35], 0
	v_mfma_f32_32x32x16_bf16 v[32:47], v[86:89], v[48:51], v[32:47]
	ds_read_b64_tr_b16 v[48:49], v170 offset:0x400
	ds_read_b64_tr_b16 v[50:51], v170 offset:0xc00
	ds_read_b64_tr_b16 v[68:69], v170 offset:0x1400
	ds_read_b64_tr_b16 v[70:71], v170 offset:0x1c00
	ds_read_b64_tr_b16 v[72:73], v170 offset:0x2400
	ds_read_b64_tr_b16 v[74:75], v170 offset:0x2c00
	ds_read_b64_tr_b16 v[76:77], v170 offset:0x3400
	v_mfma_f32_32x32x16_bf16 v[32:47], v[90:93], v[52:55], v[32:47]
	ds_read_b64_tr_b16 v[78:79], v170 offset:0x3c00
	s_waitcnt lgkmcnt(0)
	v_mfma_f32_32x32x16_bf16 v[32:47], v[94:97], v[56:59], v[32:47]
	v_mfma_f32_32x32x16_bf16 v[48:63], v[64:67], v[48:51], 0
	v_mfma_f32_32x32x16_bf16 v[48:63], v[86:89], v[68:71], v[48:63]
	ds_read_b64_tr_b16 v[68:69], v170 offset:0x600
	ds_read_b64_tr_b16 v[70:71], v170 offset:0xe00
	ds_read_b64_tr_b16 v[98:99], v170 offset:0x1600
	ds_read_b64_tr_b16 v[100:101], v170 offset:0x1e00
	ds_read_b64_tr_b16 v[102:103], v170 offset:0x2600
	ds_read_b64_tr_b16 v[104:105], v170 offset:0x2e00
	ds_read_b64_tr_b16 v[106:107], v170 offset:0x3600
	v_mfma_f32_32x32x16_bf16 v[48:63], v[90:93], v[72:75], v[48:63]
	ds_read_b64_tr_b16 v[108:109], v170 offset:0x3e00
	s_waitcnt lgkmcnt(0)
	v_mfma_f32_32x32x16_bf16 v[48:63], v[94:97], v[76:79], v[48:63]
	v_mfma_f32_32x32x16_bf16 v[64:79], v[64:67], v[68:71], 0
	s_ashr_i32 s47, s46, 31
	v_lshl_add_u64 v[110:111], v[146:147], 0, s[46:47]
	v_lshlrev_b64 v[110:111], 9, v[110:111]
	v_lshl_add_u64 v[110:111], s[56:57], 0, v[110:111]
	s_mov_b32 m0, s3
	v_lshl_add_u64 v[110:111], v[110:111], 0, v[80:81]
	s_waitcnt vmcnt(0)
	s_waitcnt vmcnt(0)
	s_barrier
; template <int D0> __device__ __forceinline__ void pv_one(f32x16& od, unsigned vb, bf16x8 pa0, bf16x8 pa1, bf16x8 pa2, bf16x8 pa3) {
;     const s16x4 l0 = tr_read<v_rd_off(D0, 0, 0)>(vb), h0 = tr_read<v_rd_off(D0, 0, 1)>(vb), l1 = tr_read<v_rd_off(D0, 1, 0)>(vb), h1 = tr_read<v_rd_off(D0, 1, 1)>(vb);
;     const s16x4 l2 = tr_read<v_rd_off(D0, 2, 0)>(vb), h2 = tr_read<v_rd_off(D0, 2, 1)>(vb), l3 = tr_read<v_rd_off(D0, 3, 0)>(vb), h3 = tr_read<v_rd_off(D0, 3, 1)>(vb);
;     asm volatile("s_waitcnt lgkmcnt(0)" ::: "memory"); SBAR();
;     ...
;     od = __builtin_amdgcn_mfma_f32_32x32x16_bf16(pa0, PK(l0, h0), od, 0, 0, 0);
;     od = __builtin_amdgcn_mfma_f32_32x32x16_bf16(pa1, PK(l1, h1), od, 0, 0, 0);
;     od = __builtin_amdgcn_mfma_f32_32x32x16_bf16(pa2, PK(l2, h2), od, 0, 0, 0);
;     od = __builtin_amdgcn_mfma_f32_32x32x16_bf16(pa3, PK(l3, h3), od, 0, 0, 0);
;     ...
; }
; __device__ __forceinline__ void pv_d0(f32x16 (&o)[4], unsigned vb, bf16x8 pa0, bf16x8 pa1, bf16x8 pa2, bf16x8 pa3) {
; __device__ __forceinline__ void partialSM(f32x16& p0, f32x16& p1) {
; #pragma unroll
;     for (int r = 0; r < 16; ++r) p0[r] = __builtin_amdgcn_exp2f(p0[r]);
; }
; __device__ __forceinline__ void finishSM(f32x16& p0, f32x16& p1, float& l_reg, bf16x8& pa0, bf16x8& pa1, bf16x8& pa2, bf16x8& pa3) {
; #pragma unroll
;     for (int r = 0; r < 16; ++r) p1[r] = __builtin_amdgcn_exp2f(p1[r]);
;     float ps = 0;
; #pragma unroll
;     for (int r = 0; r < 16; ++r) ps += p0[r];
; #pragma unroll
;     for (int r = 0; r < 16; ++r) ps += p1[r];
;     l_reg += ps;
;     ...
;     PK8(p0, 0, pa0); PK8(p0, 8, pa1); PK8(p1, 0, pa2); PK8(p1, 8, pa3);
;     ...
; }
; template <int DQK>
; __device__ __forceinline__ void qkt(f32x16& p0, f32x16& p1, const LAS char* Ks, const bf16x8 (&qr)[DQK / 16], const int (&ka)[8], float nMB) {
;     constexpr int RB = DQK * 2, NA = (RB == 256) ? 8 : 4;
; #pragma unroll
;     for (int r = 0; r < 16; ++r) { p0[r] = nMB; p1[r] = nMB; }
; #pragma unroll
;     for (int d0 = 0; d0 < DQK / 16; ++d0) {
;         const LAS char* a = Ks + ka[d0 % NA] + (d0 / NA) * (NA * 32);
;         const bf16x8 b0 = *(const LAS bf16x8*)(a);
;         const bf16x8 b1 = *(const LAS bf16x8*)(a + 32 * RB);
;         p0 = __builtin_amdgcn_mfma_f32_32x32x16_bf16(b0, qr[d0], p0, 0, 0, 0);
;         p1 = __builtin_amdgcn_mfma_f32_32x32x16_bf16(b1, qr[d0], p1, 0, 0, 0); }
; }
	global_load_lds_dwordx4 v[110:111], off
	v_lshl_add_u64 v[110:111], v[148:149], 0, s[46:47]
	v_mfma_f32_32x32x16_bf16 v[64:79], v[86:89], v[98:101], v[64:79]
	v_lshlrev_b64 v[86:87], 9, v[110:111]
	v_lshl_add_u64 v[86:87], s[56:57], 0, v[86:87]
	v_lshl_add_u64 v[86:87], v[86:87], 0, v[80:81]
	s_mov_b32 m0, s21
	v_lshl_add_u64 v[154:155], s[56:57], 0, v[80:81]
	global_load_lds_dwordx4 v[86:87], off
	v_lshl_add_u64 v[86:87], v[150:151], 0, s[46:47]
	v_lshlrev_b64 v[86:87], 9, v[86:87]
	v_lshl_add_u64 v[86:87], s[50:51], 0, v[86:87]
	v_lshl_add_u64 v[86:87], v[86:87], 0, v[82:83]
	s_mov_b32 m0, s20
	v_mfma_f32_32x32x16_bf16 v[64:79], v[90:93], v[102:105], v[64:79]
	global_load_lds_dwordx4 v[86:87], off
	v_lshl_add_u64 v[86:87], v[152:153], 0, s[46:47]
	v_lshlrev_b64 v[86:87], 9, v[86:87]
	v_lshl_add_u64 v[86:87], s[50:51], 0, v[86:87]
	v_lshl_add_u64 v[86:87], v[86:87], 0, v[84:85]
	s_mov_b32 m0, s31
	v_mfma_f32_32x32x16_bf16 v[64:79], v[94:97], v[106:109], v[64:79]
	global_load_lds_dwordx4 v[86:87], off
	v_lshl_add_u64 v[156:157], s[50:51], 0, v[82:83]
	v_lshl_add_u64 v[158:159], s[50:51], 0, v[84:85]
	s_add_i32 s20, s71, -1
	s_mov_b32 s21, 0
	s_mov_b32 s33, 0
	s_waitcnt lgkmcnt(0)
.LBB0_173:
	s_mov_b32 s31, s4
	s_mov_b32 s4, s33
	s_mul_i32 s33, s5, 0x6000
	s_add_i32 s33, s33, 0
	s_lshl_b32 s35, s5, 14
	v_add_u32_e32 v172, s33, v145
	v_add_u32_e32 v173, s33, v161
	v_add_u32_e32 v174, s33, v164
	v_add_u32_e32 v175, s33, v165
	v_add_u32_e32 v192, s33, v166
	v_add_u32_e32 v193, s33, v167
	v_add_u32_e32 v194, s33, v168
	v_add_u32_e32 v195, s33, v169
	v_add_u32_e32 v184, s35, v170
	ds_read_b128 v[204:207], v172 offset:49152
	ds_read_b128 v[208:211], v173 offset:49152
	ds_read_b128 v[212:215], v174 offset:49152
	s_waitcnt lgkmcnt(2)
	v_mfma_f32_32x32x16_bf16 v[96:111], v[204:207], v[112:115], v[0:15]
	ds_read_b128 v[216:219], v175 offset:49152
	s_waitcnt lgkmcnt(2)
	v_mfma_f32_32x32x16_bf16 v[96:111], v[208:211], v[116:119], v[96:111]
	ds_read_b128 v[204:207], v192 offset:49152
	s_waitcnt lgkmcnt(2)
	v_mfma_f32_32x32x16_bf16 v[96:111], v[212:215], v[120:123], v[96:111]
	ds_read_b128 v[208:211], v193 offset:49152
	s_waitcnt lgkmcnt(2)
	v_mfma_f32_32x32x16_bf16 v[96:111], v[216:219], v[124:127], v[96:111]
	ds_read_b128 v[212:215], v194 offset:49152
	s_waitcnt lgkmcnt(2)
	v_mfma_f32_32x32x16_bf16 v[96:111], v[204:207], v[128:131], v[96:111]
	ds_read_b128 v[216:219], v195 offset:49152
	s_waitcnt lgkmcnt(2)
	v_mfma_f32_32x32x16_bf16 v[96:111], v[208:211], v[132:135], v[96:111]
	ds_read_b128 v[204:207], v172 offset:57344
	s_waitcnt lgkmcnt(2)
	v_mfma_f32_32x32x16_bf16 v[96:111], v[212:215], v[136:139], v[96:111]
	ds_read_b128 v[208:211], v173 offset:57344
	s_waitcnt lgkmcnt(2)
	v_mfma_f32_32x32x16_bf16 v[96:111], v[216:219], v[140:143], v[96:111]
	ds_read_b128 v[212:215], v174 offset:57344
	s_waitcnt lgkmcnt(2)
	v_mfma_f32_32x32x16_bf16 v[80:95], v[204:207], v[112:115], v[0:15]
	ds_read_b128 v[216:219], v175 offset:57344
	s_waitcnt lgkmcnt(2)
	v_mfma_f32_32x32x16_bf16 v[80:95], v[208:211], v[116:119], v[80:95]
	ds_read_b128 v[204:207], v192 offset:57344
	s_nop 4
	v_exp_f32_e32 v96, v96
	v_exp_f32_e32 v97, v97
	v_exp_f32_e32 v104, v104
	v_exp_f32_e32 v105, v105
	s_waitcnt lgkmcnt(2)
	v_mfma_f32_32x32x16_bf16 v[80:95], v[212:215], v[120:123], v[80:95]
	ds_read_b128 v[208:211], v193 offset:57344
	v_exp_f32_e32 v98, v98
	v_exp_f32_e32 v99, v99
	v_exp_f32_e32 v106, v106
	s_waitcnt lgkmcnt(2)
	v_mfma_f32_32x32x16_bf16 v[80:95], v[216:219], v[124:127], v[80:95]
	ds_read_b128 v[212:215], v194 offset:57344
	v_exp_f32_e32 v100, v100
	v_exp_f32_e32 v101, v101
	v_exp_f32_e32 v107, v107
	s_waitcnt lgkmcnt(2)
	v_mfma_f32_32x32x16_bf16 v[80:95], v[204:207], v[128:131], v[80:95]
	ds_read_b128 v[216:219], v195 offset:57344
	v_exp_f32_e32 v102, v102
	v_exp_f32_e32 v103, v103
	v_exp_f32_e32 v108, v108
	s_waitcnt lgkmcnt(2)
	v_mfma_f32_32x32x16_bf16 v[80:95], v[208:211], v[132:135], v[80:95]
	ds_read_b64_tr_b16 v[204:205], v184 offset:0
	ds_read_b64_tr_b16 v[206:207], v184 offset:2048
	v_cvt_pk_bf16_f32 v172, v96, v97
	v_cvt_pk_bf16_f32 v173, v98, v99
	v_exp_f32_e32 v109, v109
	s_waitcnt lgkmcnt(3)
	v_mfma_f32_32x32x16_bf16 v[80:95], v[212:215], v[136:139], v[80:95]
	ds_read_b64_tr_b16 v[208:209], v184 offset:512
	ds_read_b64_tr_b16 v[210:211], v184 offset:2560
	v_cvt_pk_bf16_f32 v174, v100, v101
	v_exp_f32_e32 v110, v110
	s_waitcnt lgkmcnt(4)
	v_mfma_f32_32x32x16_bf16 v[80:95], v[216:219], v[140:143], v[80:95]
	ds_read_b64_tr_b16 v[212:213], v184 offset:1024
	ds_read_b64_tr_b16 v[214:215], v184 offset:3072
	v_cvt_pk_bf16_f32 v175, v102, v103
	v_exp_f32_e32 v111, v111
	v_add_f32_e32 v96, 0, v96
	v_add_f32_e32 v96, v97, v96
	s_waitcnt lgkmcnt(4)
	v_mfma_f32_32x32x16_bf16 v[16:31], v[172:175], v[204:207], v[16:31]
	ds_read_b64_tr_b16 v[216:217], v184 offset:1536
	ds_read_b64_tr_b16 v[218:219], v184 offset:3584
	v_cvt_pk_bf16_f32 v192, v104, v105
	v_add_f32_e32 v96, v98, v96
	v_add_f32_e32 v96, v99, v96
	v_add_f32_e32 v96, v100, v96
	s_waitcnt lgkmcnt(4)
	v_mfma_f32_32x32x16_bf16 v[32:47], v[172:175], v[208:211], v[32:47]
	ds_read_b64_tr_b16 v[204:205], v184 offset:4096
	ds_read_b64_tr_b16 v[206:207], v184 offset:6144
	v_cvt_pk_bf16_f32 v193, v106, v107
	v_exp_f32_e32 v80, v80
	v_exp_f32_e32 v81, v81
	v_exp_f32_e32 v88, v88
	v_exp_f32_e32 v89, v89
	v_add_f32_e32 v96, v101, v96
	v_add_f32_e32 v96, v102, v96
	s_waitcnt lgkmcnt(4)
; #define SBAR() __builtin_amdgcn_sched_barrier(0)
; #define VMW0() asm volatile("s_waitcnt vmcnt(0)" ::: "memory")
; template <int D0> __device__ __forceinline__ void pv_one(f32x16& od, unsigned vb, bf16x8 pa0, bf16x8 pa1, bf16x8 pa2, bf16x8 pa3) {
;     const s16x4 l0 = tr_read<v_rd_off(D0, 0, 0)>(vb), h0 = tr_read<v_rd_off(D0, 0, 1)>(vb), l1 = tr_read<v_rd_off(D0, 1, 0)>(vb), h1 = tr_read<v_rd_off(D0, 1, 1)>(vb);
;     const s16x4 l2 = tr_read<v_rd_off(D0, 2, 0)>(vb), h2 = tr_read<v_rd_off(D0, 2, 1)>(vb), l3 = tr_read<v_rd_off(D0, 3, 0)>(vb), h3 = tr_read<v_rd_off(D0, 3, 1)>(vb);
;     asm volatile("s_waitcnt lgkmcnt(0)" ::: "memory"); SBAR();
;     ...
;     od = __builtin_amdgcn_mfma_f32_32x32x16_bf16(pa0, PK(l0, h0), od, 0, 0, 0);
;     od = __builtin_amdgcn_mfma_f32_32x32x16_bf16(pa1, PK(l1, h1), od, 0, 0, 0);
;     od = __builtin_amdgcn_mfma_f32_32x32x16_bf16(pa2, PK(l2, h2), od, 0, 0, 0);
;     od = __builtin_amdgcn_mfma_f32_32x32x16_bf16(pa3, PK(l3, h3), od, 0, 0, 0);
;     ...
; }
; __device__ __forceinline__ void pv_d0(f32x16 (&o)[4], unsigned vb, bf16x8 pa0, bf16x8 pa1, bf16x8 pa2, bf16x8 pa3) {
;     pv_one<0>(o[0], vb, pa0, pa1, pa2, pa3); pv_one<1>(o[1], vb, pa0, pa1, pa2, pa3); pv_one<2>(o[2], vb, pa0, pa1, pa2, pa3); pv_one<3>(o[3], vb, pa0, pa1, pa2, pa3);
; }
; __device__ __forceinline__ void partialSM(f32x16& p0, f32x16& p1) {
; #pragma unroll
;     for (int r = 0; r < 16; ++r) p0[r] = __builtin_amdgcn_exp2f(p0[r]);
; }
; __device__ __forceinline__ void finishSM(f32x16& p0, f32x16& p1, float& l_reg, bf16x8& pa0, bf16x8& pa1, bf16x8& pa2, bf16x8& pa3) {
; #pragma unroll
;     for (int r = 0; r < 16; ++r) p1[r] = __builtin_amdgcn_exp2f(p1[r]);
;     float ps = 0;
; #pragma unroll
;     for (int r = 0; r < 16; ++r) ps += p0[r];
; #pragma unroll
;     for (int r = 0; r < 16; ++r) ps += p1[r];
;     l_reg += ps;
;     ...
;     PK8(p0, 0, pa0); PK8(p0, 8, pa1); PK8(p1, 0, pa2); PK8(p1, 8, pa3);
;     ...
; }
; template <int DQK, bool DOUBLE> ...
;     ...
;         for (int j = 0; j < NT; ++j) {
;             SBAR(); qkt<DQK>(p0, p1, K_lds + bc * K_STRIDE, qr, ka, nMB);
;             partialSM(p0, p1); finishSM(p0, p1, l_reg, pa0, pa1, pa2, pa3); SBAR();
;             pv_d0(o, vb0 + bc * V_BYTES, pa0, pa1, pa2, pa3);
;             if (j + 1 < NT) { VMW0(); __syncthreads(); if (j + 3 < NT) DMA(j + 3, bc); }
;             { const int _t = bc; bc = bn; bn = bf; bf = _t; }
;         }
	v_mfma_f32_32x32x16_bf16 v[48:63], v[172:175], v[212:215], v[48:63]
	ds_read_b64_tr_b16 v[208:209], v184 offset:4608
	ds_read_b64_tr_b16 v[210:211], v184 offset:6656
	v_cvt_pk_bf16_f32 v194, v108, v109
	v_exp_f32_e32 v82, v82
	v_exp_f32_e32 v83, v83
	v_exp_f32_e32 v90, v90
	v_add_f32_e32 v96, v103, v96
	s_waitcnt lgkmcnt(4)
	v_mfma_f32_32x32x16_bf16 v[64:79], v[172:175], v[216:219], v[64:79]
	ds_read_b64_tr_b16 v[212:213], v184 offset:5120
	ds_read_b64_tr_b16 v[214:215], v184 offset:7168
	v_cvt_pk_bf16_f32 v195, v110, v111
	v_exp_f32_e32 v84, v84
	v_exp_f32_e32 v85, v85
	v_exp_f32_e32 v91, v91
	v_add_f32_e32 v96, v104, v96
	v_add_f32_e32 v96, v105, v96
	s_waitcnt lgkmcnt(4)
	v_mfma_f32_32x32x16_bf16 v[16:31], v[192:195], v[204:207], v[16:31]
	ds_read_b64_tr_b16 v[216:217], v184 offset:5632
	ds_read_b64_tr_b16 v[218:219], v184 offset:7680
	v_exp_f32_e32 v86, v86
	v_exp_f32_e32 v87, v87
	v_exp_f32_e32 v92, v92
	v_add_f32_e32 v96, v106, v96
	v_add_f32_e32 v96, v107, v96
	s_waitcnt lgkmcnt(4)
	v_mfma_f32_32x32x16_bf16 v[32:47], v[192:195], v[208:211], v[32:47]
	ds_read_b64_tr_b16 v[204:205], v184 offset:8192
	ds_read_b64_tr_b16 v[206:207], v184 offset:10240
	v_cvt_pk_bf16_f32 v196, v80, v81
	v_cvt_pk_bf16_f32 v197, v82, v83
	v_exp_f32_e32 v93, v93
	v_add_f32_e32 v96, v108, v96
	v_add_f32_e32 v96, v109, v96
	s_waitcnt lgkmcnt(4)
	v_mfma_f32_32x32x16_bf16 v[48:63], v[192:195], v[212:215], v[48:63]
	ds_read_b64_tr_b16 v[208:209], v184 offset:8704
	ds_read_b64_tr_b16 v[210:211], v184 offset:10752
	v_cvt_pk_bf16_f32 v198, v84, v85
	v_exp_f32_e32 v94, v94
	v_add_f32_e32 v96, v110, v96
	v_add_f32_e32 v96, v111, v96
	s_waitcnt lgkmcnt(4)
	v_mfma_f32_32x32x16_bf16 v[64:79], v[192:195], v[216:219], v[64:79]
	ds_read_b64_tr_b16 v[212:213], v184 offset:9216
	ds_read_b64_tr_b16 v[214:215], v184 offset:11264
	v_cvt_pk_bf16_f32 v199, v86, v87
	v_exp_f32_e32 v95, v95
	v_add_f32_e32 v80, v80, v96
	v_add_f32_e32 v80, v81, v80
	s_waitcnt lgkmcnt(4)
	v_mfma_f32_32x32x16_bf16 v[16:31], v[196:199], v[204:207], v[16:31]
	ds_read_b64_tr_b16 v[216:217], v184 offset:9728
	ds_read_b64_tr_b16 v[218:219], v184 offset:11776
	v_cvt_pk_bf16_f32 v200, v88, v89
	v_add_f32_e32 v80, v82, v80
	v_add_f32_e32 v80, v83, v80
	v_add_f32_e32 v80, v84, v80
	s_waitcnt lgkmcnt(4)
	v_mfma_f32_32x32x16_bf16 v[32:47], v[196:199], v[208:211], v[32:47]
	ds_read_b64_tr_b16 v[204:205], v184 offset:12288
	ds_read_b64_tr_b16 v[206:207], v184 offset:14336
	v_cvt_pk_bf16_f32 v201, v90, v91
	v_add_f32_e32 v80, v85, v80
	v_add_f32_e32 v80, v86, v80
	v_add_f32_e32 v80, v87, v80
	s_waitcnt lgkmcnt(4)
	v_mfma_f32_32x32x16_bf16 v[48:63], v[196:199], v[212:215], v[48:63]
	ds_read_b64_tr_b16 v[208:209], v184 offset:12800
	ds_read_b64_tr_b16 v[210:211], v184 offset:14848
	v_cvt_pk_bf16_f32 v202, v92, v93
	s_waitcnt lgkmcnt(4)
	v_mfma_f32_32x32x16_bf16 v[64:79], v[196:199], v[216:219], v[64:79]
	ds_read_b64_tr_b16 v[212:213], v184 offset:13312
	ds_read_b64_tr_b16 v[214:215], v184 offset:15360
	v_cvt_pk_bf16_f32 v203, v94, v95
	v_add_f32_e32 v80, v88, v80
	v_add_f32_e32 v80, v89, v80
	v_add_f32_e32 v80, v90, v80
	s_waitcnt lgkmcnt(4)
	v_mfma_f32_32x32x16_bf16 v[16:31], v[200:203], v[204:207], v[16:31]
	ds_read_b64_tr_b16 v[216:217], v184 offset:13824
	ds_read_b64_tr_b16 v[218:219], v184 offset:15872
	v_add_f32_e32 v80, v91, v80
	v_add_f32_e32 v80, v92, v80
	v_add_f32_e32 v80, v93, v80
	v_add_f32_e32 v80, v94, v80
	s_waitcnt lgkmcnt(4)
	v_mfma_f32_32x32x16_bf16 v[32:47], v[200:203], v[208:211], v[32:47]
	v_add_f32_e32 v80, v95, v80
	s_waitcnt lgkmcnt(2)
	v_mfma_f32_32x32x16_bf16 v[48:63], v[200:203], v[212:215], v[48:63]
	s_waitcnt lgkmcnt(0)
	v_mfma_f32_32x32x16_bf16 v[64:79], v[200:203], v[216:219], v[64:79]
	s_add_i32 s41, s21, 2
	s_cmp_ge_i32 s41, s71
	s_cbranch_scc1 .LBB0_176
	s_waitcnt vmcnt(0)
	s_add_i32 s41, s21, 4
	s_cmp_ge_i32 s41, s71
	s_waitcnt vmcnt(0)
	s_barrier
	s_cbranch_scc1 .LBB0_176
	s_ashr_i32 s45, s44, 31
	v_lshl_add_u64 v[172:173], s[44:45], 0, v[146:147]
	s_add_i32 s35, s3, s35
	v_lshlrev_b64 v[172:173], 9, v[172:173]
	v_lshl_add_u64 v[172:173], v[154:155], 0, v[172:173]
	s_mov_b32 m0, s35
	s_add_i32 s33, s33, s2
	global_load_lds_dwordx4 v[172:173], off
	v_lshl_add_u64 v[172:173], s[44:45], 0, v[148:149]
	v_lshlrev_b64 v[172:173], 9, v[172:173]
	v_lshl_add_u64 v[172:173], v[154:155], 0, v[172:173]
	s_add_i32 m0, s35, 0x2000
	s_nop 0
	global_load_lds_dwordx4 v[172:173], off
	v_lshl_add_u64 v[172:173], s[44:45], 0, v[150:151]
	v_lshlrev_b64 v[172:173], 9, v[172:173]
	s_add_i32 m0, s33, 0xc000
	v_lshl_add_u64 v[172:173], v[156:157], 0, v[172:173]
	global_load_lds_dwordx4 v[172:173], off
	v_lshl_add_u64 v[172:173], s[44:45], 0, v[152:153]
	v_lshlrev_b64 v[172:173], 9, v[172:173]
	v_lshl_add_u64 v[172:173], v[158:159], 0, v[172:173]
	s_add_i32 m0, s33, 0xe000
	s_nop 0
	global_load_lds_dwordx4 v[172:173], off
.LBB0_176:
	s_add_i32 s44, s44, 64
	s_add_i32 s21, s21, 1
	s_cmp_lg_u32 s20, s21
	v_add_f32_e32 v171, v171, v80
	s_cbranch_scc0 .LBB0_178
	s_mov_b32 s33, s5
	s_mov_b32 s5, s31
	s_branch .LBB0_173
.LBB0_178:
	s_nop 11
	v_mov_b32_e32 v0, v171
	s_nop 1
	v_permlane32_swap_b32_e32 v171, v0
	v_cmp_gt_u32_e32 vcc, 32, v182
	s_and_saveexec_b64 s[44:45], vcc
	s_cbranch_execz .LBB0_107
	v_lshl_add_u32 v1, v181, 2, s90
	v_add_f32_e32 v0, v171, v0
	ds_write_b32 v1, v0
	s_branch .LBB0_107
